# Hyena FFT: warm-up touch of the next channel's filter taps at the start of order 1
# speedup vs baseline: 1.0008x; 1.0008x over previous
; #define WG_SYNC() do { asm volatile("s_waitcnt lgkmcnt(0)" ::: "memory"); __builtin_amdgcn_s_barrier(); asm volatile("" ::: "memory"); } while (0)
; template <bool INV> __device__ __forceinline__ void dft16(f32x2 (&x)[16]) {
;     constexpr float C1 = 0.92387953251128674f, S1 = 0.38268343236508977f, C2 = 0.70710678118654752f;
; #pragma unroll
;     for (int b = 0; b < 4; ++b) dft4<INV>(x[b], x[4 + b], x[8 + b], x[12 + b]);
; __device__ __forceinline__ void hyena_fft(LAS unsigned char* lds, int layer, int G, const int wave_s) {
;     ...
;         for (int c = c_lo; c < c_hi; ++c) { const int unit = c >> 2, jc = c & 3;
;             WG_SYNC();
;             { f32x2 x[16]; const unsigned* tf = TF + (size_t)c * SEQ; const unsigned* tb = TB + (size_t)c * SEQ;
; #pragma unroll
;               for (int r = 0; r < 8; ++r) { const unsigned w = tf[n2 + 512 * r]; x[r] = (f32x2){bf_lo(w), bf_hi(w)}; }
; #pragma unroll
;               for (int r = 8; r < 16; ++r) { const int l = FN - 512 * r - n2; const unsigned w = l < SEQ ? tb[l] : 0u; x[r] = (f32x2){bf_lo(w), bf_hi(w)}; }
;               __builtin_amdgcn_sched_barrier(0); fft_fwd1<false>(x, Fb, n2, w1p); __builtin_amdgcn_sched_barrier(0); }
;             hy_stage(pl0, PHY, 2 * (HY / 4) + unit, jc, tid); __builtin_amdgcn_sched_barrier(0); hy_stage(pl1, PHY, unit, jc, tid); __builtin_amdgcn_sched_barrier(0);
.Lhfft_loop:
	s_lshr_b32 s43, s80, 2
	s_mul_i32 s73, s43, 0x11000
	s_and_b32 s43, s80, 2
	s_lshl_b32 s43, s43, 1
	s_add_u32 s73, s73, s43
	s_and_b32 s43, s80, 1
	s_mov_b32 s15, 0x1000c0c
	s_cmp_eq_u32 s43, 0
	s_cselect_b32 s15, s15, 0x3020c0c
	s_lshl_b32 s43, s80, 14
	s_add_u32 s46, s36, s43
	s_addc_u32 s47, s37, 0
	s_add_u32 s50, s46, 0x4000000
	s_addc_u32 s51, s47, 0
	s_waitcnt lgkmcnt(0)
	s_barrier
	s_add_u32 s60, s46, 0
	s_addc_u32 s61, s47, 0
	global_load_dword v176, v212, s[60:61]
	global_load_dword v178, v212, s[60:61] offset:2048
	s_add_u32 s60, s46, 0x1000
	s_addc_u32 s61, s47, 0
	global_load_dword v180, v212, s[60:61]
	global_load_dword v182, v212, s[60:61] offset:2048
	s_add_u32 s60, s46, 0x2000
	s_addc_u32 s61, s47, 0
	global_load_dword v184, v212, s[60:61]
	global_load_dword v186, v212, s[60:61] offset:2048
	s_add_u32 s60, s46, 0x3000
	s_addc_u32 s61, s47, 0
	global_load_dword v188, v212, s[60:61]
	global_load_dword v166, v212, s[60:61] offset:2048
	s_add_u32 s62, s50, 0x3000
	s_addc_u32 s63, s51, 0
	global_load_dword v177, v214, s[62:63] offset:2048
	global_load_dword v179, v214, s[62:63]
	s_add_u32 s62, s50, 0x2000
	s_addc_u32 s63, s51, 0
	global_load_dword v181, v214, s[62:63] offset:2048
	global_load_dword v183, v214, s[62:63]
	s_add_u32 s62, s50, 0x1000
	s_addc_u32 s63, s51, 0
	global_load_dword v185, v214, s[62:63] offset:2048
	global_load_dword v187, v214, s[62:63]
	s_add_u32 s62, s50, 0
	s_addc_u32 s63, s51, 0
	global_load_dword v189, v214, s[62:63] offset:2048
	global_load_dword v167, v214, s[62:63]
	s_add_u32 s56, s38, s73
	s_addc_u32 s57, s39, 0
	s_add_u32 s56, s56, 0x2200000
	s_addc_u32 s57, s57, 0
	global_load_dwordx3 v[58:60], v216, s[56:57]
	global_load_dwordx3 v[62:64], v218, s[56:57]
	global_load_dwordx3 v[66:68], v220, s[56:57]
	global_load_dwordx3 v[70:72], v222, s[56:57]
	global_load_dwordx3 v[74:76], v240, s[56:57]
	global_load_dwordx3 v[78:80], v242, s[56:57]
	global_load_dwordx3 v[82:84], v244, s[56:57]
	global_load_dwordx3 v[86:88], v61, s[56:57]
	s_waitcnt vmcnt(23)
	v_and_b32_e32 v101, 0xffff0000, v176
	v_lshlrev_b32_e32 v100, 16, v176
	s_waitcnt vmcnt(22)
	v_and_b32_e32 v103, 0xffff0000, v178
	v_lshlrev_b32_e32 v102, 16, v178
	s_waitcnt vmcnt(21)
	v_and_b32_e32 v105, 0xffff0000, v180
	v_lshlrev_b32_e32 v104, 16, v180
	s_waitcnt vmcnt(20)
	v_and_b32_e32 v107, 0xffff0000, v182
	v_lshlrev_b32_e32 v106, 16, v182
	s_waitcnt vmcnt(19)
	v_and_b32_e32 v109, 0xffff0000, v184
	v_lshlrev_b32_e32 v108, 16, v184
	s_waitcnt vmcnt(18)
	v_and_b32_e32 v111, 0xffff0000, v186
	v_lshlrev_b32_e32 v110, 16, v186
	s_waitcnt vmcnt(17)
	v_and_b32_e32 v113, 0xffff0000, v188
	v_lshlrev_b32_e32 v112, 16, v188
	s_waitcnt vmcnt(16)
	v_and_b32_e32 v115, 0xffff0000, v166
	v_lshlrev_b32_e32 v114, 16, v166
	s_waitcnt vmcnt(15)
	v_cndmask_b32_e64 v177, v177, 0, s[10:11]
	v_and_b32_e32 v117, 0xffff0000, v177
	v_lshlrev_b32_e32 v116, 16, v177
	s_waitcnt vmcnt(14)
	v_and_b32_e32 v119, 0xffff0000, v179
	v_lshlrev_b32_e32 v118, 16, v179
	s_waitcnt vmcnt(13)
	v_and_b32_e32 v121, 0xffff0000, v181
	v_lshlrev_b32_e32 v120, 16, v181
	s_waitcnt vmcnt(12)
	v_and_b32_e32 v123, 0xffff0000, v183
	v_lshlrev_b32_e32 v122, 16, v183
	s_waitcnt vmcnt(11)
	v_and_b32_e32 v125, 0xffff0000, v185
	v_lshlrev_b32_e32 v124, 16, v185
	s_waitcnt vmcnt(10)
	v_and_b32_e32 v127, 0xffff0000, v187
	v_lshlrev_b32_e32 v126, 16, v187
	s_waitcnt vmcnt(9)
	v_and_b32_e32 v129, 0xffff0000, v189
	v_lshlrev_b32_e32 v128, 16, v189
	s_waitcnt vmcnt(8)
	v_and_b32_e32 v131, 0xffff0000, v167
	v_lshlrev_b32_e32 v130, 16, v167
	v_pk_add_f32 v[168:169], v[100:101], v[116:117]
	v_pk_add_f32 v[174:175], v[100:101], v[116:117] neg_lo:[0,1] neg_hi:[0,1]
	v_pk_add_f32 v[176:177], v[108:109], v[124:125]
	v_pk_add_f32 v[178:179], v[108:109], v[124:125] neg_lo:[0,1] neg_hi:[0,1]
	v_pk_add_f32 v[100:101], v[168:169], v[176:177]
	v_pk_add_f32 v[116:117], v[168:169], v[176:177] neg_lo:[0,1] neg_hi:[0,1]
	v_pk_add_f32 v[108:109], v[174:175], v[178:179] op_sel:[0,1] op_sel_hi:[1,0] neg_hi:[0,1]
	v_pk_add_f32 v[124:125], v[174:175], v[178:179] op_sel:[0,1] op_sel_hi:[1,0] neg_lo:[0,1]
	v_pk_add_f32 v[180:181], v[102:103], v[118:119]
	v_pk_add_f32 v[182:183], v[102:103], v[118:119] neg_lo:[0,1] neg_hi:[0,1]
	v_pk_add_f32 v[184:185], v[110:111], v[126:127]
	v_pk_add_f32 v[186:187], v[110:111], v[126:127] neg_lo:[0,1] neg_hi:[0,1]
	v_pk_add_f32 v[102:103], v[180:181], v[184:185]
	v_pk_add_f32 v[118:119], v[180:181], v[184:185] neg_lo:[0,1] neg_hi:[0,1]
	v_pk_add_f32 v[110:111], v[182:183], v[186:187] op_sel:[0,1] op_sel_hi:[1,0] neg_hi:[0,1]
	v_pk_add_f32 v[126:127], v[182:183], v[186:187] op_sel:[0,1] op_sel_hi:[1,0] neg_lo:[0,1]
	v_pk_add_f32 v[188:189], v[104:105], v[120:121]
	v_pk_add_f32 v[166:167], v[104:105], v[120:121] neg_lo:[0,1] neg_hi:[0,1]
	v_pk_add_f32 v[168:169], v[112:113], v[128:129]
	v_pk_add_f32 v[174:175], v[112:113], v[128:129] neg_lo:[0,1] neg_hi:[0,1]
	v_pk_add_f32 v[104:105], v[188:189], v[168:169]
	v_pk_add_f32 v[120:121], v[188:189], v[168:169] neg_lo:[0,1] neg_hi:[0,1]
	v_pk_add_f32 v[112:113], v[166:167], v[174:175] op_sel:[0,1] op_sel_hi:[1,0] neg_hi:[0,1]
	v_pk_add_f32 v[128:129], v[166:167], v[174:175] op_sel:[0,1] op_sel_hi:[1,0] neg_lo:[0,1]
	v_pk_add_f32 v[176:177], v[106:107], v[122:123]
	v_pk_add_f32 v[178:179], v[106:107], v[122:123] neg_lo:[0,1] neg_hi:[0,1]
	v_pk_add_f32 v[180:181], v[114:115], v[130:131]
	v_pk_add_f32 v[182:183], v[114:115], v[130:131] neg_lo:[0,1] neg_hi:[0,1]
	v_pk_add_f32 v[106:107], v[176:177], v[180:181]
	v_pk_add_f32 v[122:123], v[176:177], v[180:181] neg_lo:[0,1] neg_hi:[0,1]
	v_pk_add_f32 v[114:115], v[178:179], v[182:183] op_sel:[0,1] op_sel_hi:[1,0] neg_hi:[0,1]
; #define LAS __attribute__((address_space(3)))
; __device__ __forceinline__ f32x2 cmul(f32x2 a, f32x2 b) { return (f32x2){a.x * b.x - a.y * b.y, a.x * b.y + a.y * b.x}; }
; template <bool INV> __device__ __forceinline__ f32x2 cmul_tw(f32x2 a, f32x2 w) { return INV ? cmulc(a, w) : cmul(a, w); }
; template <bool INV> __device__ __forceinline__ void dft16(f32x2 (&x)[16]) {
;     ...
;     const f32x2 w1 = {C1, -S1}, w2 = {C2, -C2}, w3 = {S1, -C1}, w4 = {0.f, -1.f}, w6 = {-C2, -C2}, w9 = {-C1, S1};
;     x[4 * 1 + 1] = cmul_tw<INV>(x[5], w1); x[4 * 1 + 2] = cmul_tw<INV>(x[6], w2); x[4 * 1 + 3] = cmul_tw<INV>(x[7], w3);
;     x[4 * 2 + 1] = cmul_tw<INV>(x[9], w2); x[4 * 2 + 2] = cmul_tw<INV>(x[10], w4); x[4 * 2 + 3] = cmul_tw<INV>(x[11], w6);
;     x[4 * 3 + 1] = cmul_tw<INV>(x[13], w3); x[4 * 3 + 2] = cmul_tw<INV>(x[14], w6); x[4 * 3 + 3] = cmul_tw<INV>(x[15], w9);
; #pragma unroll
;     for (int c = 0; c < 4; ++c) dft4<INV>(x[4 * c], x[4 * c + 1], x[4 * c + 2], x[4 * c + 3]);
;     f32x2 y[16];
; #pragma unroll
;     for (int k = 0; k < 16; ++k) y[k] = x[4 * (k & 3) + (k >> 2)];
; #pragma unroll
;     for (int k = 0; k < 16; ++k) x[k] = y[k];
; }
; template <bool LO> __device__ __forceinline__ void fft_fwd1(f32x2 (&x)[16], LAS f32x2* B, int n2, const f32x2 (&w)[16]) {
;     asm volatile("" : "+v"(n2));
;     if (LO) dft16_fwd_lo(x); else dft16<false>(x);
;     B[fpad(n2)] = x[0];
; #pragma unroll
;     for (int k = 1; k < 16; ++k) B[fpad(512 * k + n2)] = cmul(x[k], w[k]);
	v_pk_add_f32 v[130:131], v[178:179], v[182:183] op_sel:[0,1] op_sel_hi:[1,0] neg_lo:[0,1]
	v_pk_mul_f32 v[184:185], v[110:111], s[68:69] op_sel:[1,1] op_sel_hi:[0,1]
	v_pk_fma_f32 v[110:111], v[110:111], s[68:69], v[184:185] op_sel_hi:[1,0,1] neg_lo:[0,0,1]
	v_pk_mul_f32 v[186:187], v[112:113], s[84:85] op_sel:[1,1] op_sel_hi:[0,1]
	v_pk_fma_f32 v[112:113], v[112:113], s[84:85], v[186:187] op_sel_hi:[1,0,1] neg_lo:[0,0,1]
	v_pk_mul_f32 v[188:189], v[114:115], s[88:89] op_sel:[1,1] op_sel_hi:[0,1]
	v_pk_fma_f32 v[114:115], v[114:115], s[88:89], v[188:189] op_sel_hi:[1,0,1] neg_lo:[0,0,1]
	v_pk_mul_f32 v[166:167], v[118:119], s[84:85] op_sel:[1,1] op_sel_hi:[0,1]
	v_pk_fma_f32 v[118:119], v[118:119], s[84:85], v[166:167] op_sel_hi:[1,0,1] neg_lo:[0,0,1]
	v_pk_mul_f32 v[168:169], v[122:123], s[90:91] op_sel:[1,1] op_sel_hi:[0,1]
	v_pk_fma_f32 v[122:123], v[122:123], s[90:91], v[168:169] op_sel_hi:[1,0,1] neg_lo:[0,0,1]
	v_pk_mul_f32 v[174:175], v[126:127], s[88:89] op_sel:[1,1] op_sel_hi:[0,1]
	v_pk_fma_f32 v[126:127], v[126:127], s[88:89], v[174:175] op_sel_hi:[1,0,1] neg_lo:[0,0,1]
	v_pk_mul_f32 v[176:177], v[128:129], s[90:91] op_sel:[1,1] op_sel_hi:[0,1]
	v_pk_fma_f32 v[128:129], v[128:129], s[90:91], v[176:177] op_sel_hi:[1,0,1] neg_lo:[0,0,1]
	v_pk_mul_f32 v[178:179], v[130:131], s[98:99] op_sel:[1,1] op_sel_hi:[0,1]
	v_pk_fma_f32 v[130:131], v[130:131], s[98:99], v[178:179] op_sel_hi:[1,0,1] neg_lo:[0,0,1]
	v_pk_add_f32 v[180:181], v[100:101], v[104:105]
	v_pk_add_f32 v[182:183], v[100:101], v[104:105] neg_lo:[0,1] neg_hi:[0,1]
	v_pk_add_f32 v[184:185], v[102:103], v[106:107]
	v_pk_add_f32 v[186:187], v[102:103], v[106:107] neg_lo:[0,1] neg_hi:[0,1]
	v_pk_add_f32 v[100:101], v[180:181], v[184:185]
	v_pk_add_f32 v[104:105], v[180:181], v[184:185] neg_lo:[0,1] neg_hi:[0,1]
	v_pk_add_f32 v[102:103], v[182:183], v[186:187] op_sel:[0,1] op_sel_hi:[1,0] neg_hi:[0,1]
	v_pk_add_f32 v[106:107], v[182:183], v[186:187] op_sel:[0,1] op_sel_hi:[1,0] neg_lo:[0,1]
	v_pk_add_f32 v[188:189], v[108:109], v[112:113]
	v_pk_add_f32 v[166:167], v[108:109], v[112:113] neg_lo:[0,1] neg_hi:[0,1]
	v_pk_add_f32 v[168:169], v[110:111], v[114:115]
	v_pk_add_f32 v[174:175], v[110:111], v[114:115] neg_lo:[0,1] neg_hi:[0,1]
	v_pk_add_f32 v[108:109], v[188:189], v[168:169]
	v_pk_add_f32 v[112:113], v[188:189], v[168:169] neg_lo:[0,1] neg_hi:[0,1]
	v_pk_add_f32 v[110:111], v[166:167], v[174:175] op_sel:[0,1] op_sel_hi:[1,0] neg_hi:[0,1]
	v_pk_add_f32 v[114:115], v[166:167], v[174:175] op_sel:[0,1] op_sel_hi:[1,0] neg_lo:[0,1]
	v_pk_add_f32 v[176:177], v[116:117], v[120:121] op_sel:[0,1] op_sel_hi:[1,0] neg_hi:[0,1]
	v_pk_add_f32 v[178:179], v[116:117], v[120:121] op_sel:[0,1] op_sel_hi:[1,0] neg_lo:[0,1]
	v_pk_add_f32 v[180:181], v[118:119], v[122:123]
	v_pk_add_f32 v[182:183], v[118:119], v[122:123] neg_lo:[0,1] neg_hi:[0,1]
	v_pk_add_f32 v[116:117], v[176:177], v[180:181]
	v_pk_add_f32 v[120:121], v[176:177], v[180:181] neg_lo:[0,1] neg_hi:[0,1]
	v_pk_add_f32 v[118:119], v[178:179], v[182:183] op_sel:[0,1] op_sel_hi:[1,0] neg_hi:[0,1]
	v_pk_add_f32 v[122:123], v[178:179], v[182:183] op_sel:[0,1] op_sel_hi:[1,0] neg_lo:[0,1]
	v_pk_add_f32 v[184:185], v[124:125], v[128:129]
	v_pk_add_f32 v[186:187], v[124:125], v[128:129] neg_lo:[0,1] neg_hi:[0,1]
	v_pk_add_f32 v[188:189], v[126:127], v[130:131]
	v_pk_add_f32 v[166:167], v[126:127], v[130:131] neg_lo:[0,1] neg_hi:[0,1]
	v_pk_add_f32 v[124:125], v[184:185], v[188:189]
	v_pk_add_f32 v[128:129], v[184:185], v[188:189] neg_lo:[0,1] neg_hi:[0,1]
	v_pk_add_f32 v[126:127], v[186:187], v[166:167] op_sel:[0,1] op_sel_hi:[1,0] neg_hi:[0,1]
	v_pk_add_f32 v[130:131], v[186:187], v[166:167] op_sel:[0,1] op_sel_hi:[1,0] neg_lo:[0,1]
	v_add_u32_e32 v65, 0x10800, v3
	ds_write_b64 v65, v[100:101]
	v_pk_mul_f32 v[174:175], v[108:109], v[6:7] op_sel:[1,1] op_sel_hi:[0,1]
	v_pk_fma_f32 v[168:169], v[108:109], v[6:7], v[174:175] op_sel_hi:[1,0,1] neg_lo:[0,0,1]
	ds_write_b64 v65, v[168:169] offset:4224
	v_pk_mul_f32 v[178:179], v[116:117], v[8:9] op_sel:[1,1] op_sel_hi:[0,1]
	v_pk_fma_f32 v[176:177], v[116:117], v[8:9], v[178:179] op_sel_hi:[1,0,1] neg_lo:[0,0,1]
	ds_write_b64 v65, v[176:177] offset:8448
	v_pk_mul_f32 v[182:183], v[124:125], v[10:11] op_sel:[1,1] op_sel_hi:[0,1]
	v_pk_fma_f32 v[180:181], v[124:125], v[10:11], v[182:183] op_sel_hi:[1,0,1] neg_lo:[0,0,1]
	ds_write_b64 v65, v[180:181] offset:12672
	v_pk_mul_f32 v[186:187], v[102:103], v[12:13] op_sel:[1,1] op_sel_hi:[0,1]
	v_pk_fma_f32 v[184:185], v[102:103], v[12:13], v[186:187] op_sel_hi:[1,0,1] neg_lo:[0,0,1]
	ds_write_b64 v65, v[184:185] offset:16896
	v_pk_mul_f32 v[166:167], v[110:111], v[14:15] op_sel:[1,1] op_sel_hi:[0,1]
	v_pk_fma_f32 v[188:189], v[110:111], v[14:15], v[166:167] op_sel_hi:[1,0,1] neg_lo:[0,0,1]
	ds_write_b64 v65, v[188:189] offset:21120
	v_pk_mul_f32 v[168:169], v[118:119], v[16:17] op_sel:[1,1] op_sel_hi:[0,1]
	v_pk_fma_f32 v[174:175], v[118:119], v[16:17], v[168:169] op_sel_hi:[1,0,1] neg_lo:[0,0,1]
	ds_write_b64 v65, v[174:175] offset:25344
	v_pk_mul_f32 v[176:177], v[126:127], v[18:19] op_sel:[1,1] op_sel_hi:[0,1]
	v_pk_fma_f32 v[178:179], v[126:127], v[18:19], v[176:177] op_sel_hi:[1,0,1] neg_lo:[0,0,1]
	ds_write_b64 v65, v[178:179] offset:29568
	v_pk_mul_f32 v[180:181], v[104:105], v[20:21] op_sel:[1,1] op_sel_hi:[0,1]
	v_pk_fma_f32 v[182:183], v[104:105], v[20:21], v[180:181] op_sel_hi:[1,0,1] neg_lo:[0,0,1]
	ds_write_b64 v65, v[182:183] offset:33792
	v_pk_mul_f32 v[184:185], v[112:113], v[22:23] op_sel:[1,1] op_sel_hi:[0,1]
	v_pk_fma_f32 v[186:187], v[112:113], v[22:23], v[184:185] op_sel_hi:[1,0,1] neg_lo:[0,0,1]
	ds_write_b64 v65, v[186:187] offset:38016
	v_pk_mul_f32 v[188:189], v[120:121], v[24:25] op_sel:[1,1] op_sel_hi:[0,1]
	v_pk_fma_f32 v[166:167], v[120:121], v[24:25], v[188:189] op_sel_hi:[1,0,1] neg_lo:[0,0,1]
	ds_write_b64 v65, v[166:167] offset:42240
	v_pk_mul_f32 v[174:175], v[128:129], v[26:27] op_sel:[1,1] op_sel_hi:[0,1]
	v_pk_fma_f32 v[168:169], v[128:129], v[26:27], v[174:175] op_sel_hi:[1,0,1] neg_lo:[0,0,1]
	ds_write_b64 v65, v[168:169] offset:46464
	v_pk_mul_f32 v[178:179], v[106:107], v[28:29] op_sel:[1,1] op_sel_hi:[0,1]
	v_pk_fma_f32 v[176:177], v[106:107], v[28:29], v[178:179] op_sel_hi:[1,0,1] neg_lo:[0,0,1]
	ds_write_b64 v65, v[176:177] offset:50688
	v_pk_mul_f32 v[182:183], v[114:115], v[30:31] op_sel:[1,1] op_sel_hi:[0,1]
	v_pk_fma_f32 v[180:181], v[114:115], v[30:31], v[182:183] op_sel_hi:[1,0,1] neg_lo:[0,0,1]
	ds_write_b64 v65, v[180:181] offset:54912
	v_pk_mul_f32 v[186:187], v[122:123], v[32:33] op_sel:[1,1] op_sel_hi:[0,1]
	v_pk_fma_f32 v[184:185], v[122:123], v[32:33], v[186:187] op_sel_hi:[1,0,1] neg_lo:[0,0,1]
	ds_write_b64 v65, v[184:185] offset:59136
	v_pk_mul_f32 v[166:167], v[130:131], v[34:35] op_sel:[1,1] op_sel_hi:[0,1]
	v_pk_fma_f32 v[188:189], v[130:131], v[34:35], v[166:167] op_sel_hi:[1,0,1] neg_lo:[0,0,1]
	ds_write_b64 v65, v[188:189] offset:63360
	s_waitcnt vmcnt(7)
; #define LAS __attribute__((address_space(3)))
; #define WG_SYNC() do { asm volatile("s_waitcnt lgkmcnt(0)" ::: "memory"); __builtin_amdgcn_s_barrier(); asm volatile("" ::: "memory"); } while (0)
; __device__ __forceinline__ void hy_stage(LAS float* plane, const bf16_t* PHY, int cg, int jc, int tid) {
;     asm volatile("" : "+v"(tid));
;     const u32x4* src = (const u32x4*)(PHY + (size_t)cg * MT * 4);
; #pragma unroll
;     for (int k = 0; k < 8; ++k) { const int i = tid + 512 * k; const u32x4 v = src[i];
;         const unsigned w0 = (jc & 2) ? v.y : v.x, w1 = (jc & 2) ? v.w : v.z;
;         f32x2 o; o.x = (jc & 1) ? bf_hi(w0) : bf_lo(w0); o.y = (jc & 1) ? bf_hi(w1) : bf_lo(w1);
;         *(LAS f32x2*)(plane + 2 * i) = o; }
; }
; __device__ __forceinline__ void hy_sconv(const LAS float* plane, float w0, float w1, float w2, float cb, int n2, float (&u)[8][2]) {
;     asm volatile("" : "+v"(n2));
; #pragma unroll
;     for (int r = 0; r < 8; ++r)
; #pragma unroll
;         for (int b = 0; b < 2; ++b) { const int t = n2 + 512 * r, row = b * SEQ + t;
;             float a = cb + w1 * plane[row];
;             if (t > 0) a += w0 * plane[row - 1];
;             if (t < SEQ - 1) a += w2 * plane[row + 1];
;             u[r][b] = a; }
; }
; __device__ __forceinline__ void hyena_fft(LAS unsigned char* lds, int layer, int G, const int wave_s) {
;     ...
;             hy_stage(pl0, PHY, 2 * (HY / 4) + unit, jc, tid); __builtin_amdgcn_sched_barrier(0); hy_stage(pl1, PHY, unit, jc, tid); __builtin_amdgcn_sched_barrier(0);
;             WG_SYNC();
;             float uz[8][2], ux[8][2];
;             hy_sconv(pl0, cw[2 * HY + c], cw[3 * HY + 2 * HY + c], cw[6 * HY + 2 * HY + c], cb[2 * HY + c], n2, uz);
	v_perm_b32 v174, 0, v58, s15
	v_perm_b32 v175, 0, v60, s15
	ds_write_b64 v206, v[174:175]
	s_waitcnt vmcnt(6)
	v_perm_b32 v168, 0, v62, s15
	v_perm_b32 v169, 0, v64, s15
	ds_write_b64 v206, v[168:169] offset:4096
	s_waitcnt vmcnt(5)
	v_perm_b32 v178, 0, v66, s15
	v_perm_b32 v179, 0, v68, s15
	ds_write_b64 v206, v[178:179] offset:8192
	s_waitcnt vmcnt(4)
	v_perm_b32 v176, 0, v70, s15
	v_perm_b32 v177, 0, v72, s15
	ds_write_b64 v206, v[176:177] offset:12288
	s_waitcnt vmcnt(3)
	v_perm_b32 v182, 0, v74, s15
	v_perm_b32 v183, 0, v76, s15
	ds_write_b64 v206, v[182:183] offset:16384
	s_waitcnt vmcnt(2)
	v_perm_b32 v180, 0, v78, s15
	v_perm_b32 v181, 0, v80, s15
	ds_write_b64 v206, v[180:181] offset:20480
	s_waitcnt vmcnt(1)
	v_perm_b32 v186, 0, v82, s15
	v_perm_b32 v187, 0, v84, s15
	ds_write_b64 v206, v[186:187] offset:24576
	s_waitcnt vmcnt(0)
	v_perm_b32 v184, 0, v86, s15
	v_perm_b32 v185, 0, v88, s15
	ds_write_b64 v206, v[184:185] offset:28672
	s_add_u32 s56, s38, s73
	s_addc_u32 s57, s39, 0
	global_load_dwordx3 v[58:60], v216, s[56:57]
	global_load_dwordx3 v[62:64], v218, s[56:57]
	global_load_dwordx3 v[66:68], v220, s[56:57]
	global_load_dwordx3 v[70:72], v222, s[56:57]
	global_load_dwordx3 v[74:76], v240, s[56:57]
	global_load_dwordx3 v[78:80], v242, s[56:57]
	global_load_dwordx3 v[82:84], v244, s[56:57]
	global_load_dwordx3 v[86:88], v61, s[56:57]
	s_load_dwordx2 s[60:61], s[94:95], 0x48
	s_load_dwordx2 s[62:63], s[94:95], 0x50
	s_load_dwordx2 s[50:51], s[94:95], 0x88
	s_lshl_b32 s43, s80, 2
	s_mul_i32 s53, s76, 0x9000
	s_add_u32 s53, s53, s43
	s_mul_i32 s55, s76, 0x3000
	s_add_u32 s55, s55, s43
	s_waitcnt lgkmcnt(0)
	s_add_u32 s60, s60, s53
	s_addc_u32 s61, s61, 0
	s_add_u32 s62, s62, s55
	s_addc_u32 s63, s63, 0
	s_mul_i32 s53, s76, 0x2000
	s_add_u32 s53, s53, s43
	s_add_u32 s50, s50, s53
	s_addc_u32 s51, s51, 0
	s_load_dword s17, s[60:61], 0x2000
	s_load_dword s23, s[60:61], 0x5000
	s_load_dword s25, s[60:61], 0x8000
	s_load_dword s26, s[62:63], 0x2000
	s_waitcnt lgkmcnt(0)
	s_barrier
	v_mov_b32_e32 v166, s17
	v_mov_b32_e32 v167, s23
	v_mov_b32_e32 v188, s25
	v_mov_b32_e32 v189, s26
	ds_read_b32 v174, v208
	ds_read_b32 v168, v210
	ds_read_b32 v178, v208 offset:4
	ds_read_b32 v175, v208 offset:16384
	ds_read_b32 v169, v210 offset:16384
	ds_read_b32 v179, v208 offset:16388
	ds_read_b32 v176, v208 offset:2048
	ds_read_b32 v182, v208 offset:2044
	ds_read_b32 v180, v208 offset:2052
	ds_read_b32 v177, v208 offset:18432
	ds_read_b32 v183, v208 offset:18428
	ds_read_b32 v181, v208 offset:18436
	s_waitcnt lgkmcnt(10)
	v_cndmask_b32_e64 v168, v168, 0, s[10:11]
	s_waitcnt lgkmcnt(7)
	v_cndmask_b32_e64 v169, v169, 0, s[10:11]
	v_pk_fma_f32 v[132:133], v[166:167], v[174:175], v[188:189] op_sel:[1,0,1]
	v_pk_fma_f32 v[132:133], v[166:167], v[168:169], v[132:133] op_sel_hi:[0,1,1]
	s_waitcnt lgkmcnt(6)
	v_pk_fma_f32 v[132:133], v[188:189], v[178:179], v[132:133] op_sel_hi:[0,1,1]
	s_waitcnt lgkmcnt(2)
	v_pk_fma_f32 v[134:135], v[166:167], v[176:177], v[188:189] op_sel:[1,0,1]
	s_waitcnt lgkmcnt(1)
	v_pk_fma_f32 v[134:135], v[166:167], v[182:183], v[134:135] op_sel_hi:[0,1,1]
	s_waitcnt lgkmcnt(0)
	v_pk_fma_f32 v[134:135], v[188:189], v[180:181], v[134:135] op_sel_hi:[0,1,1]
	ds_read_b32 v186, v208 offset:4096
	ds_read_b32 v184, v208 offset:4092
	ds_read_b32 v174, v208 offset:4100
	ds_read_b32 v187, v208 offset:20480
	ds_read_b32 v185, v208 offset:20476
	ds_read_b32 v175, v208 offset:20484
	ds_read_b32 v168, v208 offset:6144
	ds_read_b32 v178, v208 offset:6140
	ds_read_b32 v176, v208 offset:6148
	ds_read_b32 v169, v208 offset:22528
	ds_read_b32 v179, v208 offset:22524
	ds_read_b32 v177, v208 offset:22532
	s_waitcnt lgkmcnt(8)
	v_pk_fma_f32 v[136:137], v[166:167], v[186:187], v[188:189] op_sel:[1,0,1]
	s_waitcnt lgkmcnt(7)
	v_pk_fma_f32 v[136:137], v[166:167], v[184:185], v[136:137] op_sel_hi:[0,1,1]
	s_waitcnt lgkmcnt(6)
	v_pk_fma_f32 v[136:137], v[188:189], v[174:175], v[136:137] op_sel_hi:[0,1,1]
	s_waitcnt lgkmcnt(2)
	v_pk_fma_f32 v[138:139], v[166:167], v[168:169], v[188:189] op_sel:[1,0,1]
	s_waitcnt lgkmcnt(1)
	v_pk_fma_f32 v[138:139], v[166:167], v[178:179], v[138:139] op_sel_hi:[0,1,1]
	s_waitcnt lgkmcnt(0)
	v_pk_fma_f32 v[138:139], v[188:189], v[176:177], v[138:139] op_sel_hi:[0,1,1]
	ds_read_b32 v182, v208 offset:8192
	ds_read_b32 v180, v208 offset:8188
	ds_read_b32 v186, v208 offset:8196
	ds_read_b32 v183, v208 offset:24576
	ds_read_b32 v181, v208 offset:24572
	ds_read_b32 v187, v208 offset:24580
	ds_read_b32 v184, v208 offset:10240
	ds_read_b32 v174, v208 offset:10236
	ds_read_b32 v168, v208 offset:10244
	ds_read_b32 v185, v208 offset:26624
	ds_read_b32 v175, v208 offset:26620
	ds_read_b32 v169, v208 offset:26628
	s_waitcnt lgkmcnt(8)
	v_pk_fma_f32 v[140:141], v[166:167], v[182:183], v[188:189] op_sel:[1,0,1]
	s_waitcnt lgkmcnt(7)
	v_pk_fma_f32 v[140:141], v[166:167], v[180:181], v[140:141] op_sel_hi:[0,1,1]
	s_waitcnt lgkmcnt(6)
	v_pk_fma_f32 v[140:141], v[188:189], v[186:187], v[140:141] op_sel_hi:[0,1,1]
	s_waitcnt lgkmcnt(2)
	v_pk_fma_f32 v[142:143], v[166:167], v[184:185], v[188:189] op_sel:[1,0,1]
	s_waitcnt lgkmcnt(1)
	v_pk_fma_f32 v[142:143], v[166:167], v[174:175], v[142:143] op_sel_hi:[0,1,1]
	s_waitcnt lgkmcnt(0)
	v_pk_fma_f32 v[142:143], v[188:189], v[168:169], v[142:143] op_sel_hi:[0,1,1]
	ds_read_b32 v178, v208 offset:12288
	ds_read_b32 v176, v208 offset:12284
	ds_read_b32 v182, v208 offset:12292
	ds_read_b32 v179, v208 offset:28672
	ds_read_b32 v177, v208 offset:28668
	ds_read_b32 v183, v208 offset:28676
	ds_read_b32 v180, v208 offset:14336
	ds_read_b32 v186, v208 offset:14332
	ds_read_b32 v184, v208 offset:14340
	ds_read_b32 v181, v208 offset:30720
	ds_read_b32 v187, v208 offset:30716
	ds_read_b32 v185, v208 offset:30724
	s_waitcnt lgkmcnt(8)
; #define LAS __attribute__((address_space(3)))
; __device__ __forceinline__ f32x2 cmul(f32x2 a, f32x2 b) { return (f32x2){a.x * b.x - a.y * b.y, a.x * b.y + a.y * b.x}; }
; __device__ __forceinline__ void fft_fwd2(LAS f32x2* B, const LAS f32x2* TW2, int tid) {
;     asm volatile("" : "+v"(tid));
;     const int b = tid >> 5, n2 = tid & 31, base = 512 * b + n2; f32x2 x[16];
; #pragma unroll
;     for (int r = 0; r < 16; ++r) x[r] = B[fpad(base + 32 * r)];
;     dft16<false>(x);
;     B[fpad(base)] = x[0];
; #pragma unroll
;     for (int k = 1; k < 16; ++k) B[fpad(base + 32 * k)] = cmul(x[k], TW2[k * 32 + n2]);
; }
; __device__ __forceinline__ void hy_sconv(const LAS float* plane, float w0, float w1, float w2, float cb, int n2, float (&u)[8][2]) {
;     asm volatile("" : "+v"(n2));
; #pragma unroll
;     for (int r = 0; r < 8; ++r)
; #pragma unroll
;         for (int b = 0; b < 2; ++b) { const int t = n2 + 512 * r, row = b * SEQ + t;
;             float a = cb + w1 * plane[row];
;             if (t > 0) a += w0 * plane[row - 1];
;             if (t < SEQ - 1) a += w2 * plane[row + 1];
;             u[r][b] = a; }
; }
	v_pk_fma_f32 v[144:145], v[166:167], v[178:179], v[188:189] op_sel:[1,0,1]
	s_waitcnt lgkmcnt(7)
	v_pk_fma_f32 v[144:145], v[166:167], v[176:177], v[144:145] op_sel_hi:[0,1,1]
	s_waitcnt lgkmcnt(6)
	v_pk_fma_f32 v[144:145], v[188:189], v[182:183], v[144:145] op_sel_hi:[0,1,1]
	s_waitcnt lgkmcnt(3)
	v_cndmask_b32_e64 v184, v184, 0, s[28:29]
	s_waitcnt lgkmcnt(0)
	v_cndmask_b32_e64 v185, v185, 0, s[28:29]
	v_pk_fma_f32 v[146:147], v[166:167], v[180:181], v[188:189] op_sel:[1,0,1]
	v_pk_fma_f32 v[146:147], v[166:167], v[186:187], v[146:147] op_sel_hi:[0,1,1]
	v_pk_fma_f32 v[146:147], v[188:189], v[184:185], v[146:147] op_sel_hi:[0,1,1]
	s_load_dword s17, s[60:61], 0x0
	s_load_dword s23, s[60:61], 0x3000
	s_load_dword s25, s[60:61], 0x6000
	s_load_dword s26, s[62:63], 0x0
	s_waitcnt vmcnt(7)
	v_perm_b32 v174, 0, v58, s15
	v_perm_b32 v175, 0, v60, s15
	ds_write_b64 v206, v[174:175] offset:32768
	s_waitcnt vmcnt(6)
	v_perm_b32 v168, 0, v62, s15
	v_perm_b32 v169, 0, v64, s15
	ds_write_b64 v206, v[168:169] offset:36864
	s_waitcnt vmcnt(5)
	v_perm_b32 v178, 0, v66, s15
	v_perm_b32 v179, 0, v68, s15
	ds_write_b64 v206, v[178:179] offset:40960
	s_waitcnt vmcnt(4)
	v_perm_b32 v176, 0, v70, s15
	v_perm_b32 v177, 0, v72, s15
	ds_write_b64 v206, v[176:177] offset:45056
	s_waitcnt vmcnt(3)
	v_perm_b32 v182, 0, v74, s15
	v_perm_b32 v183, 0, v76, s15
	ds_write_b64 v206, v[182:183] offset:49152
	s_waitcnt vmcnt(2)
	v_perm_b32 v180, 0, v78, s15
	v_perm_b32 v181, 0, v80, s15
	ds_write_b64 v206, v[180:181] offset:53248
	s_waitcnt vmcnt(1)
	v_perm_b32 v186, 0, v82, s15
	v_perm_b32 v187, 0, v84, s15
	ds_write_b64 v206, v[186:187] offset:57344
	s_waitcnt vmcnt(0)
	v_perm_b32 v184, 0, v86, s15
	v_perm_b32 v185, 0, v88, s15
	ds_write_b64 v206, v[184:185] offset:61440
	s_add_u32 s56, s38, s73
	s_addc_u32 s57, s39, 0
	s_add_u32 s56, s56, 0x1100000
	s_addc_u32 s57, s57, 0
	global_load_dwordx3 v[58:60], v216, s[56:57]
	global_load_dwordx3 v[62:64], v218, s[56:57]
	global_load_dwordx3 v[66:68], v220, s[56:57]
	global_load_dwordx3 v[70:72], v222, s[56:57]
	global_load_dwordx3 v[74:76], v240, s[56:57]
	global_load_dwordx3 v[78:80], v242, s[56:57]
	global_load_dwordx3 v[82:84], v244, s[56:57]
	global_load_dwordx3 v[86:88], v61, s[56:57]
	v_add_u32_e32 v65, 0x10800, v5
	ds_read_b64 v[100:101], v65
	ds_read_b64 v[102:103], v65 offset:1056
	ds_read_b64 v[104:105], v65 offset:2112
	ds_read_b64 v[106:107], v65 offset:3168
	ds_read_b64 v[108:109], v65 offset:264
	ds_read_b64 v[110:111], v65 offset:1320
	ds_read_b64 v[112:113], v65 offset:2376
	ds_read_b64 v[114:115], v65 offset:3432
	ds_read_b64 v[116:117], v65 offset:528
	ds_read_b64 v[118:119], v65 offset:1584
	ds_read_b64 v[120:121], v65 offset:2640
	ds_read_b64 v[122:123], v65 offset:3696
	s_waitcnt lgkmcnt(8)
	ds_read_b64 v[124:125], v65 offset:792
	ds_read_b64 v[126:127], v65 offset:1848
	ds_read_b64 v[128:129], v65 offset:2904
	ds_read_b64 v[130:131], v65 offset:3960
	v_pk_add_f32 v[166:167], v[100:101], v[104:105]
	v_pk_add_f32 v[188:189], v[100:101], v[104:105] neg_lo:[0,1] neg_hi:[0,1]
	v_pk_add_f32 v[174:175], v[102:103], v[106:107]
	v_pk_add_f32 v[168:169], v[102:103], v[106:107] neg_lo:[0,1] neg_hi:[0,1]
	v_pk_add_f32 v[100:101], v[166:167], v[174:175]
	v_pk_add_f32 v[104:105], v[166:167], v[174:175] neg_lo:[0,1] neg_hi:[0,1]
	v_pk_add_f32 v[102:103], v[188:189], v[168:169] op_sel:[0,1] op_sel_hi:[1,0] neg_hi:[0,1]
	v_pk_add_f32 v[106:107], v[188:189], v[168:169] op_sel:[0,1] op_sel_hi:[1,0] neg_lo:[0,1]
	s_waitcnt lgkmcnt(9)
	v_pk_add_f32 v[178:179], v[108:109], v[112:113]
	v_pk_add_f32 v[176:177], v[108:109], v[112:113] neg_lo:[0,1] neg_hi:[0,1]
	s_waitcnt lgkmcnt(8)
	v_pk_add_f32 v[182:183], v[110:111], v[114:115]
	v_pk_add_f32 v[180:181], v[110:111], v[114:115] neg_lo:[0,1] neg_hi:[0,1]
	v_pk_add_f32 v[108:109], v[178:179], v[182:183]
	v_pk_add_f32 v[112:113], v[178:179], v[182:183] neg_lo:[0,1] neg_hi:[0,1]
	v_pk_add_f32 v[110:111], v[176:177], v[180:181] op_sel:[0,1] op_sel_hi:[1,0] neg_hi:[0,1]
	v_pk_add_f32 v[114:115], v[176:177], v[180:181] op_sel:[0,1] op_sel_hi:[1,0] neg_lo:[0,1]
	s_waitcnt lgkmcnt(5)
	v_pk_add_f32 v[186:187], v[116:117], v[120:121]
	v_pk_add_f32 v[184:185], v[116:117], v[120:121] neg_lo:[0,1] neg_hi:[0,1]
	s_waitcnt lgkmcnt(4)
	v_pk_add_f32 v[166:167], v[118:119], v[122:123]
	v_pk_add_f32 v[188:189], v[118:119], v[122:123] neg_lo:[0,1] neg_hi:[0,1]
	v_pk_add_f32 v[116:117], v[186:187], v[166:167]
	v_pk_add_f32 v[120:121], v[186:187], v[166:167] neg_lo:[0,1] neg_hi:[0,1]
	v_pk_add_f32 v[118:119], v[184:185], v[188:189] op_sel:[0,1] op_sel_hi:[1,0] neg_hi:[0,1]
	v_pk_add_f32 v[122:123], v[184:185], v[188:189] op_sel:[0,1] op_sel_hi:[1,0] neg_lo:[0,1]
	s_waitcnt lgkmcnt(1)
	v_pk_add_f32 v[174:175], v[124:125], v[128:129]
	v_pk_add_f32 v[168:169], v[124:125], v[128:129] neg_lo:[0,1] neg_hi:[0,1]
	s_waitcnt lgkmcnt(0)
; #define LAS __attribute__((address_space(3)))
; __device__ __forceinline__ f32x2 cmul(f32x2 a, f32x2 b) { return (f32x2){a.x * b.x - a.y * b.y, a.x * b.y + a.y * b.x}; }
; template <bool INV> __device__ __forceinline__ f32x2 cmul_tw(f32x2 a, f32x2 w) { return INV ? cmulc(a, w) : cmul(a, w); }
; template <bool INV> __device__ __forceinline__ void dft16(f32x2 (&x)[16]) {
;     constexpr float C1 = 0.92387953251128674f, S1 = 0.38268343236508977f, C2 = 0.70710678118654752f;
; #pragma unroll
;     for (int b = 0; b < 4; ++b) dft4<INV>(x[b], x[4 + b], x[8 + b], x[12 + b]);
;     const f32x2 w1 = {C1, -S1}, w2 = {C2, -C2}, w3 = {S1, -C1}, w4 = {0.f, -1.f}, w6 = {-C2, -C2}, w9 = {-C1, S1};
;     x[4 * 1 + 1] = cmul_tw<INV>(x[5], w1); x[4 * 1 + 2] = cmul_tw<INV>(x[6], w2); x[4 * 1 + 3] = cmul_tw<INV>(x[7], w3);
;     x[4 * 2 + 1] = cmul_tw<INV>(x[9], w2); x[4 * 2 + 2] = cmul_tw<INV>(x[10], w4); x[4 * 2 + 3] = cmul_tw<INV>(x[11], w6);
;     x[4 * 3 + 1] = cmul_tw<INV>(x[13], w3); x[4 * 3 + 2] = cmul_tw<INV>(x[14], w6); x[4 * 3 + 3] = cmul_tw<INV>(x[15], w9);
; #pragma unroll
;     for (int c = 0; c < 4; ++c) dft4<INV>(x[4 * c], x[4 * c + 1], x[4 * c + 2], x[4 * c + 3]);
;     f32x2 y[16];
; #pragma unroll
;     for (int k = 0; k < 16; ++k) y[k] = x[4 * (k & 3) + (k >> 2)];
; #pragma unroll
;     for (int k = 0; k < 16; ++k) x[k] = y[k];
; }
; __device__ __forceinline__ void fft_fwd2(LAS f32x2* B, const LAS f32x2* TW2, int tid) {
;     asm volatile("" : "+v"(tid));
;     const int b = tid >> 5, n2 = tid & 31, base = 512 * b + n2; f32x2 x[16];
; #pragma unroll
;     for (int r = 0; r < 16; ++r) x[r] = B[fpad(base + 32 * r)];
;     dft16<false>(x);
;     B[fpad(base)] = x[0];
; #pragma unroll
;     for (int k = 1; k < 16; ++k) B[fpad(base + 32 * k)] = cmul(x[k], TW2[k * 32 + n2]);
; }
	v_pk_add_f32 v[178:179], v[126:127], v[130:131]
	v_pk_add_f32 v[176:177], v[126:127], v[130:131] neg_lo:[0,1] neg_hi:[0,1]
	v_pk_add_f32 v[124:125], v[174:175], v[178:179]
	v_pk_add_f32 v[128:129], v[174:175], v[178:179] neg_lo:[0,1] neg_hi:[0,1]
	v_pk_add_f32 v[126:127], v[168:169], v[176:177] op_sel:[0,1] op_sel_hi:[1,0] neg_hi:[0,1]
	v_pk_add_f32 v[130:131], v[168:169], v[176:177] op_sel:[0,1] op_sel_hi:[1,0] neg_lo:[0,1]
	v_pk_mul_f32 v[182:183], v[110:111], s[68:69] op_sel:[1,1] op_sel_hi:[0,1]
	v_pk_fma_f32 v[110:111], v[110:111], s[68:69], v[182:183] op_sel_hi:[1,0,1] neg_lo:[0,0,1]
	v_pk_mul_f32 v[180:181], v[118:119], s[84:85] op_sel:[1,1] op_sel_hi:[0,1]
	v_pk_fma_f32 v[118:119], v[118:119], s[84:85], v[180:181] op_sel_hi:[1,0,1] neg_lo:[0,0,1]
	v_pk_mul_f32 v[186:187], v[126:127], s[88:89] op_sel:[1,1] op_sel_hi:[0,1]
	v_pk_fma_f32 v[126:127], v[126:127], s[88:89], v[186:187] op_sel_hi:[1,0,1] neg_lo:[0,0,1]
	v_pk_mul_f32 v[184:185], v[112:113], s[84:85] op_sel:[1,1] op_sel_hi:[0,1]
	v_pk_fma_f32 v[112:113], v[112:113], s[84:85], v[184:185] op_sel_hi:[1,0,1] neg_lo:[0,0,1]
	v_pk_mul_f32 v[166:167], v[128:129], s[90:91] op_sel:[1,1] op_sel_hi:[0,1]
	v_pk_fma_f32 v[128:129], v[128:129], s[90:91], v[166:167] op_sel_hi:[1,0,1] neg_lo:[0,0,1]
	v_pk_mul_f32 v[188:189], v[114:115], s[88:89] op_sel:[1,1] op_sel_hi:[0,1]
	v_pk_fma_f32 v[114:115], v[114:115], s[88:89], v[188:189] op_sel_hi:[1,0,1] neg_lo:[0,0,1]
	v_pk_mul_f32 v[174:175], v[122:123], s[90:91] op_sel:[1,1] op_sel_hi:[0,1]
	v_pk_fma_f32 v[122:123], v[122:123], s[90:91], v[174:175] op_sel_hi:[1,0,1] neg_lo:[0,0,1]
	v_pk_mul_f32 v[168:169], v[130:131], s[98:99] op_sel:[1,1] op_sel_hi:[0,1]
	v_pk_fma_f32 v[130:131], v[130:131], s[98:99], v[168:169] op_sel_hi:[1,0,1] neg_lo:[0,0,1]
	v_pk_add_f32 v[178:179], v[100:101], v[116:117]
	v_pk_add_f32 v[176:177], v[100:101], v[116:117] neg_lo:[0,1] neg_hi:[0,1]
	v_pk_add_f32 v[182:183], v[108:109], v[124:125]
	v_pk_add_f32 v[180:181], v[108:109], v[124:125] neg_lo:[0,1] neg_hi:[0,1]
	v_pk_add_f32 v[100:101], v[178:179], v[182:183]
	v_pk_add_f32 v[116:117], v[178:179], v[182:183] neg_lo:[0,1] neg_hi:[0,1]
	v_pk_add_f32 v[108:109], v[176:177], v[180:181] op_sel:[0,1] op_sel_hi:[1,0] neg_hi:[0,1]
	v_pk_add_f32 v[124:125], v[176:177], v[180:181] op_sel:[0,1] op_sel_hi:[1,0] neg_lo:[0,1]
	v_pk_add_f32 v[186:187], v[102:103], v[118:119]
	v_pk_add_f32 v[184:185], v[102:103], v[118:119] neg_lo:[0,1] neg_hi:[0,1]
	v_pk_add_f32 v[166:167], v[110:111], v[126:127]
	v_pk_add_f32 v[188:189], v[110:111], v[126:127] neg_lo:[0,1] neg_hi:[0,1]
	v_pk_add_f32 v[102:103], v[186:187], v[166:167]
	v_pk_add_f32 v[118:119], v[186:187], v[166:167] neg_lo:[0,1] neg_hi:[0,1]
	v_pk_add_f32 v[110:111], v[184:185], v[188:189] op_sel:[0,1] op_sel_hi:[1,0] neg_hi:[0,1]
	v_pk_add_f32 v[126:127], v[184:185], v[188:189] op_sel:[0,1] op_sel_hi:[1,0] neg_lo:[0,1]
	v_pk_add_f32 v[174:175], v[104:105], v[120:121] op_sel:[0,1] op_sel_hi:[1,0] neg_hi:[0,1]
	v_pk_add_f32 v[168:169], v[104:105], v[120:121] op_sel:[0,1] op_sel_hi:[1,0] neg_lo:[0,1]
	v_pk_add_f32 v[178:179], v[112:113], v[128:129]
	v_pk_add_f32 v[176:177], v[112:113], v[128:129] neg_lo:[0,1] neg_hi:[0,1]
	v_pk_add_f32 v[104:105], v[174:175], v[178:179]
	v_pk_add_f32 v[120:121], v[174:175], v[178:179] neg_lo:[0,1] neg_hi:[0,1]
	v_pk_add_f32 v[112:113], v[168:169], v[176:177] op_sel:[0,1] op_sel_hi:[1,0] neg_hi:[0,1]
	v_pk_add_f32 v[128:129], v[168:169], v[176:177] op_sel:[0,1] op_sel_hi:[1,0] neg_lo:[0,1]
	v_pk_add_f32 v[182:183], v[106:107], v[122:123]
	v_pk_add_f32 v[180:181], v[106:107], v[122:123] neg_lo:[0,1] neg_hi:[0,1]
	v_pk_add_f32 v[186:187], v[114:115], v[130:131]
	v_pk_add_f32 v[184:185], v[114:115], v[130:131] neg_lo:[0,1] neg_hi:[0,1]
	v_pk_add_f32 v[106:107], v[182:183], v[186:187]
	v_pk_add_f32 v[122:123], v[182:183], v[186:187] neg_lo:[0,1] neg_hi:[0,1]
	v_pk_add_f32 v[114:115], v[180:181], v[184:185] op_sel:[0,1] op_sel_hi:[1,0] neg_hi:[0,1]
	v_pk_add_f32 v[130:131], v[180:181], v[184:185] op_sel:[0,1] op_sel_hi:[1,0] neg_lo:[0,1]
	ds_write_b64 v65, v[100:101]
	ds_read_b64 v[166:167], v56 offset:256
	ds_read_b64 v[188:189], v56 offset:512
	ds_read_b64 v[174:175], v56 offset:768
	ds_read_b64 v[168:169], v56 offset:1024
	s_waitcnt lgkmcnt(3)
	v_pk_mul_f32 v[178:179], v[102:103], v[166:167] op_sel:[1,1] op_sel_hi:[0,1]
	v_pk_fma_f32 v[102:103], v[102:103], v[166:167], v[178:179] op_sel_hi:[1,0,1] neg_lo:[0,0,1]
	ds_write_b64 v65, v[102:103] offset:264
	s_waitcnt lgkmcnt(3)
	v_pk_mul_f32 v[176:177], v[104:105], v[188:189] op_sel:[1,1] op_sel_hi:[0,1]
	v_pk_fma_f32 v[104:105], v[104:105], v[188:189], v[176:177] op_sel_hi:[1,0,1] neg_lo:[0,0,1]
	ds_write_b64 v65, v[104:105] offset:528
	s_waitcnt lgkmcnt(3)
	v_pk_mul_f32 v[182:183], v[106:107], v[174:175] op_sel:[1,1] op_sel_hi:[0,1]
	v_pk_fma_f32 v[106:107], v[106:107], v[174:175], v[182:183] op_sel_hi:[1,0,1] neg_lo:[0,0,1]
	ds_write_b64 v65, v[106:107] offset:792
	s_waitcnt lgkmcnt(3)
	v_pk_mul_f32 v[180:181], v[108:109], v[168:169] op_sel:[1,1] op_sel_hi:[0,1]
	v_pk_fma_f32 v[108:109], v[108:109], v[168:169], v[180:181] op_sel_hi:[1,0,1] neg_lo:[0,0,1]
	ds_write_b64 v65, v[108:109] offset:1056
	ds_read_b64 v[186:187], v56 offset:1280
	ds_read_b64 v[184:185], v56 offset:1536
	ds_read_b64 v[178:179], v56 offset:1792
	ds_read_b64 v[176:177], v56 offset:2048
	s_waitcnt lgkmcnt(3)
	v_pk_mul_f32 v[182:183], v[110:111], v[186:187] op_sel:[1,1] op_sel_hi:[0,1]
	v_pk_fma_f32 v[110:111], v[110:111], v[186:187], v[182:183] op_sel_hi:[1,0,1] neg_lo:[0,0,1]
	ds_write_b64 v65, v[110:111] offset:1320
	s_waitcnt lgkmcnt(3)
; #define LAS __attribute__((address_space(3)))
; __device__ __forceinline__ f32x2 cmul(f32x2 a, f32x2 b) { return (f32x2){a.x * b.x - a.y * b.y, a.x * b.y + a.y * b.x}; }
; __device__ __forceinline__ void fft_fwd2(LAS f32x2* B, const LAS f32x2* TW2, int tid) {
;     asm volatile("" : "+v"(tid));
;     const int b = tid >> 5, n2 = tid & 31, base = 512 * b + n2; f32x2 x[16];
; #pragma unroll
;     for (int r = 0; r < 16; ++r) x[r] = B[fpad(base + 32 * r)];
;     dft16<false>(x);
;     B[fpad(base)] = x[0];
; #pragma unroll
;     for (int k = 1; k < 16; ++k) B[fpad(base + 32 * k)] = cmul(x[k], TW2[k * 32 + n2]);
; }
; __device__ __forceinline__ void hy_sconv(const LAS float* plane, float w0, float w1, float w2, float cb, int n2, float (&u)[8][2]) {
;     asm volatile("" : "+v"(n2));
; #pragma unroll
;     for (int r = 0; r < 8; ++r)
; #pragma unroll
;         for (int b = 0; b < 2; ++b) { const int t = n2 + 512 * r, row = b * SEQ + t;
;             float a = cb + w1 * plane[row];
;             if (t > 0) a += w0 * plane[row - 1];
;             if (t < SEQ - 1) a += w2 * plane[row + 1];
;             u[r][b] = a; }
; }
	v_pk_mul_f32 v[180:181], v[112:113], v[184:185] op_sel:[1,1] op_sel_hi:[0,1]
	v_pk_fma_f32 v[112:113], v[112:113], v[184:185], v[180:181] op_sel_hi:[1,0,1] neg_lo:[0,0,1]
	ds_write_b64 v65, v[112:113] offset:1584
	s_waitcnt lgkmcnt(3)
	v_pk_mul_f32 v[166:167], v[114:115], v[178:179] op_sel:[1,1] op_sel_hi:[0,1]
	v_pk_fma_f32 v[114:115], v[114:115], v[178:179], v[166:167] op_sel_hi:[1,0,1] neg_lo:[0,0,1]
	ds_write_b64 v65, v[114:115] offset:1848
	s_waitcnt lgkmcnt(3)
	v_pk_mul_f32 v[188:189], v[116:117], v[176:177] op_sel:[1,1] op_sel_hi:[0,1]
	v_pk_fma_f32 v[116:117], v[116:117], v[176:177], v[188:189] op_sel_hi:[1,0,1] neg_lo:[0,0,1]
	ds_write_b64 v65, v[116:117] offset:2112
	ds_read_b64 v[174:175], v56 offset:2304
	ds_read_b64 v[168:169], v56 offset:2560
	ds_read_b64 v[182:183], v56 offset:2816
	ds_read_b64 v[180:181], v56 offset:3072
	s_waitcnt lgkmcnt(3)
	v_pk_mul_f32 v[166:167], v[118:119], v[174:175] op_sel:[1,1] op_sel_hi:[0,1]
	v_pk_fma_f32 v[118:119], v[118:119], v[174:175], v[166:167] op_sel_hi:[1,0,1] neg_lo:[0,0,1]
	ds_write_b64 v65, v[118:119] offset:2376
	s_waitcnt lgkmcnt(3)
	v_pk_mul_f32 v[188:189], v[120:121], v[168:169] op_sel:[1,1] op_sel_hi:[0,1]
	v_pk_fma_f32 v[120:121], v[120:121], v[168:169], v[188:189] op_sel_hi:[1,0,1] neg_lo:[0,0,1]
	ds_write_b64 v65, v[120:121] offset:2640
	s_waitcnt lgkmcnt(3)
	v_pk_mul_f32 v[186:187], v[122:123], v[182:183] op_sel:[1,1] op_sel_hi:[0,1]
	v_pk_fma_f32 v[122:123], v[122:123], v[182:183], v[186:187] op_sel_hi:[1,0,1] neg_lo:[0,0,1]
	ds_write_b64 v65, v[122:123] offset:2904
	s_waitcnt lgkmcnt(3)
	v_pk_mul_f32 v[184:185], v[124:125], v[180:181] op_sel:[1,1] op_sel_hi:[0,1]
	v_pk_fma_f32 v[124:125], v[124:125], v[180:181], v[184:185] op_sel_hi:[1,0,1] neg_lo:[0,0,1]
	ds_write_b64 v65, v[124:125] offset:3168
	ds_read_b64 v[178:179], v56 offset:3328
	ds_read_b64 v[176:177], v56 offset:3584
	ds_read_b64 v[166:167], v56 offset:3840
	s_waitcnt lgkmcnt(2)
	v_pk_mul_f32 v[188:189], v[126:127], v[178:179] op_sel:[1,1] op_sel_hi:[0,1]
	v_pk_fma_f32 v[126:127], v[126:127], v[178:179], v[188:189] op_sel_hi:[1,0,1] neg_lo:[0,0,1]
	ds_write_b64 v65, v[126:127] offset:3432
	s_waitcnt lgkmcnt(2)
	v_pk_mul_f32 v[186:187], v[128:129], v[176:177] op_sel:[1,1] op_sel_hi:[0,1]
	v_pk_fma_f32 v[128:129], v[128:129], v[176:177], v[186:187] op_sel_hi:[1,0,1] neg_lo:[0,0,1]
	ds_write_b64 v65, v[128:129] offset:3696
	s_waitcnt lgkmcnt(2)
	v_pk_mul_f32 v[184:185], v[130:131], v[166:167] op_sel:[1,1] op_sel_hi:[0,1]
	v_pk_fma_f32 v[130:131], v[130:131], v[166:167], v[184:185] op_sel_hi:[1,0,1] neg_lo:[0,0,1]
	ds_write_b64 v65, v[130:131] offset:3960
	s_waitcnt lgkmcnt(0)
	s_barrier
	v_mov_b32_e32 v174, s17
	v_mov_b32_e32 v175, s23
	v_mov_b32_e32 v168, s25
	v_mov_b32_e32 v169, s26
	ds_read_b32 v182, v208 offset:32768
	ds_read_b32 v180, v210 offset:32768
	ds_read_b32 v188, v208 offset:32772
	ds_read_b32 v183, v208 offset:49152
	ds_read_b32 v181, v210 offset:49152
	ds_read_b32 v189, v208 offset:49156
	ds_read_b32 v186, v208 offset:34816
	ds_read_b32 v184, v208 offset:34812
	ds_read_b32 v178, v208 offset:34820
	ds_read_b32 v187, v208 offset:51200
	ds_read_b32 v185, v208 offset:51196
	ds_read_b32 v179, v208 offset:51204
	s_waitcnt lgkmcnt(10)
	v_cndmask_b32_e64 v180, v180, 0, s[10:11]
	s_waitcnt lgkmcnt(7)
	v_cndmask_b32_e64 v181, v181, 0, s[10:11]
	v_pk_fma_f32 v[148:149], v[174:175], v[182:183], v[168:169] op_sel:[1,0,1]
	v_pk_fma_f32 v[148:149], v[174:175], v[180:181], v[148:149] op_sel_hi:[0,1,1]
	s_waitcnt lgkmcnt(6)
	v_pk_fma_f32 v[148:149], v[168:169], v[188:189], v[148:149] op_sel_hi:[0,1,1]
	s_waitcnt lgkmcnt(2)
	v_pk_fma_f32 v[150:151], v[174:175], v[186:187], v[168:169] op_sel:[1,0,1]
	s_waitcnt lgkmcnt(1)
	v_pk_fma_f32 v[150:151], v[174:175], v[184:185], v[150:151] op_sel_hi:[0,1,1]
	s_waitcnt lgkmcnt(0)
	v_pk_fma_f32 v[150:151], v[168:169], v[178:179], v[150:151] op_sel_hi:[0,1,1]
	ds_read_b32 v176, v208 offset:36864
	ds_read_b32 v166, v208 offset:36860
	ds_read_b32 v182, v208 offset:36868
	ds_read_b32 v177, v208 offset:53248
	ds_read_b32 v167, v208 offset:53244
	ds_read_b32 v183, v208 offset:53252
	ds_read_b32 v180, v208 offset:38912
	ds_read_b32 v188, v208 offset:38908
	ds_read_b32 v186, v208 offset:38916
	ds_read_b32 v181, v208 offset:55296
	ds_read_b32 v189, v208 offset:55292
	ds_read_b32 v187, v208 offset:55300
	s_waitcnt lgkmcnt(8)
	v_pk_fma_f32 v[152:153], v[174:175], v[176:177], v[168:169] op_sel:[1,0,1]
	s_waitcnt lgkmcnt(7)
	v_pk_fma_f32 v[152:153], v[174:175], v[166:167], v[152:153] op_sel_hi:[0,1,1]
	s_waitcnt lgkmcnt(6)
	v_pk_fma_f32 v[152:153], v[168:169], v[182:183], v[152:153] op_sel_hi:[0,1,1]
	s_waitcnt lgkmcnt(2)
	v_pk_fma_f32 v[154:155], v[174:175], v[180:181], v[168:169] op_sel:[1,0,1]
	s_waitcnt lgkmcnt(1)
	v_pk_fma_f32 v[154:155], v[174:175], v[188:189], v[154:155] op_sel_hi:[0,1,1]
	s_waitcnt lgkmcnt(0)
	v_pk_fma_f32 v[154:155], v[168:169], v[186:187], v[154:155] op_sel_hi:[0,1,1]
	ds_read_b32 v184, v208 offset:40960
	ds_read_b32 v178, v208 offset:40956
	ds_read_b32 v176, v208 offset:40964
	ds_read_b32 v185, v208 offset:57344
	ds_read_b32 v179, v208 offset:57340
	ds_read_b32 v177, v208 offset:57348
	ds_read_b32 v166, v208 offset:43008
	ds_read_b32 v182, v208 offset:43004
	ds_read_b32 v180, v208 offset:43012
	ds_read_b32 v167, v208 offset:59392
	ds_read_b32 v183, v208 offset:59388
	ds_read_b32 v181, v208 offset:59396
	s_waitcnt lgkmcnt(8)
	v_pk_fma_f32 v[158:159], v[174:175], v[184:185], v[168:169] op_sel:[1,0,1]
	s_waitcnt lgkmcnt(7)
	v_pk_fma_f32 v[158:159], v[174:175], v[178:179], v[158:159] op_sel_hi:[0,1,1]
	s_waitcnt lgkmcnt(6)
; #define LAS __attribute__((address_space(3)))
; __device__ __forceinline__ f32x2 cmul(f32x2 a, f32x2 b) { return (f32x2){a.x * b.x - a.y * b.y, a.x * b.y + a.y * b.x}; }
; template <int MODE> __device__ __forceinline__ void fft_pair32(LAS f32x2* B, const LAS f32x2* F, int wave, int lane) {
;     asm volatile("" : "+v"(lane));
;     constexpr float CS[16] = {1.f, 0.98078528040323043f, 0.92387953251128674f, 0.83146961230254524f, 0.70710678118654752f, 0.55557023301960218f, 0.38268343236508977f, 0.19509032201612825f,
;                               0.f, -0.19509032201612825f, -0.38268343236508977f, -0.55557023301960218f, -0.70710678118654752f, -0.83146961230254524f, -0.92387953251128674f, -0.98078528040323043f};
;     constexpr float SN[16] = {0.f, 0.19509032201612825f, 0.38268343236508977f, 0.55557023301960218f, 0.70710678118654752f, 0.83146961230254524f, 0.92387953251128674f, 0.98078528040323043f,
;                               1.f, 0.98078528040323043f, 0.92387953251128674f, 0.83146961230254524f, 0.70710678118654752f, 0.55557023301960218f, 0.38268343236508977f, 0.19509032201612825f};
;     const int hi = lane >> 5, blk = 32 * wave + (lane & 31); const float sg = hi ? -1.f : 1.f;
;     LAS f32x2* p = B + 33 * blk; f32x2 v[16];
; #pragma unroll
;     for (int j = 0; j < 16; ++j) { const f32x2 d = p[j] + p[j + 16] * sg;
;         const f32x2 w = {hi ? CS[j] : 1.f, hi ? -SN[j] : 0.f}; v[j] = j == 0 ? d : cmul(d, w); }
;     dft16<false>(v);
;     if (MODE == 2) {
; #pragma unroll
;         for (int k = 0; k < 16; ++k) p[2 * k + hi] = v[k];
;         return; }
	v_pk_fma_f32 v[158:159], v[168:169], v[176:177], v[158:159] op_sel_hi:[0,1,1]
	s_waitcnt lgkmcnt(2)
	v_pk_fma_f32 v[160:161], v[174:175], v[166:167], v[168:169] op_sel:[1,0,1]
	s_waitcnt lgkmcnt(1)
	v_pk_fma_f32 v[160:161], v[174:175], v[182:183], v[160:161] op_sel_hi:[0,1,1]
	s_waitcnt lgkmcnt(0)
	v_pk_fma_f32 v[160:161], v[168:169], v[180:181], v[160:161] op_sel_hi:[0,1,1]
	ds_read_b32 v188, v208 offset:45056
	ds_read_b32 v186, v208 offset:45052
	ds_read_b32 v184, v208 offset:45060
	ds_read_b32 v189, v208 offset:61440
	ds_read_b32 v187, v208 offset:61436
	ds_read_b32 v185, v208 offset:61444
	ds_read_b32 v178, v208 offset:47104
	ds_read_b32 v176, v208 offset:47100
	ds_read_b32 v166, v208 offset:47108
	ds_read_b32 v179, v208 offset:63488
	ds_read_b32 v177, v208 offset:63484
	ds_read_b32 v167, v208 offset:63492
	s_waitcnt lgkmcnt(8)
	v_pk_fma_f32 v[162:163], v[174:175], v[188:189], v[168:169] op_sel:[1,0,1]
	s_waitcnt lgkmcnt(7)
	v_pk_fma_f32 v[162:163], v[174:175], v[186:187], v[162:163] op_sel_hi:[0,1,1]
	s_waitcnt lgkmcnt(6)
	v_pk_fma_f32 v[162:163], v[168:169], v[184:185], v[162:163] op_sel_hi:[0,1,1]
	s_waitcnt lgkmcnt(3)
	v_cndmask_b32_e64 v166, v166, 0, s[28:29]
	s_waitcnt lgkmcnt(0)
	v_cndmask_b32_e64 v167, v167, 0, s[28:29]
	v_pk_fma_f32 v[164:165], v[174:175], v[178:179], v[168:169] op_sel:[1,0,1]
	v_pk_fma_f32 v[164:165], v[174:175], v[176:177], v[164:165] op_sel_hi:[0,1,1]
	v_pk_fma_f32 v[164:165], v[168:169], v[166:167], v[164:165] op_sel_hi:[0,1,1]
	s_load_dword s17, s[60:61], 0x1000
	s_load_dword s23, s[60:61], 0x4000
	s_load_dword s25, s[60:61], 0x7000
	s_load_dword s26, s[62:63], 0x1000
	v_add_u32_e32 v65, 0x10800, v156
	v_add_u32_e32 v69, 0x10800, v196
	ds_read_b64 v[100:101], v65
	ds_read_b64 v[182:183], v65 offset:128
	ds_read_b64 v[102:103], v65 offset:8
	ds_read_b64 v[180:181], v65 offset:136
	ds_read_b64 v[104:105], v65 offset:16
	ds_read_b64 v[188:189], v65 offset:144
	ds_read_b64 v[106:107], v65 offset:24
	ds_read_b64 v[186:187], v65 offset:152
	s_waitcnt lgkmcnt(0)
	v_pk_fma_f32 v[100:101], v[182:183], v[190:191], v[100:101] op_sel_hi:[1,0,1]
	v_pk_fma_f32 v[102:103], v[180:181], v[190:191], v[102:103] op_sel_hi:[1,0,1]
	v_pk_mul_f32 v[184:185], v[102:103], v[36:37] op_sel:[1,1] op_sel_hi:[0,1]
	v_pk_fma_f32 v[102:103], v[102:103], v[36:37], v[184:185] op_sel_hi:[1,0,1] neg_lo:[0,0,1]
	v_pk_fma_f32 v[104:105], v[188:189], v[190:191], v[104:105] op_sel_hi:[1,0,1]
	v_pk_mul_f32 v[178:179], v[104:105], v[38:39] op_sel:[1,1] op_sel_hi:[0,1]
	v_pk_fma_f32 v[104:105], v[104:105], v[38:39], v[178:179] op_sel_hi:[1,0,1] neg_lo:[0,0,1]
	v_pk_fma_f32 v[106:107], v[186:187], v[190:191], v[106:107] op_sel_hi:[1,0,1]
	v_pk_mul_f32 v[176:177], v[106:107], v[40:41] op_sel:[1,1] op_sel_hi:[0,1]
	v_pk_fma_f32 v[106:107], v[106:107], v[40:41], v[176:177] op_sel_hi:[1,0,1] neg_lo:[0,0,1]
	ds_read_b64 v[108:109], v65 offset:32
	ds_read_b64 v[166:167], v65 offset:160
	ds_read_b64 v[110:111], v65 offset:40
	ds_read_b64 v[174:175], v65 offset:168
	ds_read_b64 v[112:113], v65 offset:48
	ds_read_b64 v[168:169], v65 offset:176
	ds_read_b64 v[114:115], v65 offset:56
	ds_read_b64 v[184:185], v65 offset:184
	s_waitcnt lgkmcnt(6)
	v_pk_fma_f32 v[108:109], v[166:167], v[190:191], v[108:109] op_sel_hi:[1,0,1]
	v_pk_mul_f32 v[178:179], v[108:109], v[42:43] op_sel:[1,1] op_sel_hi:[0,1]
	v_pk_fma_f32 v[108:109], v[108:109], v[42:43], v[178:179] op_sel_hi:[1,0,1] neg_lo:[0,0,1]
	s_waitcnt lgkmcnt(4)
	v_pk_fma_f32 v[110:111], v[174:175], v[190:191], v[110:111] op_sel_hi:[1,0,1]
	v_pk_mul_f32 v[176:177], v[110:111], v[44:45] op_sel:[1,1] op_sel_hi:[0,1]
	v_pk_fma_f32 v[110:111], v[110:111], v[44:45], v[176:177] op_sel_hi:[1,0,1] neg_lo:[0,0,1]
	s_waitcnt lgkmcnt(2)
	v_pk_fma_f32 v[112:113], v[168:169], v[190:191], v[112:113] op_sel_hi:[1,0,1]
	v_pk_mul_f32 v[182:183], v[112:113], v[46:47] op_sel:[1,1] op_sel_hi:[0,1]
	v_pk_fma_f32 v[112:113], v[112:113], v[46:47], v[182:183] op_sel_hi:[1,0,1] neg_lo:[0,0,1]
	s_waitcnt lgkmcnt(0)
	v_pk_fma_f32 v[114:115], v[184:185], v[190:191], v[114:115] op_sel_hi:[1,0,1]
	v_pk_mul_f32 v[180:181], v[114:115], v[48:49] op_sel:[1,1] op_sel_hi:[0,1]
	v_pk_fma_f32 v[114:115], v[114:115], v[48:49], v[180:181] op_sel_hi:[1,0,1] neg_lo:[0,0,1]
	ds_read_b64 v[116:117], v65 offset:64
	ds_read_b64 v[188:189], v65 offset:192
	ds_read_b64 v[118:119], v65 offset:72
	ds_read_b64 v[186:187], v65 offset:200
	ds_read_b64 v[120:121], v65 offset:80
	ds_read_b64 v[178:179], v65 offset:208
	ds_read_b64 v[122:123], v65 offset:88
	ds_read_b64 v[176:177], v65 offset:216
	s_waitcnt lgkmcnt(6)
	v_pk_fma_f32 v[116:117], v[188:189], v[190:191], v[116:117] op_sel_hi:[1,0,1]
	v_pk_mul_f32 v[182:183], v[116:117], v[50:51] op_sel:[1,1] op_sel_hi:[0,1]
	v_pk_fma_f32 v[116:117], v[116:117], v[50:51], v[182:183] op_sel_hi:[1,0,1] neg_lo:[0,0,1]
	s_waitcnt lgkmcnt(4)
	v_pk_fma_f32 v[118:119], v[186:187], v[190:191], v[118:119] op_sel_hi:[1,0,1]
	v_pk_mul_f32 v[180:181], v[118:119], v[52:53] op_sel:[1,1] op_sel_hi:[0,1]
	v_pk_fma_f32 v[118:119], v[118:119], v[52:53], v[180:181] op_sel_hi:[1,0,1] neg_lo:[0,0,1]
	s_waitcnt lgkmcnt(2)
	v_pk_fma_f32 v[120:121], v[178:179], v[190:191], v[120:121] op_sel_hi:[1,0,1]
	v_pk_mul_f32 v[166:167], v[120:121], v[54:55] op_sel:[1,1] op_sel_hi:[0,1]
	v_pk_fma_f32 v[120:121], v[120:121], v[54:55], v[166:167] op_sel_hi:[1,0,1] neg_lo:[0,0,1]
	s_waitcnt lgkmcnt(0)
; #define LAS __attribute__((address_space(3)))
; template <bool INV> __device__ __forceinline__ void dft16(f32x2 (&x)[16]) {
;     constexpr float C1 = 0.92387953251128674f, S1 = 0.38268343236508977f, C2 = 0.70710678118654752f;
; #pragma unroll
;     for (int b = 0; b < 4; ++b) dft4<INV>(x[b], x[4 + b], x[8 + b], x[12 + b]);
;     const f32x2 w1 = {C1, -S1}, w2 = {C2, -C2}, w3 = {S1, -C1}, w4 = {0.f, -1.f}, w6 = {-C2, -C2}, w9 = {-C1, S1};
;     x[4 * 1 + 1] = cmul_tw<INV>(x[5], w1); x[4 * 1 + 2] = cmul_tw<INV>(x[6], w2); x[4 * 1 + 3] = cmul_tw<INV>(x[7], w3);
;     x[4 * 2 + 1] = cmul_tw<INV>(x[9], w2); x[4 * 2 + 2] = cmul_tw<INV>(x[10], w4); x[4 * 2 + 3] = cmul_tw<INV>(x[11], w6);
;     x[4 * 3 + 1] = cmul_tw<INV>(x[13], w3); x[4 * 3 + 2] = cmul_tw<INV>(x[14], w6); x[4 * 3 + 3] = cmul_tw<INV>(x[15], w9);
; #pragma unroll
;     for (int c = 0; c < 4; ++c) dft4<INV>(x[4 * c], x[4 * c + 1], x[4 * c + 2], x[4 * c + 3]);
;     f32x2 y[16];
; #pragma unroll
; template <int MODE> __device__ __forceinline__ void fft_pair32(LAS f32x2* B, const LAS f32x2* F, int wave, int lane) {
;     asm volatile("" : "+v"(lane));
;     constexpr float CS[16] = {1.f, 0.98078528040323043f, 0.92387953251128674f, 0.83146961230254524f, 0.70710678118654752f, 0.55557023301960218f, 0.38268343236508977f, 0.19509032201612825f,
;                               0.f, -0.19509032201612825f, -0.38268343236508977f, -0.55557023301960218f, -0.70710678118654752f, -0.83146961230254524f, -0.92387953251128674f, -0.98078528040323043f};
;     constexpr float SN[16] = {0.f, 0.19509032201612825f, 0.38268343236508977f, 0.55557023301960218f, 0.70710678118654752f, 0.83146961230254524f, 0.92387953251128674f, 0.98078528040323043f,
;                               1.f, 0.98078528040323043f, 0.92387953251128674f, 0.83146961230254524f, 0.70710678118654752f, 0.55557023301960218f, 0.38268343236508977f, 0.19509032201612825f};
;     const int hi = lane >> 5, blk = 32 * wave + (lane & 31); const float sg = hi ? -1.f : 1.f;
;     LAS f32x2* p = B + 33 * blk; f32x2 v[16];
; #pragma unroll
;     for (int j = 0; j < 16; ++j) { const f32x2 d = p[j] + p[j + 16] * sg;
;         const f32x2 w = {hi ? CS[j] : 1.f, hi ? -SN[j] : 0.f}; v[j] = j == 0 ? d : cmul(d, w); }
;     dft16<false>(v);
;     if (MODE == 2) {
; #pragma unroll
;         for (int k = 0; k < 16; ++k) p[2 * k + hi] = v[k];
;         return; }
	v_pk_fma_f32 v[122:123], v[176:177], v[190:191], v[122:123] op_sel_hi:[1,0,1]
	v_pk_mul_f32 v[174:175], v[122:123], v[90:91] op_sel:[1,1] op_sel_hi:[0,1]
	v_pk_fma_f32 v[122:123], v[122:123], v[90:91], v[174:175] op_sel_hi:[1,0,1] neg_lo:[0,0,1]
	ds_read_b64 v[124:125], v65 offset:96
	ds_read_b64 v[168:169], v65 offset:224
	ds_read_b64 v[126:127], v65 offset:104
	ds_read_b64 v[184:185], v65 offset:232
	ds_read_b64 v[128:129], v65 offset:112
	ds_read_b64 v[182:183], v65 offset:240
	ds_read_b64 v[130:131], v65 offset:120
	ds_read_b64 v[180:181], v65 offset:248
	s_waitcnt lgkmcnt(6)
	v_pk_fma_f32 v[124:125], v[168:169], v[190:191], v[124:125] op_sel_hi:[1,0,1]
	v_pk_mul_f32 v[166:167], v[124:125], v[92:93] op_sel:[1,1] op_sel_hi:[0,1]
	v_pk_fma_f32 v[124:125], v[124:125], v[92:93], v[166:167] op_sel_hi:[1,0,1] neg_lo:[0,0,1]
	s_waitcnt lgkmcnt(4)
	v_pk_fma_f32 v[126:127], v[184:185], v[190:191], v[126:127] op_sel_hi:[1,0,1]
	v_pk_mul_f32 v[174:175], v[126:127], v[94:95] op_sel:[1,1] op_sel_hi:[0,1]
	v_pk_fma_f32 v[126:127], v[126:127], v[94:95], v[174:175] op_sel_hi:[1,0,1] neg_lo:[0,0,1]
	s_waitcnt lgkmcnt(2)
	v_pk_fma_f32 v[128:129], v[182:183], v[190:191], v[128:129] op_sel_hi:[1,0,1]
	v_pk_mul_f32 v[188:189], v[128:129], v[96:97] op_sel:[1,1] op_sel_hi:[0,1]
	v_pk_fma_f32 v[128:129], v[128:129], v[96:97], v[188:189] op_sel_hi:[1,0,1] neg_lo:[0,0,1]
	s_waitcnt lgkmcnt(0)
	v_pk_fma_f32 v[130:131], v[180:181], v[190:191], v[130:131] op_sel_hi:[1,0,1]
	v_pk_mul_f32 v[186:187], v[130:131], v[98:99] op_sel:[1,1] op_sel_hi:[0,1]
	v_pk_fma_f32 v[130:131], v[130:131], v[98:99], v[186:187] op_sel_hi:[1,0,1] neg_lo:[0,0,1]
	v_pk_add_f32 v[178:179], v[100:101], v[116:117]
	v_pk_add_f32 v[176:177], v[100:101], v[116:117] neg_lo:[0,1] neg_hi:[0,1]
	v_pk_add_f32 v[166:167], v[108:109], v[124:125]
	v_pk_add_f32 v[174:175], v[108:109], v[124:125] neg_lo:[0,1] neg_hi:[0,1]
	v_pk_add_f32 v[100:101], v[178:179], v[166:167]
	v_pk_add_f32 v[116:117], v[178:179], v[166:167] neg_lo:[0,1] neg_hi:[0,1]
	v_pk_add_f32 v[108:109], v[176:177], v[174:175] op_sel:[0,1] op_sel_hi:[1,0] neg_hi:[0,1]
	v_pk_add_f32 v[124:125], v[176:177], v[174:175] op_sel:[0,1] op_sel_hi:[1,0] neg_lo:[0,1]
	v_pk_add_f32 v[188:189], v[102:103], v[118:119]
	v_pk_add_f32 v[186:187], v[102:103], v[118:119] neg_lo:[0,1] neg_hi:[0,1]
	v_pk_add_f32 v[168:169], v[110:111], v[126:127]
	v_pk_add_f32 v[184:185], v[110:111], v[126:127] neg_lo:[0,1] neg_hi:[0,1]
	v_pk_add_f32 v[102:103], v[188:189], v[168:169]
	v_pk_add_f32 v[118:119], v[188:189], v[168:169] neg_lo:[0,1] neg_hi:[0,1]
	v_pk_add_f32 v[110:111], v[186:187], v[184:185] op_sel:[0,1] op_sel_hi:[1,0] neg_hi:[0,1]
	v_pk_add_f32 v[126:127], v[186:187], v[184:185] op_sel:[0,1] op_sel_hi:[1,0] neg_lo:[0,1]
	v_pk_add_f32 v[182:183], v[104:105], v[120:121]
	v_pk_add_f32 v[180:181], v[104:105], v[120:121] neg_lo:[0,1] neg_hi:[0,1]
	v_pk_add_f32 v[178:179], v[112:113], v[128:129]
	v_pk_add_f32 v[176:177], v[112:113], v[128:129] neg_lo:[0,1] neg_hi:[0,1]
	v_pk_add_f32 v[104:105], v[182:183], v[178:179]
	v_pk_add_f32 v[120:121], v[182:183], v[178:179] neg_lo:[0,1] neg_hi:[0,1]
	v_pk_add_f32 v[112:113], v[180:181], v[176:177] op_sel:[0,1] op_sel_hi:[1,0] neg_hi:[0,1]
	v_pk_add_f32 v[128:129], v[180:181], v[176:177] op_sel:[0,1] op_sel_hi:[1,0] neg_lo:[0,1]
	v_pk_add_f32 v[166:167], v[106:107], v[122:123]
	v_pk_add_f32 v[174:175], v[106:107], v[122:123] neg_lo:[0,1] neg_hi:[0,1]
	v_pk_add_f32 v[188:189], v[114:115], v[130:131]
	v_pk_add_f32 v[186:187], v[114:115], v[130:131] neg_lo:[0,1] neg_hi:[0,1]
	v_pk_add_f32 v[106:107], v[166:167], v[188:189]
	v_pk_add_f32 v[122:123], v[166:167], v[188:189] neg_lo:[0,1] neg_hi:[0,1]
	v_pk_add_f32 v[114:115], v[174:175], v[186:187] op_sel:[0,1] op_sel_hi:[1,0] neg_hi:[0,1]
	v_pk_add_f32 v[130:131], v[174:175], v[186:187] op_sel:[0,1] op_sel_hi:[1,0] neg_lo:[0,1]
	v_pk_mul_f32 v[168:169], v[110:111], s[68:69] op_sel:[1,1] op_sel_hi:[0,1]
	v_pk_fma_f32 v[110:111], v[110:111], s[68:69], v[168:169] op_sel_hi:[1,0,1] neg_lo:[0,0,1]
	v_pk_mul_f32 v[184:185], v[112:113], s[84:85] op_sel:[1,1] op_sel_hi:[0,1]
	v_pk_fma_f32 v[112:113], v[112:113], s[84:85], v[184:185] op_sel_hi:[1,0,1] neg_lo:[0,0,1]
	v_pk_mul_f32 v[182:183], v[114:115], s[88:89] op_sel:[1,1] op_sel_hi:[0,1]
	v_pk_fma_f32 v[114:115], v[114:115], s[88:89], v[182:183] op_sel_hi:[1,0,1] neg_lo:[0,0,1]
	v_pk_mul_f32 v[180:181], v[118:119], s[84:85] op_sel:[1,1] op_sel_hi:[0,1]
	v_pk_fma_f32 v[118:119], v[118:119], s[84:85], v[180:181] op_sel_hi:[1,0,1] neg_lo:[0,0,1]
	v_pk_mul_f32 v[178:179], v[122:123], s[90:91] op_sel:[1,1] op_sel_hi:[0,1]
	v_pk_fma_f32 v[122:123], v[122:123], s[90:91], v[178:179] op_sel_hi:[1,0,1] neg_lo:[0,0,1]
	v_pk_mul_f32 v[176:177], v[126:127], s[88:89] op_sel:[1,1] op_sel_hi:[0,1]
	v_pk_fma_f32 v[126:127], v[126:127], s[88:89], v[176:177] op_sel_hi:[1,0,1] neg_lo:[0,0,1]
	v_pk_mul_f32 v[166:167], v[128:129], s[90:91] op_sel:[1,1] op_sel_hi:[0,1]
	v_pk_fma_f32 v[128:129], v[128:129], s[90:91], v[166:167] op_sel_hi:[1,0,1] neg_lo:[0,0,1]
	v_pk_mul_f32 v[174:175], v[130:131], s[98:99] op_sel:[1,1] op_sel_hi:[0,1]
	v_pk_fma_f32 v[130:131], v[130:131], s[98:99], v[174:175] op_sel_hi:[1,0,1] neg_lo:[0,0,1]
	v_pk_add_f32 v[188:189], v[100:101], v[104:105]
	v_pk_add_f32 v[186:187], v[100:101], v[104:105] neg_lo:[0,1] neg_hi:[0,1]
	v_pk_add_f32 v[168:169], v[102:103], v[106:107]
	v_pk_add_f32 v[184:185], v[102:103], v[106:107] neg_lo:[0,1] neg_hi:[0,1]
	v_pk_add_f32 v[100:101], v[188:189], v[168:169]
	v_pk_add_f32 v[104:105], v[188:189], v[168:169] neg_lo:[0,1] neg_hi:[0,1]
	v_pk_add_f32 v[102:103], v[186:187], v[184:185] op_sel:[0,1] op_sel_hi:[1,0] neg_hi:[0,1]
; __device__ __forceinline__ f32x2 cmul(f32x2 a, f32x2 b) { return (f32x2){a.x * b.x - a.y * b.y, a.x * b.y + a.y * b.x}; }
; __device__ __forceinline__ void dft16_fwd_lo(f32x2 (&x)[16]) {
;     constexpr float C1 = 0.92387953251128674f, S1 = 0.38268343236508977f, C2 = 0.70710678118654752f;
; #pragma unroll
;     for (int b = 0; b < 4; ++b) { const f32x2 x0 = x[b], x1 = x[4 + b]; const f32x2 j1 = {x1.y, -x1.x};
;         x[b] = x0 + x1; x[4 + b] = x0 + j1; x[8 + b] = x0 - x1; x[12 + b] = x0 - j1; }
;     const f32x2 w1 = {C1, -S1}, w2 = {C2, -C2}, w3 = {S1, -C1}, w4 = {0.f, -1.f}, w6 = {-C2, -C2}, w9 = {-C1, S1};
;     x[5] = cmul(x[5], w1); x[6] = cmul(x[6], w2); x[7] = cmul(x[7], w3);
;     x[9] = cmul(x[9], w2); x[10] = cmul(x[10], w4); x[11] = cmul(x[11], w6);
;     x[13] = cmul(x[13], w3); x[14] = cmul(x[14], w6); x[15] = cmul(x[15], w9);
; #pragma unroll
;     for (int c = 0; c < 4; ++c) dft4<false>(x[4 * c], x[4 * c + 1], x[4 * c + 2], x[4 * c + 3]);
;     f32x2 y[16];
; #pragma unroll
;     for (int k = 0; k < 16; ++k) y[k] = x[4 * (k & 3) + (k >> 2)];
; #pragma unroll
;     for (int k = 0; k < 16; ++k) x[k] = y[k];
; }
; template <int MODE> __device__ __forceinline__ void fft_pair32(LAS f32x2* B, const LAS f32x2* F, int wave, int lane) {
;     ...
;     for (int j = 0; j < 16; ++j) { const f32x2 d = p[j] + p[j + 16] * sg;
;         const f32x2 w = {hi ? CS[j] : 1.f, hi ? -SN[j] : 0.f}; v[j] = j == 0 ? d : cmul(d, w); }
;     dft16<false>(v);
;     if (MODE == 2) {
; #pragma unroll
;         for (int k = 0; k < 16; ++k) p[2 * k + hi] = v[k];
;         return; }
	v_pk_add_f32 v[106:107], v[186:187], v[184:185] op_sel:[0,1] op_sel_hi:[1,0] neg_lo:[0,1]
	v_pk_add_f32 v[182:183], v[108:109], v[112:113]
	v_pk_add_f32 v[180:181], v[108:109], v[112:113] neg_lo:[0,1] neg_hi:[0,1]
	v_pk_add_f32 v[178:179], v[110:111], v[114:115]
	v_pk_add_f32 v[176:177], v[110:111], v[114:115] neg_lo:[0,1] neg_hi:[0,1]
	v_pk_add_f32 v[108:109], v[182:183], v[178:179]
	v_pk_add_f32 v[112:113], v[182:183], v[178:179] neg_lo:[0,1] neg_hi:[0,1]
	v_pk_add_f32 v[110:111], v[180:181], v[176:177] op_sel:[0,1] op_sel_hi:[1,0] neg_hi:[0,1]
	v_pk_add_f32 v[114:115], v[180:181], v[176:177] op_sel:[0,1] op_sel_hi:[1,0] neg_lo:[0,1]
	v_pk_add_f32 v[166:167], v[116:117], v[120:121] op_sel:[0,1] op_sel_hi:[1,0] neg_hi:[0,1]
	v_pk_add_f32 v[174:175], v[116:117], v[120:121] op_sel:[0,1] op_sel_hi:[1,0] neg_lo:[0,1]
	v_pk_add_f32 v[188:189], v[118:119], v[122:123]
	v_pk_add_f32 v[186:187], v[118:119], v[122:123] neg_lo:[0,1] neg_hi:[0,1]
	v_pk_add_f32 v[116:117], v[166:167], v[188:189]
	v_pk_add_f32 v[120:121], v[166:167], v[188:189] neg_lo:[0,1] neg_hi:[0,1]
	v_pk_add_f32 v[118:119], v[174:175], v[186:187] op_sel:[0,1] op_sel_hi:[1,0] neg_hi:[0,1]
	v_pk_add_f32 v[122:123], v[174:175], v[186:187] op_sel:[0,1] op_sel_hi:[1,0] neg_lo:[0,1]
	v_pk_add_f32 v[168:169], v[124:125], v[128:129]
	v_pk_add_f32 v[184:185], v[124:125], v[128:129] neg_lo:[0,1] neg_hi:[0,1]
	v_pk_add_f32 v[182:183], v[126:127], v[130:131]
	v_pk_add_f32 v[180:181], v[126:127], v[130:131] neg_lo:[0,1] neg_hi:[0,1]
	v_pk_add_f32 v[124:125], v[168:169], v[182:183]
	v_pk_add_f32 v[128:129], v[168:169], v[182:183] neg_lo:[0,1] neg_hi:[0,1]
	v_pk_add_f32 v[126:127], v[184:185], v[180:181] op_sel:[0,1] op_sel_hi:[1,0] neg_hi:[0,1]
	v_pk_add_f32 v[130:131], v[184:185], v[180:181] op_sel:[0,1] op_sel_hi:[1,0] neg_lo:[0,1]
	v_pk_mul_f32 v[100:101], v[100:101], v[192:193] op_sel_hi:[1,0]
	ds_write_b64 v69, v[100:101]
	v_pk_mul_f32 v[108:109], v[108:109], v[192:193] op_sel_hi:[1,0]
	ds_write_b64 v69, v[108:109] offset:16
	v_pk_mul_f32 v[116:117], v[116:117], v[192:193] op_sel_hi:[1,0]
	ds_write_b64 v69, v[116:117] offset:32
	v_pk_mul_f32 v[124:125], v[124:125], v[192:193] op_sel_hi:[1,0]
	ds_write_b64 v69, v[124:125] offset:48
	v_pk_mul_f32 v[102:103], v[102:103], v[192:193] op_sel_hi:[1,0]
	ds_write_b64 v69, v[102:103] offset:64
	v_pk_mul_f32 v[110:111], v[110:111], v[192:193] op_sel_hi:[1,0]
	ds_write_b64 v69, v[110:111] offset:80
	v_pk_mul_f32 v[118:119], v[118:119], v[192:193] op_sel_hi:[1,0]
	ds_write_b64 v69, v[118:119] offset:96
	v_pk_mul_f32 v[126:127], v[126:127], v[192:193] op_sel_hi:[1,0]
	ds_write_b64 v69, v[126:127] offset:112
	v_pk_mul_f32 v[104:105], v[104:105], v[192:193] op_sel_hi:[1,0]
	ds_write_b64 v69, v[104:105] offset:128
	v_pk_mul_f32 v[112:113], v[112:113], v[192:193] op_sel_hi:[1,0]
	ds_write_b64 v69, v[112:113] offset:144
	v_pk_mul_f32 v[120:121], v[120:121], v[192:193] op_sel_hi:[1,0]
	ds_write_b64 v69, v[120:121] offset:160
	v_pk_mul_f32 v[128:129], v[128:129], v[192:193] op_sel_hi:[1,0]
	ds_write_b64 v69, v[128:129] offset:176
	v_pk_mul_f32 v[106:107], v[106:107], v[192:193] op_sel_hi:[1,0]
	ds_write_b64 v69, v[106:107] offset:192
	v_pk_mul_f32 v[114:115], v[114:115], v[192:193] op_sel_hi:[1,0]
	ds_write_b64 v69, v[114:115] offset:208
	v_pk_mul_f32 v[122:123], v[122:123], v[192:193] op_sel_hi:[1,0]
	ds_write_b64 v69, v[122:123] offset:224
	v_pk_mul_f32 v[130:131], v[130:131], v[192:193] op_sel_hi:[1,0]
	ds_write_b64 v69, v[130:131] offset:240
	s_waitcnt lgkmcnt(0)
	s_barrier
	v_pk_add_f32 v[104:105], v[132:133], v[140:141] neg_lo:[0,1] neg_hi:[0,1]
	v_pk_add_f32 v[106:107], v[132:133], v[140:141] op_sel:[0,1] op_sel_hi:[1,0] neg_lo:[0,1]
	v_pk_add_f32 v[178:179], v[132:133], v[140:141] op_sel:[0,1] op_sel_hi:[1,0] neg_hi:[0,1]
	v_pk_add_f32 v[100:101], v[132:133], v[140:141]
	v_pk_add_f32 v[112:113], v[134:135], v[142:143] neg_lo:[0,1] neg_hi:[0,1]
	v_pk_add_f32 v[114:115], v[134:135], v[142:143] op_sel:[0,1] op_sel_hi:[1,0] neg_lo:[0,1]
	v_pk_add_f32 v[176:177], v[134:135], v[142:143] op_sel:[0,1] op_sel_hi:[1,0] neg_hi:[0,1]
	v_pk_add_f32 v[108:109], v[134:135], v[142:143]
	v_pk_add_f32 v[120:121], v[136:137], v[144:145] neg_lo:[0,1] neg_hi:[0,1]
	v_pk_add_f32 v[122:123], v[136:137], v[144:145] op_sel:[0,1] op_sel_hi:[1,0] neg_lo:[0,1]
	v_pk_add_f32 v[166:167], v[136:137], v[144:145] op_sel:[0,1] op_sel_hi:[1,0] neg_hi:[0,1]
	v_pk_add_f32 v[116:117], v[136:137], v[144:145]
	v_pk_add_f32 v[128:129], v[138:139], v[146:147] neg_lo:[0,1] neg_hi:[0,1]
	v_pk_add_f32 v[130:131], v[138:139], v[146:147] op_sel:[0,1] op_sel_hi:[1,0] neg_lo:[0,1]
	v_pk_add_f32 v[174:175], v[138:139], v[146:147] op_sel:[0,1] op_sel_hi:[1,0] neg_hi:[0,1]
	v_pk_add_f32 v[124:125], v[138:139], v[146:147]
	v_pk_mul_f32 v[188:189], v[176:177], s[68:69] op_sel:[1,1] op_sel_hi:[0,1]
	v_pk_fma_f32 v[176:177], v[176:177], s[68:69], v[188:189] op_sel_hi:[1,0,1] neg_lo:[0,0,1]
	v_pk_mul_f32 v[186:187], v[166:167], s[84:85] op_sel:[1,1] op_sel_hi:[0,1]
	v_pk_fma_f32 v[166:167], v[166:167], s[84:85], v[186:187] op_sel_hi:[1,0,1] neg_lo:[0,0,1]
	v_pk_mul_f32 v[168:169], v[174:175], s[88:89] op_sel:[1,1] op_sel_hi:[0,1]
	v_pk_fma_f32 v[174:175], v[174:175], s[88:89], v[168:169] op_sel_hi:[1,0,1] neg_lo:[0,0,1]
	v_pk_mul_f32 v[184:185], v[112:113], s[84:85] op_sel:[1,1] op_sel_hi:[0,1]
	v_pk_fma_f32 v[112:113], v[112:113], s[84:85], v[184:185] op_sel_hi:[1,0,1] neg_lo:[0,0,1]
	v_pk_mul_f32 v[182:183], v[128:129], s[90:91] op_sel:[1,1] op_sel_hi:[0,1]
	v_pk_fma_f32 v[128:129], v[128:129], s[90:91], v[182:183] op_sel_hi:[1,0,1] neg_lo:[0,0,1]
	v_pk_mul_f32 v[180:181], v[114:115], s[88:89] op_sel:[1,1] op_sel_hi:[0,1]
; #define LAS __attribute__((address_space(3)))
; __device__ __forceinline__ f32x2 cmul(f32x2 a, f32x2 b) { return (f32x2){a.x * b.x - a.y * b.y, a.x * b.y + a.y * b.x}; }
; __device__ __forceinline__ void dft16_fwd_lo(f32x2 (&x)[16]) {
;     constexpr float C1 = 0.92387953251128674f, S1 = 0.38268343236508977f, C2 = 0.70710678118654752f;
; #pragma unroll
;     for (int b = 0; b < 4; ++b) { const f32x2 x0 = x[b], x1 = x[4 + b]; const f32x2 j1 = {x1.y, -x1.x};
;         x[b] = x0 + x1; x[4 + b] = x0 + j1; x[8 + b] = x0 - x1; x[12 + b] = x0 - j1; }
;     const f32x2 w1 = {C1, -S1}, w2 = {C2, -C2}, w3 = {S1, -C1}, w4 = {0.f, -1.f}, w6 = {-C2, -C2}, w9 = {-C1, S1};
;     x[5] = cmul(x[5], w1); x[6] = cmul(x[6], w2); x[7] = cmul(x[7], w3);
;     x[9] = cmul(x[9], w2); x[10] = cmul(x[10], w4); x[11] = cmul(x[11], w6);
;     x[13] = cmul(x[13], w3); x[14] = cmul(x[14], w6); x[15] = cmul(x[15], w9);
; #pragma unroll
;     for (int c = 0; c < 4; ++c) dft4<false>(x[4 * c], x[4 * c + 1], x[4 * c + 2], x[4 * c + 3]);
;     f32x2 y[16];
; #pragma unroll
;     for (int k = 0; k < 16; ++k) y[k] = x[4 * (k & 3) + (k >> 2)];
; #pragma unroll
;     for (int k = 0; k < 16; ++k) x[k] = y[k];
; }
; template <bool LO> __device__ __forceinline__ void fft_fwd1(f32x2 (&x)[16], LAS f32x2* B, int n2, const f32x2 (&w)[16]) {
;     asm volatile("" : "+v"(n2));
;     if (LO) dft16_fwd_lo(x); else dft16<false>(x);
;     B[fpad(n2)] = x[0];
; #pragma unroll
;     for (int k = 1; k < 16; ++k) B[fpad(512 * k + n2)] = cmul(x[k], w[k]);
; }
	v_pk_fma_f32 v[114:115], v[114:115], s[88:89], v[180:181] op_sel_hi:[1,0,1] neg_lo:[0,0,1]
	v_pk_mul_f32 v[102:103], v[122:123], s[90:91] op_sel:[1,1] op_sel_hi:[0,1]
	v_pk_fma_f32 v[122:123], v[122:123], s[90:91], v[102:103] op_sel_hi:[1,0,1] neg_lo:[0,0,1]
	v_pk_mul_f32 v[110:111], v[130:131], s[98:99] op_sel:[1,1] op_sel_hi:[0,1]
	v_pk_fma_f32 v[130:131], v[130:131], s[98:99], v[110:111] op_sel_hi:[1,0,1] neg_lo:[0,0,1]
	v_pk_add_f32 v[118:119], v[100:101], v[116:117]
	v_pk_add_f32 v[126:127], v[100:101], v[116:117] neg_lo:[0,1] neg_hi:[0,1]
	v_pk_add_f32 v[188:189], v[108:109], v[124:125]
	v_pk_add_f32 v[186:187], v[108:109], v[124:125] neg_lo:[0,1] neg_hi:[0,1]
	v_pk_add_f32 v[100:101], v[118:119], v[188:189]
	v_pk_add_f32 v[116:117], v[118:119], v[188:189] neg_lo:[0,1] neg_hi:[0,1]
	v_pk_add_f32 v[108:109], v[126:127], v[186:187] op_sel:[0,1] op_sel_hi:[1,0] neg_hi:[0,1]
	v_pk_add_f32 v[124:125], v[126:127], v[186:187] op_sel:[0,1] op_sel_hi:[1,0] neg_lo:[0,1]
	v_pk_add_f32 v[168:169], v[178:179], v[166:167]
	v_pk_add_f32 v[184:185], v[178:179], v[166:167] neg_lo:[0,1] neg_hi:[0,1]
	v_pk_add_f32 v[182:183], v[176:177], v[174:175]
	v_pk_add_f32 v[180:181], v[176:177], v[174:175] neg_lo:[0,1] neg_hi:[0,1]
	v_pk_add_f32 v[178:179], v[168:169], v[182:183]
	v_pk_add_f32 v[166:167], v[168:169], v[182:183] neg_lo:[0,1] neg_hi:[0,1]
	v_pk_add_f32 v[176:177], v[184:185], v[180:181] op_sel:[0,1] op_sel_hi:[1,0] neg_hi:[0,1]
	v_pk_add_f32 v[174:175], v[184:185], v[180:181] op_sel:[0,1] op_sel_hi:[1,0] neg_lo:[0,1]
	v_pk_add_f32 v[102:103], v[104:105], v[120:121] op_sel:[0,1] op_sel_hi:[1,0] neg_hi:[0,1]
	v_pk_add_f32 v[110:111], v[104:105], v[120:121] op_sel:[0,1] op_sel_hi:[1,0] neg_lo:[0,1]
	v_pk_add_f32 v[118:119], v[112:113], v[128:129]
	v_pk_add_f32 v[126:127], v[112:113], v[128:129] neg_lo:[0,1] neg_hi:[0,1]
	v_pk_add_f32 v[104:105], v[102:103], v[118:119]
	v_pk_add_f32 v[120:121], v[102:103], v[118:119] neg_lo:[0,1] neg_hi:[0,1]
	v_pk_add_f32 v[112:113], v[110:111], v[126:127] op_sel:[0,1] op_sel_hi:[1,0] neg_hi:[0,1]
	v_pk_add_f32 v[128:129], v[110:111], v[126:127] op_sel:[0,1] op_sel_hi:[1,0] neg_lo:[0,1]
	v_pk_add_f32 v[188:189], v[106:107], v[122:123]
	v_pk_add_f32 v[186:187], v[106:107], v[122:123] neg_lo:[0,1] neg_hi:[0,1]
	v_pk_add_f32 v[168:169], v[114:115], v[130:131]
	v_pk_add_f32 v[184:185], v[114:115], v[130:131] neg_lo:[0,1] neg_hi:[0,1]
	v_pk_add_f32 v[106:107], v[188:189], v[168:169]
	v_pk_add_f32 v[122:123], v[188:189], v[168:169] neg_lo:[0,1] neg_hi:[0,1]
	v_pk_add_f32 v[114:115], v[186:187], v[184:185] op_sel:[0,1] op_sel_hi:[1,0] neg_hi:[0,1]
	v_pk_add_f32 v[130:131], v[186:187], v[184:185] op_sel:[0,1] op_sel_hi:[1,0] neg_lo:[0,1]
	ds_write_b64 v3, v[100:101]
	v_pk_mul_f32 v[180:181], v[178:179], v[6:7] op_sel:[1,1] op_sel_hi:[0,1]
	v_pk_fma_f32 v[182:183], v[178:179], v[6:7], v[180:181] op_sel_hi:[1,0,1] neg_lo:[0,0,1]
	ds_write_b64 v3, v[182:183] offset:4224
	v_pk_mul_f32 v[110:111], v[104:105], v[8:9] op_sel:[1,1] op_sel_hi:[0,1]
	v_pk_fma_f32 v[102:103], v[104:105], v[8:9], v[110:111] op_sel_hi:[1,0,1] neg_lo:[0,0,1]
	ds_write_b64 v3, v[102:103] offset:8448
	v_pk_mul_f32 v[126:127], v[106:107], v[10:11] op_sel:[1,1] op_sel_hi:[0,1]
	v_pk_fma_f32 v[118:119], v[106:107], v[10:11], v[126:127] op_sel_hi:[1,0,1] neg_lo:[0,0,1]
	ds_write_b64 v3, v[118:119] offset:12672
	v_pk_mul_f32 v[186:187], v[108:109], v[12:13] op_sel:[1,1] op_sel_hi:[0,1]
	v_pk_fma_f32 v[188:189], v[108:109], v[12:13], v[186:187] op_sel_hi:[1,0,1] neg_lo:[0,0,1]
	ds_write_b64 v3, v[188:189] offset:16896
	v_pk_mul_f32 v[184:185], v[176:177], v[14:15] op_sel:[1,1] op_sel_hi:[0,1]
	v_pk_fma_f32 v[168:169], v[176:177], v[14:15], v[184:185] op_sel_hi:[1,0,1] neg_lo:[0,0,1]
	ds_write_b64 v3, v[168:169] offset:21120
	v_pk_mul_f32 v[182:183], v[112:113], v[16:17] op_sel:[1,1] op_sel_hi:[0,1]
	v_pk_fma_f32 v[180:181], v[112:113], v[16:17], v[182:183] op_sel_hi:[1,0,1] neg_lo:[0,0,1]
	ds_write_b64 v3, v[180:181] offset:25344
	v_pk_mul_f32 v[102:103], v[114:115], v[18:19] op_sel:[1,1] op_sel_hi:[0,1]
	v_pk_fma_f32 v[110:111], v[114:115], v[18:19], v[102:103] op_sel_hi:[1,0,1] neg_lo:[0,0,1]
	ds_write_b64 v3, v[110:111] offset:29568
	v_pk_mul_f32 v[118:119], v[116:117], v[20:21] op_sel:[1,1] op_sel_hi:[0,1]
	v_pk_fma_f32 v[126:127], v[116:117], v[20:21], v[118:119] op_sel_hi:[1,0,1] neg_lo:[0,0,1]
	ds_write_b64 v3, v[126:127] offset:33792
	v_pk_mul_f32 v[188:189], v[166:167], v[22:23] op_sel:[1,1] op_sel_hi:[0,1]
	v_pk_fma_f32 v[186:187], v[166:167], v[22:23], v[188:189] op_sel_hi:[1,0,1] neg_lo:[0,0,1]
	ds_write_b64 v3, v[186:187] offset:38016
	v_pk_mul_f32 v[168:169], v[120:121], v[24:25] op_sel:[1,1] op_sel_hi:[0,1]
	v_pk_fma_f32 v[184:185], v[120:121], v[24:25], v[168:169] op_sel_hi:[1,0,1] neg_lo:[0,0,1]
	ds_write_b64 v3, v[184:185] offset:42240
	v_pk_mul_f32 v[180:181], v[122:123], v[26:27] op_sel:[1,1] op_sel_hi:[0,1]
	v_pk_fma_f32 v[182:183], v[122:123], v[26:27], v[180:181] op_sel_hi:[1,0,1] neg_lo:[0,0,1]
	ds_write_b64 v3, v[182:183] offset:46464
	v_pk_mul_f32 v[110:111], v[124:125], v[28:29] op_sel:[1,1] op_sel_hi:[0,1]
	v_pk_fma_f32 v[102:103], v[124:125], v[28:29], v[110:111] op_sel_hi:[1,0,1] neg_lo:[0,0,1]
	ds_write_b64 v3, v[102:103] offset:50688
	v_pk_mul_f32 v[126:127], v[174:175], v[30:31] op_sel:[1,1] op_sel_hi:[0,1]
	v_pk_fma_f32 v[118:119], v[174:175], v[30:31], v[126:127] op_sel_hi:[1,0,1] neg_lo:[0,0,1]
	ds_write_b64 v3, v[118:119] offset:54912
	v_pk_mul_f32 v[186:187], v[128:129], v[32:33] op_sel:[1,1] op_sel_hi:[0,1]
	v_pk_fma_f32 v[188:189], v[128:129], v[32:33], v[186:187] op_sel_hi:[1,0,1] neg_lo:[0,0,1]
	ds_write_b64 v3, v[188:189] offset:59136
	v_pk_mul_f32 v[184:185], v[130:131], v[34:35] op_sel:[1,1] op_sel_hi:[0,1]
	v_pk_fma_f32 v[168:169], v[130:131], v[34:35], v[184:185] op_sel_hi:[1,0,1] neg_lo:[0,0,1]
	ds_write_b64 v3, v[168:169] offset:63360
	s_waitcnt lgkmcnt(0)
	s_barrier
; #define LAS __attribute__((address_space(3)))
; __device__ __forceinline__ f32x2 cmul(f32x2 a, f32x2 b) { return (f32x2){a.x * b.x - a.y * b.y, a.x * b.y + a.y * b.x}; }
; template <bool INV> __device__ __forceinline__ f32x2 cmul_tw(f32x2 a, f32x2 w) { return INV ? cmulc(a, w) : cmul(a, w); }
; template <bool INV> __device__ __forceinline__ void dft16(f32x2 (&x)[16]) {
;     constexpr float C1 = 0.92387953251128674f, S1 = 0.38268343236508977f, C2 = 0.70710678118654752f;
; #pragma unroll
;     for (int b = 0; b < 4; ++b) dft4<INV>(x[b], x[4 + b], x[8 + b], x[12 + b]);
;     const f32x2 w1 = {C1, -S1}, w2 = {C2, -C2}, w3 = {S1, -C1}, w4 = {0.f, -1.f}, w6 = {-C2, -C2}, w9 = {-C1, S1};
;     x[4 * 1 + 1] = cmul_tw<INV>(x[5], w1); x[4 * 1 + 2] = cmul_tw<INV>(x[6], w2); x[4 * 1 + 3] = cmul_tw<INV>(x[7], w3);
;     x[4 * 2 + 1] = cmul_tw<INV>(x[9], w2); x[4 * 2 + 2] = cmul_tw<INV>(x[10], w4); x[4 * 2 + 3] = cmul_tw<INV>(x[11], w6);
;     x[4 * 3 + 1] = cmul_tw<INV>(x[13], w3); x[4 * 3 + 2] = cmul_tw<INV>(x[14], w6); x[4 * 3 + 3] = cmul_tw<INV>(x[15], w9);
; #pragma unroll
;     for (int c = 0; c < 4; ++c) dft4<INV>(x[4 * c], x[4 * c + 1], x[4 * c + 2], x[4 * c + 3]);
;     f32x2 y[16];
; #pragma unroll
;     for (int k = 0; k < 16; ++k) y[k] = x[4 * (k & 3) + (k >> 2)];
; #pragma unroll
;     for (int k = 0; k < 16; ++k) x[k] = y[k];
; }
; __device__ __forceinline__ void fft_fwd2(LAS f32x2* B, const LAS f32x2* TW2, int tid) {
;     asm volatile("" : "+v"(tid));
;     const int b = tid >> 5, n2 = tid & 31, base = 512 * b + n2; f32x2 x[16];
; #pragma unroll
;     for (int r = 0; r < 16; ++r) x[r] = B[fpad(base + 32 * r)];
;     dft16<false>(x);
;     B[fpad(base)] = x[0];
; #pragma unroll
;     for (int k = 1; k < 16; ++k) B[fpad(base + 32 * k)] = cmul(x[k], TW2[k * 32 + n2]);
; }
	ds_read_b64 v[100:101], v5
	ds_read_b64 v[108:109], v5 offset:1056
	ds_read_b64 v[116:117], v5 offset:2112
	ds_read_b64 v[124:125], v5 offset:3168
	ds_read_b64 v[178:179], v5 offset:264
	ds_read_b64 v[176:177], v5 offset:1320
	ds_read_b64 v[166:167], v5 offset:2376
	ds_read_b64 v[174:175], v5 offset:3432
	ds_read_b64 v[104:105], v5 offset:528
	ds_read_b64 v[112:113], v5 offset:1584
	ds_read_b64 v[120:121], v5 offset:2640
	ds_read_b64 v[128:129], v5 offset:3696
	s_waitcnt lgkmcnt(8)
	ds_read_b64 v[106:107], v5 offset:792
	ds_read_b64 v[114:115], v5 offset:1848
	ds_read_b64 v[122:123], v5 offset:2904
	ds_read_b64 v[130:131], v5 offset:3960
	v_pk_add_f32 v[180:181], v[100:101], v[116:117]
	v_pk_add_f32 v[182:183], v[100:101], v[116:117] neg_lo:[0,1] neg_hi:[0,1]
	v_pk_add_f32 v[110:111], v[108:109], v[124:125]
	v_pk_add_f32 v[102:103], v[108:109], v[124:125] neg_lo:[0,1] neg_hi:[0,1]
	v_pk_add_f32 v[100:101], v[180:181], v[110:111]
	v_pk_add_f32 v[116:117], v[180:181], v[110:111] neg_lo:[0,1] neg_hi:[0,1]
	v_pk_add_f32 v[108:109], v[182:183], v[102:103] op_sel:[0,1] op_sel_hi:[1,0] neg_hi:[0,1]
	v_pk_add_f32 v[124:125], v[182:183], v[102:103] op_sel:[0,1] op_sel_hi:[1,0] neg_lo:[0,1]
	s_waitcnt lgkmcnt(9)
	v_pk_add_f32 v[126:127], v[178:179], v[166:167]
	v_pk_add_f32 v[118:119], v[178:179], v[166:167] neg_lo:[0,1] neg_hi:[0,1]
	s_waitcnt lgkmcnt(8)
	v_pk_add_f32 v[186:187], v[176:177], v[174:175]
	v_pk_add_f32 v[188:189], v[176:177], v[174:175] neg_lo:[0,1] neg_hi:[0,1]
	v_pk_add_f32 v[178:179], v[126:127], v[186:187]
	v_pk_add_f32 v[166:167], v[126:127], v[186:187] neg_lo:[0,1] neg_hi:[0,1]
	v_pk_add_f32 v[176:177], v[118:119], v[188:189] op_sel:[0,1] op_sel_hi:[1,0] neg_hi:[0,1]
	v_pk_add_f32 v[174:175], v[118:119], v[188:189] op_sel:[0,1] op_sel_hi:[1,0] neg_lo:[0,1]
	s_waitcnt lgkmcnt(5)
	v_pk_add_f32 v[184:185], v[104:105], v[120:121]
	v_pk_add_f32 v[168:169], v[104:105], v[120:121] neg_lo:[0,1] neg_hi:[0,1]
	s_waitcnt lgkmcnt(4)
	v_pk_add_f32 v[180:181], v[112:113], v[128:129]
	v_pk_add_f32 v[182:183], v[112:113], v[128:129] neg_lo:[0,1] neg_hi:[0,1]
	v_pk_add_f32 v[104:105], v[184:185], v[180:181]
	v_pk_add_f32 v[120:121], v[184:185], v[180:181] neg_lo:[0,1] neg_hi:[0,1]
	v_pk_add_f32 v[112:113], v[168:169], v[182:183] op_sel:[0,1] op_sel_hi:[1,0] neg_hi:[0,1]
	v_pk_add_f32 v[128:129], v[168:169], v[182:183] op_sel:[0,1] op_sel_hi:[1,0] neg_lo:[0,1]
	s_waitcnt lgkmcnt(1)
	v_pk_add_f32 v[110:111], v[106:107], v[122:123]
	v_pk_add_f32 v[102:103], v[106:107], v[122:123] neg_lo:[0,1] neg_hi:[0,1]
	s_waitcnt lgkmcnt(0)
	v_pk_add_f32 v[126:127], v[114:115], v[130:131]
	v_pk_add_f32 v[118:119], v[114:115], v[130:131] neg_lo:[0,1] neg_hi:[0,1]
	v_pk_add_f32 v[106:107], v[110:111], v[126:127]
	v_pk_add_f32 v[122:123], v[110:111], v[126:127] neg_lo:[0,1] neg_hi:[0,1]
	v_pk_add_f32 v[114:115], v[102:103], v[118:119] op_sel:[0,1] op_sel_hi:[1,0] neg_hi:[0,1]
	v_pk_add_f32 v[130:131], v[102:103], v[118:119] op_sel:[0,1] op_sel_hi:[1,0] neg_lo:[0,1]
	v_pk_mul_f32 v[186:187], v[176:177], s[68:69] op_sel:[1,1] op_sel_hi:[0,1]
	v_pk_fma_f32 v[176:177], v[176:177], s[68:69], v[186:187] op_sel_hi:[1,0,1] neg_lo:[0,0,1]
	v_pk_mul_f32 v[188:189], v[112:113], s[84:85] op_sel:[1,1] op_sel_hi:[0,1]
	v_pk_fma_f32 v[112:113], v[112:113], s[84:85], v[188:189] op_sel_hi:[1,0,1] neg_lo:[0,0,1]
	v_pk_mul_f32 v[184:185], v[114:115], s[88:89] op_sel:[1,1] op_sel_hi:[0,1]
	v_pk_fma_f32 v[114:115], v[114:115], s[88:89], v[184:185] op_sel_hi:[1,0,1] neg_lo:[0,0,1]
	v_pk_mul_f32 v[168:169], v[166:167], s[84:85] op_sel:[1,1] op_sel_hi:[0,1]
	v_pk_fma_f32 v[166:167], v[166:167], s[84:85], v[168:169] op_sel_hi:[1,0,1] neg_lo:[0,0,1]
	v_pk_mul_f32 v[180:181], v[122:123], s[90:91] op_sel:[1,1] op_sel_hi:[0,1]
	v_pk_fma_f32 v[122:123], v[122:123], s[90:91], v[180:181] op_sel_hi:[1,0,1] neg_lo:[0,0,1]
	v_pk_mul_f32 v[182:183], v[174:175], s[88:89] op_sel:[1,1] op_sel_hi:[0,1]
	v_pk_fma_f32 v[174:175], v[174:175], s[88:89], v[182:183] op_sel_hi:[1,0,1] neg_lo:[0,0,1]
	v_pk_mul_f32 v[110:111], v[128:129], s[90:91] op_sel:[1,1] op_sel_hi:[0,1]
	v_pk_fma_f32 v[128:129], v[128:129], s[90:91], v[110:111] op_sel_hi:[1,0,1] neg_lo:[0,0,1]
	v_pk_mul_f32 v[102:103], v[130:131], s[98:99] op_sel:[1,1] op_sel_hi:[0,1]
	v_pk_fma_f32 v[130:131], v[130:131], s[98:99], v[102:103] op_sel_hi:[1,0,1] neg_lo:[0,0,1]
	v_pk_add_f32 v[126:127], v[100:101], v[104:105]
	v_pk_add_f32 v[118:119], v[100:101], v[104:105] neg_lo:[0,1] neg_hi:[0,1]
	v_pk_add_f32 v[186:187], v[178:179], v[106:107]
	v_pk_add_f32 v[188:189], v[178:179], v[106:107] neg_lo:[0,1] neg_hi:[0,1]
	v_pk_add_f32 v[100:101], v[126:127], v[186:187]
	v_pk_add_f32 v[104:105], v[126:127], v[186:187] neg_lo:[0,1] neg_hi:[0,1]
	v_pk_add_f32 v[178:179], v[118:119], v[188:189] op_sel:[0,1] op_sel_hi:[1,0] neg_hi:[0,1]
	v_pk_add_f32 v[106:107], v[118:119], v[188:189] op_sel:[0,1] op_sel_hi:[1,0] neg_lo:[0,1]
	v_pk_add_f32 v[184:185], v[108:109], v[112:113]
	v_pk_add_f32 v[168:169], v[108:109], v[112:113] neg_lo:[0,1] neg_hi:[0,1]
	v_pk_add_f32 v[180:181], v[176:177], v[114:115]
	v_pk_add_f32 v[182:183], v[176:177], v[114:115] neg_lo:[0,1] neg_hi:[0,1]
	v_pk_add_f32 v[108:109], v[184:185], v[180:181]
	v_pk_add_f32 v[112:113], v[184:185], v[180:181] neg_lo:[0,1] neg_hi:[0,1]
	v_pk_add_f32 v[176:177], v[168:169], v[182:183] op_sel:[0,1] op_sel_hi:[1,0] neg_hi:[0,1]
	v_pk_add_f32 v[114:115], v[168:169], v[182:183] op_sel:[0,1] op_sel_hi:[1,0] neg_lo:[0,1]
	v_pk_add_f32 v[110:111], v[116:117], v[120:121] op_sel:[0,1] op_sel_hi:[1,0] neg_hi:[0,1]
	v_pk_add_f32 v[102:103], v[116:117], v[120:121] op_sel:[0,1] op_sel_hi:[1,0] neg_lo:[0,1]
	v_pk_add_f32 v[126:127], v[166:167], v[122:123]
	v_pk_add_f32 v[118:119], v[166:167], v[122:123] neg_lo:[0,1] neg_hi:[0,1]
	v_pk_add_f32 v[116:117], v[110:111], v[126:127]
	v_pk_add_f32 v[120:121], v[110:111], v[126:127] neg_lo:[0,1] neg_hi:[0,1]
	v_pk_add_f32 v[166:167], v[102:103], v[118:119] op_sel:[0,1] op_sel_hi:[1,0] neg_hi:[0,1]
	v_pk_add_f32 v[122:123], v[102:103], v[118:119] op_sel:[0,1] op_sel_hi:[1,0] neg_lo:[0,1]
	v_pk_add_f32 v[186:187], v[124:125], v[128:129]
	v_pk_add_f32 v[188:189], v[124:125], v[128:129] neg_lo:[0,1] neg_hi:[0,1]
	v_pk_add_f32 v[184:185], v[174:175], v[130:131]
	v_pk_add_f32 v[168:169], v[174:175], v[130:131] neg_lo:[0,1] neg_hi:[0,1]
	v_pk_add_f32 v[124:125], v[186:187], v[184:185]
	v_pk_add_f32 v[128:129], v[186:187], v[184:185] neg_lo:[0,1] neg_hi:[0,1]
	v_pk_add_f32 v[174:175], v[188:189], v[168:169] op_sel:[0,1] op_sel_hi:[1,0] neg_hi:[0,1]
	v_pk_add_f32 v[130:131], v[188:189], v[168:169] op_sel:[0,1] op_sel_hi:[1,0] neg_lo:[0,1]
	ds_write_b64 v5, v[100:101]
	ds_read_b64 v[180:181], v56 offset:256
	ds_read_b64 v[182:183], v56 offset:512
	ds_read_b64 v[110:111], v56 offset:768
	ds_read_b64 v[102:103], v56 offset:1024
	s_waitcnt lgkmcnt(3)
; #define LAS __attribute__((address_space(3)))
; __device__ __forceinline__ f32x2 cmul(f32x2 a, f32x2 b) { return (f32x2){a.x * b.x - a.y * b.y, a.x * b.y + a.y * b.x}; }
; __device__ __forceinline__ void fft_fwd2(LAS f32x2* B, const LAS f32x2* TW2, int tid) {
;     asm volatile("" : "+v"(tid));
;     const int b = tid >> 5, n2 = tid & 31, base = 512 * b + n2; f32x2 x[16];
; #pragma unroll
;     for (int r = 0; r < 16; ++r) x[r] = B[fpad(base + 32 * r)];
;     dft16<false>(x);
;     B[fpad(base)] = x[0];
; #pragma unroll
;     for (int k = 1; k < 16; ++k) B[fpad(base + 32 * k)] = cmul(x[k], TW2[k * 32 + n2]);
; }
; template <int MODE> __device__ __forceinline__ void fft_pair32(LAS f32x2* B, const LAS f32x2* F, int wave, int lane) {
;     asm volatile("" : "+v"(lane));
;     constexpr float CS[16] = {1.f, 0.98078528040323043f, 0.92387953251128674f, 0.83146961230254524f, 0.70710678118654752f, 0.55557023301960218f, 0.38268343236508977f, 0.19509032201612825f,
;                               0.f, -0.19509032201612825f, -0.38268343236508977f, -0.55557023301960218f, -0.70710678118654752f, -0.83146961230254524f, -0.92387953251128674f, -0.98078528040323043f};
;     constexpr float SN[16] = {0.f, 0.19509032201612825f, 0.38268343236508977f, 0.55557023301960218f, 0.70710678118654752f, 0.83146961230254524f, 0.92387953251128674f, 0.98078528040323043f,
;                               1.f, 0.98078528040323043f, 0.92387953251128674f, 0.83146961230254524f, 0.70710678118654752f, 0.55557023301960218f, 0.38268343236508977f, 0.19509032201612825f};
;     const int hi = lane >> 5, blk = 32 * wave + (lane & 31); const float sg = hi ? -1.f : 1.f;
;     LAS f32x2* p = B + 33 * blk; f32x2 v[16];
; #pragma unroll
;     for (int j = 0; j < 16; ++j) { const f32x2 d = p[j] + p[j + 16] * sg;
;         const f32x2 w = {hi ? CS[j] : 1.f, hi ? -SN[j] : 0.f}; v[j] = j == 0 ? d : cmul(d, w); }
;     dft16<false>(v);
	v_pk_mul_f32 v[126:127], v[108:109], v[180:181] op_sel:[1,1] op_sel_hi:[0,1]
	v_pk_fma_f32 v[108:109], v[108:109], v[180:181], v[126:127] op_sel_hi:[1,0,1] neg_lo:[0,0,1]
	ds_write_b64 v5, v[108:109] offset:264
	s_waitcnt lgkmcnt(3)
	v_pk_mul_f32 v[118:119], v[116:117], v[182:183] op_sel:[1,1] op_sel_hi:[0,1]
	v_pk_fma_f32 v[116:117], v[116:117], v[182:183], v[118:119] op_sel_hi:[1,0,1] neg_lo:[0,0,1]
	ds_write_b64 v5, v[116:117] offset:528
	s_waitcnt lgkmcnt(3)
	v_pk_mul_f32 v[186:187], v[124:125], v[110:111] op_sel:[1,1] op_sel_hi:[0,1]
	v_pk_fma_f32 v[124:125], v[124:125], v[110:111], v[186:187] op_sel_hi:[1,0,1] neg_lo:[0,0,1]
	ds_write_b64 v5, v[124:125] offset:792
	s_waitcnt lgkmcnt(3)
	v_pk_mul_f32 v[188:189], v[178:179], v[102:103] op_sel:[1,1] op_sel_hi:[0,1]
	v_pk_fma_f32 v[178:179], v[178:179], v[102:103], v[188:189] op_sel_hi:[1,0,1] neg_lo:[0,0,1]
	ds_write_b64 v5, v[178:179] offset:1056
	ds_read_b64 v[184:185], v56 offset:1280
	ds_read_b64 v[168:169], v56 offset:1536
	ds_read_b64 v[126:127], v56 offset:1792
	ds_read_b64 v[118:119], v56 offset:2048
	s_waitcnt lgkmcnt(3)
	v_pk_mul_f32 v[186:187], v[176:177], v[184:185] op_sel:[1,1] op_sel_hi:[0,1]
	v_pk_fma_f32 v[176:177], v[176:177], v[184:185], v[186:187] op_sel_hi:[1,0,1] neg_lo:[0,0,1]
	ds_write_b64 v5, v[176:177] offset:1320
	s_waitcnt lgkmcnt(3)
	v_pk_mul_f32 v[188:189], v[166:167], v[168:169] op_sel:[1,1] op_sel_hi:[0,1]
	v_pk_fma_f32 v[166:167], v[166:167], v[168:169], v[188:189] op_sel_hi:[1,0,1] neg_lo:[0,0,1]
	ds_write_b64 v5, v[166:167] offset:1584
	s_waitcnt lgkmcnt(3)
	v_pk_mul_f32 v[180:181], v[174:175], v[126:127] op_sel:[1,1] op_sel_hi:[0,1]
	v_pk_fma_f32 v[174:175], v[174:175], v[126:127], v[180:181] op_sel_hi:[1,0,1] neg_lo:[0,0,1]
	ds_write_b64 v5, v[174:175] offset:1848
	s_waitcnt lgkmcnt(3)
	v_pk_mul_f32 v[182:183], v[104:105], v[118:119] op_sel:[1,1] op_sel_hi:[0,1]
	v_pk_fma_f32 v[104:105], v[104:105], v[118:119], v[182:183] op_sel_hi:[1,0,1] neg_lo:[0,0,1]
	ds_write_b64 v5, v[104:105] offset:2112
	ds_read_b64 v[110:111], v56 offset:2304
	ds_read_b64 v[102:103], v56 offset:2560
	ds_read_b64 v[186:187], v56 offset:2816
	ds_read_b64 v[188:189], v56 offset:3072
	s_waitcnt lgkmcnt(3)
	v_pk_mul_f32 v[180:181], v[112:113], v[110:111] op_sel:[1,1] op_sel_hi:[0,1]
	v_pk_fma_f32 v[112:113], v[112:113], v[110:111], v[180:181] op_sel_hi:[1,0,1] neg_lo:[0,0,1]
	ds_write_b64 v5, v[112:113] offset:2376
	s_waitcnt lgkmcnt(3)
	v_pk_mul_f32 v[182:183], v[120:121], v[102:103] op_sel:[1,1] op_sel_hi:[0,1]
	v_pk_fma_f32 v[120:121], v[120:121], v[102:103], v[182:183] op_sel_hi:[1,0,1] neg_lo:[0,0,1]
	ds_write_b64 v5, v[120:121] offset:2640
	s_waitcnt lgkmcnt(3)
	v_pk_mul_f32 v[184:185], v[128:129], v[186:187] op_sel:[1,1] op_sel_hi:[0,1]
	v_pk_fma_f32 v[128:129], v[128:129], v[186:187], v[184:185] op_sel_hi:[1,0,1] neg_lo:[0,0,1]
	ds_write_b64 v5, v[128:129] offset:2904
	s_waitcnt lgkmcnt(3)
	v_pk_mul_f32 v[168:169], v[106:107], v[188:189] op_sel:[1,1] op_sel_hi:[0,1]
	v_pk_fma_f32 v[106:107], v[106:107], v[188:189], v[168:169] op_sel_hi:[1,0,1] neg_lo:[0,0,1]
	ds_write_b64 v5, v[106:107] offset:3168
	ds_read_b64 v[126:127], v56 offset:3328
	ds_read_b64 v[118:119], v56 offset:3584
	ds_read_b64 v[180:181], v56 offset:3840
	s_waitcnt lgkmcnt(2)
	v_pk_mul_f32 v[182:183], v[114:115], v[126:127] op_sel:[1,1] op_sel_hi:[0,1]
	v_pk_fma_f32 v[114:115], v[114:115], v[126:127], v[182:183] op_sel_hi:[1,0,1] neg_lo:[0,0,1]
	ds_write_b64 v5, v[114:115] offset:3432
	s_waitcnt lgkmcnt(2)
	v_pk_mul_f32 v[184:185], v[122:123], v[118:119] op_sel:[1,1] op_sel_hi:[0,1]
	v_pk_fma_f32 v[122:123], v[122:123], v[118:119], v[184:185] op_sel_hi:[1,0,1] neg_lo:[0,0,1]
	ds_write_b64 v5, v[122:123] offset:3696
	s_waitcnt lgkmcnt(2)
	v_pk_mul_f32 v[168:169], v[130:131], v[180:181] op_sel:[1,1] op_sel_hi:[0,1]
	v_pk_fma_f32 v[130:131], v[130:131], v[180:181], v[168:169] op_sel_hi:[1,0,1] neg_lo:[0,0,1]
	ds_write_b64 v5, v[130:131] offset:3960
	s_waitcnt lgkmcnt(0)
	ds_read_b64 v[100:101], v156
	ds_read_b64 v[110:111], v156 offset:128
	ds_read_b64 v[108:109], v156 offset:8
	ds_read_b64 v[102:103], v156 offset:136
	ds_read_b64 v[116:117], v156 offset:16
	ds_read_b64 v[186:187], v156 offset:144
	ds_read_b64 v[124:125], v156 offset:24
	ds_read_b64 v[188:189], v156 offset:152
	s_waitcnt lgkmcnt(6)
	v_pk_fma_f32 v[100:101], v[110:111], v[190:191], v[100:101] op_sel_hi:[1,0,1]
	s_waitcnt lgkmcnt(4)
	v_pk_fma_f32 v[108:109], v[102:103], v[190:191], v[108:109] op_sel_hi:[1,0,1]
	v_pk_mul_f32 v[182:183], v[108:109], v[36:37] op_sel:[1,1] op_sel_hi:[0,1]
	v_pk_fma_f32 v[108:109], v[108:109], v[36:37], v[182:183] op_sel_hi:[1,0,1] neg_lo:[0,0,1]
	s_waitcnt lgkmcnt(2)
	v_pk_fma_f32 v[116:117], v[186:187], v[190:191], v[116:117] op_sel_hi:[1,0,1]
	v_pk_mul_f32 v[184:185], v[116:117], v[38:39] op_sel:[1,1] op_sel_hi:[0,1]
	v_pk_fma_f32 v[116:117], v[116:117], v[38:39], v[184:185] op_sel_hi:[1,0,1] neg_lo:[0,0,1]
	s_waitcnt lgkmcnt(0)
	v_pk_fma_f32 v[124:125], v[188:189], v[190:191], v[124:125] op_sel_hi:[1,0,1]
	v_pk_mul_f32 v[168:169], v[124:125], v[40:41] op_sel:[1,1] op_sel_hi:[0,1]
	v_pk_fma_f32 v[124:125], v[124:125], v[40:41], v[168:169] op_sel_hi:[1,0,1] neg_lo:[0,0,1]
	ds_read_b64 v[178:179], v156 offset:32
	ds_read_b64 v[126:127], v156 offset:160
	ds_read_b64 v[176:177], v156 offset:40
	ds_read_b64 v[118:119], v156 offset:168
	ds_read_b64 v[166:167], v156 offset:48
	ds_read_b64 v[180:181], v156 offset:176
	ds_read_b64 v[174:175], v156 offset:56
	ds_read_b64 v[182:183], v156 offset:184
	s_waitcnt lgkmcnt(6)
; #define LAS __attribute__((address_space(3)))
; template <bool INV> __device__ __forceinline__ void dft16(f32x2 (&x)[16]) {
;     constexpr float C1 = 0.92387953251128674f, S1 = 0.38268343236508977f, C2 = 0.70710678118654752f;
; #pragma unroll
;     for (int b = 0; b < 4; ++b) dft4<INV>(x[b], x[4 + b], x[8 + b], x[12 + b]);
;     const f32x2 w1 = {C1, -S1}, w2 = {C2, -C2}, w3 = {S1, -C1}, w4 = {0.f, -1.f}, w6 = {-C2, -C2}, w9 = {-C1, S1};
;     x[4 * 1 + 1] = cmul_tw<INV>(x[5], w1); x[4 * 1 + 2] = cmul_tw<INV>(x[6], w2); x[4 * 1 + 3] = cmul_tw<INV>(x[7], w3);
;     x[4 * 2 + 1] = cmul_tw<INV>(x[9], w2); x[4 * 2 + 2] = cmul_tw<INV>(x[10], w4); x[4 * 2 + 3] = cmul_tw<INV>(x[11], w6);
;     x[4 * 3 + 1] = cmul_tw<INV>(x[13], w3); x[4 * 3 + 2] = cmul_tw<INV>(x[14], w6); x[4 * 3 + 3] = cmul_tw<INV>(x[15], w9);
; #pragma unroll
;     for (int c = 0; c < 4; ++c) dft4<INV>(x[4 * c], x[4 * c + 1], x[4 * c + 2], x[4 * c + 3]);
;     f32x2 y[16];
; #pragma unroll
;     for (int k = 0; k < 16; ++k) y[k] = x[4 * (k & 3) + (k >> 2)];
; #pragma unroll
;     for (int k = 0; k < 16; ++k) x[k] = y[k];
; }
; template <int MODE> __device__ __forceinline__ void fft_pair32(LAS f32x2* B, const LAS f32x2* F, int wave, int lane) {
;     asm volatile("" : "+v"(lane));
;     constexpr float CS[16] = {1.f, 0.98078528040323043f, 0.92387953251128674f, 0.83146961230254524f, 0.70710678118654752f, 0.55557023301960218f, 0.38268343236508977f, 0.19509032201612825f,
;                               0.f, -0.19509032201612825f, -0.38268343236508977f, -0.55557023301960218f, -0.70710678118654752f, -0.83146961230254524f, -0.92387953251128674f, -0.98078528040323043f};
;     constexpr float SN[16] = {0.f, 0.19509032201612825f, 0.38268343236508977f, 0.55557023301960218f, 0.70710678118654752f, 0.83146961230254524f, 0.92387953251128674f, 0.98078528040323043f,
;                               1.f, 0.98078528040323043f, 0.92387953251128674f, 0.83146961230254524f, 0.70710678118654752f, 0.55557023301960218f, 0.38268343236508977f, 0.19509032201612825f};
;     const int hi = lane >> 5, blk = 32 * wave + (lane & 31); const float sg = hi ? -1.f : 1.f;
;     LAS f32x2* p = B + 33 * blk; f32x2 v[16];
; #pragma unroll
;     for (int j = 0; j < 16; ++j) { const f32x2 d = p[j] + p[j + 16] * sg;
;         const f32x2 w = {hi ? CS[j] : 1.f, hi ? -SN[j] : 0.f}; v[j] = j == 0 ? d : cmul(d, w); }
;     dft16<false>(v);
	v_pk_fma_f32 v[178:179], v[126:127], v[190:191], v[178:179] op_sel_hi:[1,0,1]
	v_pk_mul_f32 v[184:185], v[178:179], v[42:43] op_sel:[1,1] op_sel_hi:[0,1]
	v_pk_fma_f32 v[178:179], v[178:179], v[42:43], v[184:185] op_sel_hi:[1,0,1] neg_lo:[0,0,1]
	s_waitcnt lgkmcnt(4)
	v_pk_fma_f32 v[176:177], v[118:119], v[190:191], v[176:177] op_sel_hi:[1,0,1]
	v_pk_mul_f32 v[168:169], v[176:177], v[44:45] op_sel:[1,1] op_sel_hi:[0,1]
	v_pk_fma_f32 v[176:177], v[176:177], v[44:45], v[168:169] op_sel_hi:[1,0,1] neg_lo:[0,0,1]
	s_waitcnt lgkmcnt(2)
	v_pk_fma_f32 v[166:167], v[180:181], v[190:191], v[166:167] op_sel_hi:[1,0,1]
	v_pk_mul_f32 v[110:111], v[166:167], v[46:47] op_sel:[1,1] op_sel_hi:[0,1]
	v_pk_fma_f32 v[166:167], v[166:167], v[46:47], v[110:111] op_sel_hi:[1,0,1] neg_lo:[0,0,1]
	s_waitcnt lgkmcnt(0)
	v_pk_fma_f32 v[174:175], v[182:183], v[190:191], v[174:175] op_sel_hi:[1,0,1]
	v_pk_mul_f32 v[102:103], v[174:175], v[48:49] op_sel:[1,1] op_sel_hi:[0,1]
	v_pk_fma_f32 v[174:175], v[174:175], v[48:49], v[102:103] op_sel_hi:[1,0,1] neg_lo:[0,0,1]
	ds_read_b64 v[104:105], v156 offset:64
	ds_read_b64 v[186:187], v156 offset:192
	ds_read_b64 v[112:113], v156 offset:72
	ds_read_b64 v[188:189], v156 offset:200
	ds_read_b64 v[120:121], v156 offset:80
	ds_read_b64 v[184:185], v156 offset:208
	ds_read_b64 v[128:129], v156 offset:88
	ds_read_b64 v[168:169], v156 offset:216
	s_waitcnt lgkmcnt(6)
	v_pk_fma_f32 v[104:105], v[186:187], v[190:191], v[104:105] op_sel_hi:[1,0,1]
	v_pk_mul_f32 v[110:111], v[104:105], v[50:51] op_sel:[1,1] op_sel_hi:[0,1]
	v_pk_fma_f32 v[104:105], v[104:105], v[50:51], v[110:111] op_sel_hi:[1,0,1] neg_lo:[0,0,1]
	s_waitcnt lgkmcnt(4)
	v_pk_fma_f32 v[112:113], v[188:189], v[190:191], v[112:113] op_sel_hi:[1,0,1]
	v_pk_mul_f32 v[102:103], v[112:113], v[52:53] op_sel:[1,1] op_sel_hi:[0,1]
	v_pk_fma_f32 v[112:113], v[112:113], v[52:53], v[102:103] op_sel_hi:[1,0,1] neg_lo:[0,0,1]
	s_waitcnt lgkmcnt(2)
	v_pk_fma_f32 v[120:121], v[184:185], v[190:191], v[120:121] op_sel_hi:[1,0,1]
	v_pk_mul_f32 v[126:127], v[120:121], v[54:55] op_sel:[1,1] op_sel_hi:[0,1]
	v_pk_fma_f32 v[120:121], v[120:121], v[54:55], v[126:127] op_sel_hi:[1,0,1] neg_lo:[0,0,1]
	s_waitcnt lgkmcnt(0)
	v_pk_fma_f32 v[128:129], v[168:169], v[190:191], v[128:129] op_sel_hi:[1,0,1]
	v_pk_mul_f32 v[118:119], v[128:129], v[90:91] op_sel:[1,1] op_sel_hi:[0,1]
	v_pk_fma_f32 v[128:129], v[128:129], v[90:91], v[118:119] op_sel_hi:[1,0,1] neg_lo:[0,0,1]
	ds_read_b64 v[106:107], v156 offset:96
	ds_read_b64 v[180:181], v156 offset:224
	ds_read_b64 v[114:115], v156 offset:104
	ds_read_b64 v[182:183], v156 offset:232
	ds_read_b64 v[122:123], v156 offset:112
	ds_read_b64 v[110:111], v156 offset:240
	ds_read_b64 v[130:131], v156 offset:120
	ds_read_b64 v[102:103], v156 offset:248
	s_waitcnt lgkmcnt(6)
	v_pk_fma_f32 v[106:107], v[180:181], v[190:191], v[106:107] op_sel_hi:[1,0,1]
	v_pk_mul_f32 v[126:127], v[106:107], v[92:93] op_sel:[1,1] op_sel_hi:[0,1]
	v_pk_fma_f32 v[106:107], v[106:107], v[92:93], v[126:127] op_sel_hi:[1,0,1] neg_lo:[0,0,1]
	s_waitcnt lgkmcnt(4)
	v_pk_fma_f32 v[114:115], v[182:183], v[190:191], v[114:115] op_sel_hi:[1,0,1]
	v_pk_mul_f32 v[118:119], v[114:115], v[94:95] op_sel:[1,1] op_sel_hi:[0,1]
	v_pk_fma_f32 v[114:115], v[114:115], v[94:95], v[118:119] op_sel_hi:[1,0,1] neg_lo:[0,0,1]
	s_waitcnt lgkmcnt(2)
	v_pk_fma_f32 v[122:123], v[110:111], v[190:191], v[122:123] op_sel_hi:[1,0,1]
	v_pk_mul_f32 v[186:187], v[122:123], v[96:97] op_sel:[1,1] op_sel_hi:[0,1]
	v_pk_fma_f32 v[122:123], v[122:123], v[96:97], v[186:187] op_sel_hi:[1,0,1] neg_lo:[0,0,1]
	s_waitcnt lgkmcnt(0)
	v_pk_fma_f32 v[130:131], v[102:103], v[190:191], v[130:131] op_sel_hi:[1,0,1]
	v_pk_mul_f32 v[188:189], v[130:131], v[98:99] op_sel:[1,1] op_sel_hi:[0,1]
	v_pk_fma_f32 v[130:131], v[130:131], v[98:99], v[188:189] op_sel_hi:[1,0,1] neg_lo:[0,0,1]
	v_pk_add_f32 v[184:185], v[100:101], v[104:105]
	v_pk_add_f32 v[168:169], v[100:101], v[104:105] neg_lo:[0,1] neg_hi:[0,1]
	v_pk_add_f32 v[126:127], v[178:179], v[106:107]
	v_pk_add_f32 v[118:119], v[178:179], v[106:107] neg_lo:[0,1] neg_hi:[0,1]
	v_pk_add_f32 v[100:101], v[184:185], v[126:127]
	v_pk_add_f32 v[104:105], v[184:185], v[126:127] neg_lo:[0,1] neg_hi:[0,1]
	v_pk_add_f32 v[178:179], v[168:169], v[118:119] op_sel:[0,1] op_sel_hi:[1,0] neg_hi:[0,1]
	v_pk_add_f32 v[106:107], v[168:169], v[118:119] op_sel:[0,1] op_sel_hi:[1,0] neg_lo:[0,1]
	v_pk_add_f32 v[186:187], v[108:109], v[112:113]
	v_pk_add_f32 v[188:189], v[108:109], v[112:113] neg_lo:[0,1] neg_hi:[0,1]
	v_pk_add_f32 v[180:181], v[176:177], v[114:115]
	v_pk_add_f32 v[182:183], v[176:177], v[114:115] neg_lo:[0,1] neg_hi:[0,1]
	v_pk_add_f32 v[108:109], v[186:187], v[180:181]
	v_pk_add_f32 v[112:113], v[186:187], v[180:181] neg_lo:[0,1] neg_hi:[0,1]
	v_pk_add_f32 v[176:177], v[188:189], v[182:183] op_sel:[0,1] op_sel_hi:[1,0] neg_hi:[0,1]
	v_pk_add_f32 v[114:115], v[188:189], v[182:183] op_sel:[0,1] op_sel_hi:[1,0] neg_lo:[0,1]
	v_pk_add_f32 v[110:111], v[116:117], v[120:121]
	v_pk_add_f32 v[102:103], v[116:117], v[120:121] neg_lo:[0,1] neg_hi:[0,1]
	v_pk_add_f32 v[184:185], v[166:167], v[122:123]
	v_pk_add_f32 v[168:169], v[166:167], v[122:123] neg_lo:[0,1] neg_hi:[0,1]
	v_pk_add_f32 v[116:117], v[110:111], v[184:185]
	v_pk_add_f32 v[120:121], v[110:111], v[184:185] neg_lo:[0,1] neg_hi:[0,1]
	v_pk_add_f32 v[166:167], v[102:103], v[168:169] op_sel:[0,1] op_sel_hi:[1,0] neg_hi:[0,1]
	v_pk_add_f32 v[122:123], v[102:103], v[168:169] op_sel:[0,1] op_sel_hi:[1,0] neg_lo:[0,1]
	v_pk_add_f32 v[126:127], v[124:125], v[128:129]
	v_pk_add_f32 v[118:119], v[124:125], v[128:129] neg_lo:[0,1] neg_hi:[0,1]
; #define LAS __attribute__((address_space(3)))
; __device__ __forceinline__ f32x2 cmul(f32x2 a, f32x2 b) { return (f32x2){a.x * b.x - a.y * b.y, a.x * b.y + a.y * b.x}; }
; template <int MODE> __device__ __forceinline__ void fft_pair32(LAS f32x2* B, const LAS f32x2* F, int wave, int lane) {
;     ...
;     const int k1 = blk >> 4, k2 = blk & 15, kb1 = (16 - k1) & 15, b1 = k1 != 0 ? 1 : 0, kb2 = (16 - k2 - b1) & 15, b2 = (k2 != 0 || b1) ? 1 : 0;
;     const LAS f32x2* fa = F + 33 * blk; const LAS f32x2* fb = F + 33 * (16 * kb1 + kb2);
;     const LAS f32x2* fah = fa + hi; const LAS f32x2* fbh = fb + (1 - b2) - hi;
;     constexpr float SC = 1.0f / (2.0f * (float)FN);
; #pragma unroll
;     for (int k = 0; k < 16; ++k) { const f32x2 A = fah[2 * k]; f32x2 Bm = fbh[31 - 2 * k];
;         if (k == 0) { const f32x2 m0 = b2 ? fb[31] : fa[0]; Bm = hi ? Bm : m0; }
;         const f32x2 H = MODE == 0 ? (f32x2){(A.x + Bm.x) * SC, (A.y - Bm.y) * SC} : (f32x2){(A.y + Bm.y) * SC, (Bm.x - A.x) * SC};
;         v[k] = cmul(v[k], H); }
	v_pk_add_f32 v[186:187], v[174:175], v[130:131]
	v_pk_add_f32 v[188:189], v[174:175], v[130:131] neg_lo:[0,1] neg_hi:[0,1]
	v_pk_add_f32 v[124:125], v[126:127], v[186:187]
	v_pk_add_f32 v[128:129], v[126:127], v[186:187] neg_lo:[0,1] neg_hi:[0,1]
	v_pk_add_f32 v[174:175], v[118:119], v[188:189] op_sel:[0,1] op_sel_hi:[1,0] neg_hi:[0,1]
	v_pk_add_f32 v[130:131], v[118:119], v[188:189] op_sel:[0,1] op_sel_hi:[1,0] neg_lo:[0,1]
	v_pk_mul_f32 v[180:181], v[176:177], s[68:69] op_sel:[1,1] op_sel_hi:[0,1]
	v_pk_fma_f32 v[176:177], v[176:177], s[68:69], v[180:181] op_sel_hi:[1,0,1] neg_lo:[0,0,1]
	v_pk_mul_f32 v[182:183], v[166:167], s[84:85] op_sel:[1,1] op_sel_hi:[0,1]
	v_pk_fma_f32 v[166:167], v[166:167], s[84:85], v[182:183] op_sel_hi:[1,0,1] neg_lo:[0,0,1]
	v_pk_mul_f32 v[110:111], v[174:175], s[88:89] op_sel:[1,1] op_sel_hi:[0,1]
	v_pk_fma_f32 v[174:175], v[174:175], s[88:89], v[110:111] op_sel_hi:[1,0,1] neg_lo:[0,0,1]
	v_pk_mul_f32 v[102:103], v[112:113], s[84:85] op_sel:[1,1] op_sel_hi:[0,1]
	v_pk_fma_f32 v[112:113], v[112:113], s[84:85], v[102:103] op_sel_hi:[1,0,1] neg_lo:[0,0,1]
	v_pk_mul_f32 v[184:185], v[128:129], s[90:91] op_sel:[1,1] op_sel_hi:[0,1]
	v_pk_fma_f32 v[128:129], v[128:129], s[90:91], v[184:185] op_sel_hi:[1,0,1] neg_lo:[0,0,1]
	v_pk_mul_f32 v[168:169], v[114:115], s[88:89] op_sel:[1,1] op_sel_hi:[0,1]
	v_pk_fma_f32 v[114:115], v[114:115], s[88:89], v[168:169] op_sel_hi:[1,0,1] neg_lo:[0,0,1]
	v_pk_mul_f32 v[126:127], v[122:123], s[90:91] op_sel:[1,1] op_sel_hi:[0,1]
	v_pk_fma_f32 v[122:123], v[122:123], s[90:91], v[126:127] op_sel_hi:[1,0,1] neg_lo:[0,0,1]
	v_pk_mul_f32 v[118:119], v[130:131], s[98:99] op_sel:[1,1] op_sel_hi:[0,1]
	v_pk_fma_f32 v[130:131], v[130:131], s[98:99], v[118:119] op_sel_hi:[1,0,1] neg_lo:[0,0,1]
	v_pk_add_f32 v[186:187], v[100:101], v[116:117]
	v_pk_add_f32 v[188:189], v[100:101], v[116:117] neg_lo:[0,1] neg_hi:[0,1]
	v_pk_add_f32 v[180:181], v[108:109], v[124:125]
	v_pk_add_f32 v[182:183], v[108:109], v[124:125] neg_lo:[0,1] neg_hi:[0,1]
	v_pk_add_f32 v[100:101], v[186:187], v[180:181]
	v_pk_add_f32 v[116:117], v[186:187], v[180:181] neg_lo:[0,1] neg_hi:[0,1]
	v_pk_add_f32 v[108:109], v[188:189], v[182:183] op_sel:[0,1] op_sel_hi:[1,0] neg_hi:[0,1]
	v_pk_add_f32 v[124:125], v[188:189], v[182:183] op_sel:[0,1] op_sel_hi:[1,0] neg_lo:[0,1]
	v_pk_add_f32 v[110:111], v[178:179], v[166:167]
	v_pk_add_f32 v[102:103], v[178:179], v[166:167] neg_lo:[0,1] neg_hi:[0,1]
	v_pk_add_f32 v[184:185], v[176:177], v[174:175]
	v_pk_add_f32 v[168:169], v[176:177], v[174:175] neg_lo:[0,1] neg_hi:[0,1]
	v_pk_add_f32 v[178:179], v[110:111], v[184:185]
	v_pk_add_f32 v[166:167], v[110:111], v[184:185] neg_lo:[0,1] neg_hi:[0,1]
	v_pk_add_f32 v[176:177], v[102:103], v[168:169] op_sel:[0,1] op_sel_hi:[1,0] neg_hi:[0,1]
	v_pk_add_f32 v[174:175], v[102:103], v[168:169] op_sel:[0,1] op_sel_hi:[1,0] neg_lo:[0,1]
	v_pk_add_f32 v[126:127], v[104:105], v[120:121] op_sel:[0,1] op_sel_hi:[1,0] neg_hi:[0,1]
	v_pk_add_f32 v[118:119], v[104:105], v[120:121] op_sel:[0,1] op_sel_hi:[1,0] neg_lo:[0,1]
	v_pk_add_f32 v[186:187], v[112:113], v[128:129]
	v_pk_add_f32 v[188:189], v[112:113], v[128:129] neg_lo:[0,1] neg_hi:[0,1]
	v_pk_add_f32 v[104:105], v[126:127], v[186:187]
	v_pk_add_f32 v[120:121], v[126:127], v[186:187] neg_lo:[0,1] neg_hi:[0,1]
	v_pk_add_f32 v[112:113], v[118:119], v[188:189] op_sel:[0,1] op_sel_hi:[1,0] neg_hi:[0,1]
	v_pk_add_f32 v[128:129], v[118:119], v[188:189] op_sel:[0,1] op_sel_hi:[1,0] neg_lo:[0,1]
	v_pk_add_f32 v[180:181], v[106:107], v[122:123]
	v_pk_add_f32 v[182:183], v[106:107], v[122:123] neg_lo:[0,1] neg_hi:[0,1]
	v_pk_add_f32 v[110:111], v[114:115], v[130:131]
	v_pk_add_f32 v[102:103], v[114:115], v[130:131] neg_lo:[0,1] neg_hi:[0,1]
	v_pk_add_f32 v[106:107], v[180:181], v[110:111]
	v_pk_add_f32 v[122:123], v[180:181], v[110:111] neg_lo:[0,1] neg_hi:[0,1]
	v_pk_add_f32 v[114:115], v[182:183], v[102:103] op_sel:[0,1] op_sel_hi:[1,0] neg_hi:[0,1]
	v_pk_add_f32 v[130:131], v[182:183], v[102:103] op_sel:[0,1] op_sel_hi:[1,0] neg_lo:[0,1]
	ds_read_b64 v[184:185], v200
	ds_read_b64 v[186:187], v204
	ds_read_b64 v[168:169], v200 offset:16
	ds_read_b64 v[188:189], v202 offset:232
	ds_read_b64 v[126:127], v200 offset:32
	ds_read_b64 v[180:181], v202 offset:216
	ds_read_b64 v[118:119], v200 offset:48
	ds_read_b64 v[182:183], v202 offset:200
	s_waitcnt lgkmcnt(6)
	v_pk_add_f32 v[184:185], v[184:185], v[186:187] neg_hi:[0,1]
	v_pk_mul_f32 v[110:111], v[100:101], v[184:185] op_sel:[1,1] op_sel_hi:[0,1]
	v_pk_fma_f32 v[100:101], v[100:101], v[184:185], v[110:111] op_sel_hi:[1,0,1] neg_lo:[0,0,1]
	s_waitcnt lgkmcnt(4)
	v_pk_add_f32 v[168:169], v[168:169], v[188:189] neg_hi:[0,1]
	v_pk_mul_f32 v[102:103], v[178:179], v[168:169] op_sel:[1,1] op_sel_hi:[0,1]
	v_pk_fma_f32 v[178:179], v[178:179], v[168:169], v[102:103] op_sel_hi:[1,0,1] neg_lo:[0,0,1]
	s_waitcnt lgkmcnt(2)
	v_pk_add_f32 v[126:127], v[126:127], v[180:181] neg_hi:[0,1]
	v_pk_mul_f32 v[110:111], v[104:105], v[126:127] op_sel:[1,1] op_sel_hi:[0,1]
	v_pk_fma_f32 v[104:105], v[104:105], v[126:127], v[110:111] op_sel_hi:[1,0,1] neg_lo:[0,0,1]
	s_waitcnt lgkmcnt(0)
	v_pk_add_f32 v[118:119], v[118:119], v[182:183] neg_hi:[0,1]
	v_pk_mul_f32 v[102:103], v[106:107], v[118:119] op_sel:[1,1] op_sel_hi:[0,1]
	v_pk_fma_f32 v[106:107], v[106:107], v[118:119], v[102:103] op_sel_hi:[1,0,1] neg_lo:[0,0,1]
	ds_read_b64 v[110:111], v200 offset:64
	ds_read_b64 v[126:127], v202 offset:184
	ds_read_b64 v[102:103], v200 offset:80
	ds_read_b64 v[118:119], v202 offset:168
	ds_read_b64 v[184:185], v200 offset:96
	ds_read_b64 v[186:187], v202 offset:152
	ds_read_b64 v[168:169], v200 offset:112
	ds_read_b64 v[188:189], v202 offset:136
	s_waitcnt lgkmcnt(6)
; #define LAS __attribute__((address_space(3)))
; __device__ __forceinline__ f32x2 cmul(f32x2 a, f32x2 b) { return (f32x2){a.x * b.x - a.y * b.y, a.x * b.y + a.y * b.x}; }
; template <bool INV> __device__ __forceinline__ f32x2 cmul_tw(f32x2 a, f32x2 w) { return INV ? cmulc(a, w) : cmul(a, w); }
; template <bool INV> __device__ __forceinline__ void dft16(f32x2 (&x)[16]) {
;     constexpr float C1 = 0.92387953251128674f, S1 = 0.38268343236508977f, C2 = 0.70710678118654752f;
; #pragma unroll
;     for (int b = 0; b < 4; ++b) dft4<INV>(x[b], x[4 + b], x[8 + b], x[12 + b]);
;     const f32x2 w1 = {C1, -S1}, w2 = {C2, -C2}, w3 = {S1, -C1}, w4 = {0.f, -1.f}, w6 = {-C2, -C2}, w9 = {-C1, S1};
;     x[4 * 1 + 1] = cmul_tw<INV>(x[5], w1); x[4 * 1 + 2] = cmul_tw<INV>(x[6], w2); x[4 * 1 + 3] = cmul_tw<INV>(x[7], w3);
;     x[4 * 2 + 1] = cmul_tw<INV>(x[9], w2); x[4 * 2 + 2] = cmul_tw<INV>(x[10], w4); x[4 * 2 + 3] = cmul_tw<INV>(x[11], w6);
;     x[4 * 3 + 1] = cmul_tw<INV>(x[13], w3); x[4 * 3 + 2] = cmul_tw<INV>(x[14], w6); x[4 * 3 + 3] = cmul_tw<INV>(x[15], w9);
; #pragma unroll
;     for (int c = 0; c < 4; ++c) dft4<INV>(x[4 * c], x[4 * c + 1], x[4 * c + 2], x[4 * c + 3]);
;     f32x2 y[16];
; #pragma unroll
;     for (int k = 0; k < 16; ++k) y[k] = x[4 * (k & 3) + (k >> 2)];
; #pragma unroll
;     for (int k = 0; k < 16; ++k) x[k] = y[k];
; }
; template <int MODE> __device__ __forceinline__ void fft_pair32(LAS f32x2* B, const LAS f32x2* F, int wave, int lane) {
;     ...
;     const int k1 = blk >> 4, k2 = blk & 15, kb1 = (16 - k1) & 15, b1 = k1 != 0 ? 1 : 0, kb2 = (16 - k2 - b1) & 15, b2 = (k2 != 0 || b1) ? 1 : 0;
;     const LAS f32x2* fa = F + 33 * blk; const LAS f32x2* fb = F + 33 * (16 * kb1 + kb2);
;     const LAS f32x2* fah = fa + hi; const LAS f32x2* fbh = fb + (1 - b2) - hi;
;     constexpr float SC = 1.0f / (2.0f * (float)FN);
; #pragma unroll
;     for (int k = 0; k < 16; ++k) { const f32x2 A = fah[2 * k]; f32x2 Bm = fbh[31 - 2 * k];
;         if (k == 0) { const f32x2 m0 = b2 ? fb[31] : fa[0]; Bm = hi ? Bm : m0; }
;         const f32x2 H = MODE == 0 ? (f32x2){(A.x + Bm.x) * SC, (A.y - Bm.y) * SC} : (f32x2){(A.y + Bm.y) * SC, (Bm.x - A.x) * SC};
;         v[k] = cmul(v[k], H); }
;     dft16<true>(v);
	v_pk_add_f32 v[110:111], v[110:111], v[126:127] neg_hi:[0,1]
	v_pk_mul_f32 v[180:181], v[108:109], v[110:111] op_sel:[1,1] op_sel_hi:[0,1]
	v_pk_fma_f32 v[108:109], v[108:109], v[110:111], v[180:181] op_sel_hi:[1,0,1] neg_lo:[0,0,1]
	s_waitcnt lgkmcnt(4)
	v_pk_add_f32 v[102:103], v[102:103], v[118:119] neg_hi:[0,1]
	v_pk_mul_f32 v[182:183], v[176:177], v[102:103] op_sel:[1,1] op_sel_hi:[0,1]
	v_pk_fma_f32 v[176:177], v[176:177], v[102:103], v[182:183] op_sel_hi:[1,0,1] neg_lo:[0,0,1]
	s_waitcnt lgkmcnt(2)
	v_pk_add_f32 v[184:185], v[184:185], v[186:187] neg_hi:[0,1]
	v_pk_mul_f32 v[180:181], v[112:113], v[184:185] op_sel:[1,1] op_sel_hi:[0,1]
	v_pk_fma_f32 v[112:113], v[112:113], v[184:185], v[180:181] op_sel_hi:[1,0,1] neg_lo:[0,0,1]
	s_waitcnt lgkmcnt(0)
	v_pk_add_f32 v[168:169], v[168:169], v[188:189] neg_hi:[0,1]
	v_pk_mul_f32 v[182:183], v[114:115], v[168:169] op_sel:[1,1] op_sel_hi:[0,1]
	v_pk_fma_f32 v[114:115], v[114:115], v[168:169], v[182:183] op_sel_hi:[1,0,1] neg_lo:[0,0,1]
	ds_read_b64 v[180:181], v200 offset:128
	ds_read_b64 v[184:185], v202 offset:120
	ds_read_b64 v[182:183], v200 offset:144
	ds_read_b64 v[168:169], v202 offset:104
	ds_read_b64 v[110:111], v200 offset:160
	ds_read_b64 v[126:127], v202 offset:88
	ds_read_b64 v[102:103], v200 offset:176
	ds_read_b64 v[118:119], v202 offset:72
	s_waitcnt lgkmcnt(6)
	v_pk_add_f32 v[180:181], v[180:181], v[184:185] neg_hi:[0,1]
	v_pk_mul_f32 v[186:187], v[116:117], v[180:181] op_sel:[1,1] op_sel_hi:[0,1]
	v_pk_fma_f32 v[116:117], v[116:117], v[180:181], v[186:187] op_sel_hi:[1,0,1] neg_lo:[0,0,1]
	s_waitcnt lgkmcnt(4)
	v_pk_add_f32 v[182:183], v[182:183], v[168:169] neg_hi:[0,1]
	v_pk_mul_f32 v[188:189], v[166:167], v[182:183] op_sel:[1,1] op_sel_hi:[0,1]
	v_pk_fma_f32 v[166:167], v[166:167], v[182:183], v[188:189] op_sel_hi:[1,0,1] neg_lo:[0,0,1]
	s_waitcnt lgkmcnt(2)
	v_pk_add_f32 v[110:111], v[110:111], v[126:127] neg_hi:[0,1]
	v_pk_mul_f32 v[186:187], v[120:121], v[110:111] op_sel:[1,1] op_sel_hi:[0,1]
	v_pk_fma_f32 v[120:121], v[120:121], v[110:111], v[186:187] op_sel_hi:[1,0,1] neg_lo:[0,0,1]
	s_waitcnt lgkmcnt(0)
	v_pk_add_f32 v[102:103], v[102:103], v[118:119] neg_hi:[0,1]
	v_pk_mul_f32 v[188:189], v[122:123], v[102:103] op_sel:[1,1] op_sel_hi:[0,1]
	v_pk_fma_f32 v[122:123], v[122:123], v[102:103], v[188:189] op_sel_hi:[1,0,1] neg_lo:[0,0,1]
	ds_read_b64 v[186:187], v200 offset:192
	ds_read_b64 v[110:111], v202 offset:56
	ds_read_b64 v[188:189], v200 offset:208
	ds_read_b64 v[102:103], v202 offset:40
	ds_read_b64 v[180:181], v200 offset:224
	ds_read_b64 v[184:185], v202 offset:24
	ds_read_b64 v[182:183], v200 offset:240
	ds_read_b64 v[168:169], v202 offset:8
	s_waitcnt lgkmcnt(6)
	v_pk_add_f32 v[186:187], v[186:187], v[110:111] neg_hi:[0,1]
	v_pk_mul_f32 v[126:127], v[124:125], v[186:187] op_sel:[1,1] op_sel_hi:[0,1]
	v_pk_fma_f32 v[124:125], v[124:125], v[186:187], v[126:127] op_sel_hi:[1,0,1] neg_lo:[0,0,1]
	s_waitcnt lgkmcnt(4)
	v_pk_add_f32 v[188:189], v[188:189], v[102:103] neg_hi:[0,1]
	v_pk_mul_f32 v[118:119], v[174:175], v[188:189] op_sel:[1,1] op_sel_hi:[0,1]
	v_pk_fma_f32 v[174:175], v[174:175], v[188:189], v[118:119] op_sel_hi:[1,0,1] neg_lo:[0,0,1]
	s_waitcnt lgkmcnt(2)
	v_pk_add_f32 v[180:181], v[180:181], v[184:185] neg_hi:[0,1]
	v_pk_mul_f32 v[126:127], v[128:129], v[180:181] op_sel:[1,1] op_sel_hi:[0,1]
	v_pk_fma_f32 v[128:129], v[128:129], v[180:181], v[126:127] op_sel_hi:[1,0,1] neg_lo:[0,0,1]
	s_waitcnt lgkmcnt(0)
	v_pk_add_f32 v[182:183], v[182:183], v[168:169] neg_hi:[0,1]
	v_pk_mul_f32 v[118:119], v[130:131], v[182:183] op_sel:[1,1] op_sel_hi:[0,1]
	v_pk_fma_f32 v[130:131], v[130:131], v[182:183], v[118:119] op_sel_hi:[1,0,1] neg_lo:[0,0,1]
	v_pk_add_f32 v[126:127], v[100:101], v[116:117]
	v_pk_add_f32 v[118:119], v[100:101], v[116:117] neg_lo:[0,1] neg_hi:[0,1]
	v_pk_add_f32 v[186:187], v[108:109], v[124:125]
	v_pk_add_f32 v[188:189], v[108:109], v[124:125] neg_lo:[0,1] neg_hi:[0,1]
	v_pk_add_f32 v[100:101], v[126:127], v[186:187]
	v_pk_add_f32 v[116:117], v[126:127], v[186:187] neg_lo:[0,1] neg_hi:[0,1]
	v_pk_add_f32 v[108:109], v[118:119], v[188:189] op_sel:[0,1] op_sel_hi:[1,0] neg_lo:[0,1]
	v_pk_add_f32 v[124:125], v[118:119], v[188:189] op_sel:[0,1] op_sel_hi:[1,0] neg_hi:[0,1]
	v_pk_add_f32 v[180:181], v[178:179], v[166:167]
	v_pk_add_f32 v[182:183], v[178:179], v[166:167] neg_lo:[0,1] neg_hi:[0,1]
	v_pk_add_f32 v[110:111], v[176:177], v[174:175]
	v_pk_add_f32 v[102:103], v[176:177], v[174:175] neg_lo:[0,1] neg_hi:[0,1]
	v_pk_add_f32 v[178:179], v[180:181], v[110:111]
	v_pk_add_f32 v[166:167], v[180:181], v[110:111] neg_lo:[0,1] neg_hi:[0,1]
	v_pk_add_f32 v[176:177], v[182:183], v[102:103] op_sel:[0,1] op_sel_hi:[1,0] neg_lo:[0,1]
	v_pk_add_f32 v[174:175], v[182:183], v[102:103] op_sel:[0,1] op_sel_hi:[1,0] neg_hi:[0,1]
	v_pk_add_f32 v[184:185], v[104:105], v[120:121]
	v_pk_add_f32 v[168:169], v[104:105], v[120:121] neg_lo:[0,1] neg_hi:[0,1]
	v_pk_add_f32 v[126:127], v[112:113], v[128:129]
	v_pk_add_f32 v[118:119], v[112:113], v[128:129] neg_lo:[0,1] neg_hi:[0,1]
	v_pk_add_f32 v[104:105], v[184:185], v[126:127]
	v_pk_add_f32 v[120:121], v[184:185], v[126:127] neg_lo:[0,1] neg_hi:[0,1]
	v_pk_add_f32 v[112:113], v[168:169], v[118:119] op_sel:[0,1] op_sel_hi:[1,0] neg_lo:[0,1]
	v_pk_add_f32 v[128:129], v[168:169], v[118:119] op_sel:[0,1] op_sel_hi:[1,0] neg_hi:[0,1]
	v_pk_add_f32 v[186:187], v[106:107], v[122:123]
	v_pk_add_f32 v[188:189], v[106:107], v[122:123] neg_lo:[0,1] neg_hi:[0,1]
	v_pk_add_f32 v[180:181], v[114:115], v[130:131]
	v_pk_add_f32 v[182:183], v[114:115], v[130:131] neg_lo:[0,1] neg_hi:[0,1]
	v_pk_add_f32 v[106:107], v[186:187], v[180:181]
; __device__ __forceinline__ f32x2 cmulc(f32x2 a, f32x2 b) { return (f32x2){a.x * b.x + a.y * b.y, a.y * b.x - a.x * b.y}; }
; template <int MODE> __device__ __forceinline__ void fft_pair32(LAS f32x2* B, const LAS f32x2* F, int wave, int lane) {
;     ...
;     dft16<true>(v);
; #pragma unroll
;     for (int j = 0; j < 16; ++j) { const f32x2 w = {hi ? CS[j] : 1.f, hi ? -SN[j] : 0.f}; const f32x2 u = j == 0 ? v[j] : cmulc(v[j], w);
;         const auto rx = __builtin_amdgcn_permlane32_swap(__float_as_uint(u.x), __float_as_uint(u.x), false, false);
;         const auto ry = __builtin_amdgcn_permlane32_swap(__float_as_uint(u.y), __float_as_uint(u.y), false, false);
;         const f32x2 a = {__uint_as_float(rx[0]), __uint_as_float(ry[0])}, b = {__uint_as_float(rx[1]), __uint_as_float(ry[1])};
;         p[16 * hi + j] = a + b * sg; }
	v_pk_add_f32 v[122:123], v[186:187], v[180:181] neg_lo:[0,1] neg_hi:[0,1]
	v_pk_add_f32 v[114:115], v[188:189], v[182:183] op_sel:[0,1] op_sel_hi:[1,0] neg_lo:[0,1]
	v_pk_add_f32 v[130:131], v[188:189], v[182:183] op_sel:[0,1] op_sel_hi:[1,0] neg_hi:[0,1]
	v_pk_mul_f32 v[110:111], v[176:177], s[68:69] op_sel:[1,1] op_sel_hi:[0,1]
	v_pk_fma_f32 v[176:177], v[176:177], s[68:69], v[110:111] op_sel_hi:[1,0,1] neg_hi:[0,0,1]
	v_pk_mul_f32 v[102:103], v[112:113], s[84:85] op_sel:[1,1] op_sel_hi:[0,1]
	v_pk_fma_f32 v[112:113], v[112:113], s[84:85], v[102:103] op_sel_hi:[1,0,1] neg_hi:[0,0,1]
	v_pk_mul_f32 v[184:185], v[114:115], s[88:89] op_sel:[1,1] op_sel_hi:[0,1]
	v_pk_fma_f32 v[114:115], v[114:115], s[88:89], v[184:185] op_sel_hi:[1,0,1] neg_hi:[0,0,1]
	v_pk_mul_f32 v[168:169], v[166:167], s[84:85] op_sel:[1,1] op_sel_hi:[0,1]
	v_pk_fma_f32 v[166:167], v[166:167], s[84:85], v[168:169] op_sel_hi:[1,0,1] neg_hi:[0,0,1]
	v_pk_mul_f32 v[126:127], v[122:123], s[90:91] op_sel:[1,1] op_sel_hi:[0,1]
	v_pk_fma_f32 v[122:123], v[122:123], s[90:91], v[126:127] op_sel_hi:[1,0,1] neg_hi:[0,0,1]
	v_pk_mul_f32 v[118:119], v[174:175], s[88:89] op_sel:[1,1] op_sel_hi:[0,1]
	v_pk_fma_f32 v[174:175], v[174:175], s[88:89], v[118:119] op_sel_hi:[1,0,1] neg_hi:[0,0,1]
	v_pk_mul_f32 v[186:187], v[128:129], s[90:91] op_sel:[1,1] op_sel_hi:[0,1]
	v_pk_fma_f32 v[128:129], v[128:129], s[90:91], v[186:187] op_sel_hi:[1,0,1] neg_hi:[0,0,1]
	v_pk_mul_f32 v[188:189], v[130:131], s[98:99] op_sel:[1,1] op_sel_hi:[0,1]
	v_pk_fma_f32 v[130:131], v[130:131], s[98:99], v[188:189] op_sel_hi:[1,0,1] neg_hi:[0,0,1]
	v_pk_add_f32 v[180:181], v[100:101], v[104:105]
	v_pk_add_f32 v[182:183], v[100:101], v[104:105] neg_lo:[0,1] neg_hi:[0,1]
	v_pk_add_f32 v[110:111], v[178:179], v[106:107]
	v_pk_add_f32 v[102:103], v[178:179], v[106:107] neg_lo:[0,1] neg_hi:[0,1]
	v_pk_add_f32 v[100:101], v[180:181], v[110:111]
	v_pk_add_f32 v[104:105], v[180:181], v[110:111] neg_lo:[0,1] neg_hi:[0,1]
	v_pk_add_f32 v[178:179], v[182:183], v[102:103] op_sel:[0,1] op_sel_hi:[1,0] neg_lo:[0,1]
	v_pk_add_f32 v[106:107], v[182:183], v[102:103] op_sel:[0,1] op_sel_hi:[1,0] neg_hi:[0,1]
	v_pk_add_f32 v[184:185], v[108:109], v[112:113]
	v_pk_add_f32 v[168:169], v[108:109], v[112:113] neg_lo:[0,1] neg_hi:[0,1]
	v_pk_add_f32 v[126:127], v[176:177], v[114:115]
	v_pk_add_f32 v[118:119], v[176:177], v[114:115] neg_lo:[0,1] neg_hi:[0,1]
	v_pk_add_f32 v[108:109], v[184:185], v[126:127]
	v_pk_add_f32 v[112:113], v[184:185], v[126:127] neg_lo:[0,1] neg_hi:[0,1]
	v_pk_add_f32 v[176:177], v[168:169], v[118:119] op_sel:[0,1] op_sel_hi:[1,0] neg_lo:[0,1]
	v_pk_add_f32 v[114:115], v[168:169], v[118:119] op_sel:[0,1] op_sel_hi:[1,0] neg_hi:[0,1]
	v_pk_add_f32 v[186:187], v[116:117], v[120:121] op_sel:[0,1] op_sel_hi:[1,0] neg_lo:[0,1]
	v_pk_add_f32 v[188:189], v[116:117], v[120:121] op_sel:[0,1] op_sel_hi:[1,0] neg_hi:[0,1]
	v_pk_add_f32 v[180:181], v[166:167], v[122:123]
	v_pk_add_f32 v[182:183], v[166:167], v[122:123] neg_lo:[0,1] neg_hi:[0,1]
	v_pk_add_f32 v[116:117], v[186:187], v[180:181]
	v_pk_add_f32 v[120:121], v[186:187], v[180:181] neg_lo:[0,1] neg_hi:[0,1]
	v_pk_add_f32 v[166:167], v[188:189], v[182:183] op_sel:[0,1] op_sel_hi:[1,0] neg_lo:[0,1]
	v_pk_add_f32 v[122:123], v[188:189], v[182:183] op_sel:[0,1] op_sel_hi:[1,0] neg_hi:[0,1]
	v_pk_add_f32 v[110:111], v[124:125], v[128:129]
	v_pk_add_f32 v[102:103], v[124:125], v[128:129] neg_lo:[0,1] neg_hi:[0,1]
	v_pk_add_f32 v[184:185], v[174:175], v[130:131]
	v_pk_add_f32 v[168:169], v[174:175], v[130:131] neg_lo:[0,1] neg_hi:[0,1]
	v_pk_add_f32 v[124:125], v[110:111], v[184:185]
	v_pk_add_f32 v[128:129], v[110:111], v[184:185] neg_lo:[0,1] neg_hi:[0,1]
	v_pk_add_f32 v[174:175], v[102:103], v[168:169] op_sel:[0,1] op_sel_hi:[1,0] neg_lo:[0,1]
	v_pk_add_f32 v[130:131], v[102:103], v[168:169] op_sel:[0,1] op_sel_hi:[1,0] neg_hi:[0,1]
	v_mov_b32_e32 v126, v100
	v_mov_b32_e32 v127, v101
	v_pk_mul_f32 v[180:181], v[108:109], v[36:37] op_sel:[1,1] op_sel_hi:[0,1]
	v_pk_fma_f32 v[118:119], v[108:109], v[36:37], v[180:181] op_sel_hi:[1,0,1] neg_hi:[0,0,1]
	v_pk_fma_f32 v[108:109], v[108:109], v[36:37], v[180:181] op_sel_hi:[1,0,1] neg_hi:[0,0,1]
	v_pk_mul_f32 v[182:183], v[116:117], v[38:39] op_sel:[1,1] op_sel_hi:[0,1]
	v_pk_fma_f32 v[186:187], v[116:117], v[38:39], v[182:183] op_sel_hi:[1,0,1] neg_hi:[0,0,1]
	v_pk_fma_f32 v[116:117], v[116:117], v[38:39], v[182:183] op_sel_hi:[1,0,1] neg_hi:[0,0,1]
	v_pk_mul_f32 v[110:111], v[124:125], v[40:41] op_sel:[1,1] op_sel_hi:[0,1]
	v_pk_fma_f32 v[188:189], v[124:125], v[40:41], v[110:111] op_sel_hi:[1,0,1] neg_hi:[0,0,1]
	v_pk_fma_f32 v[124:125], v[124:125], v[40:41], v[110:111] op_sel_hi:[1,0,1] neg_hi:[0,0,1]
	s_nop 1
	v_permlane32_swap_b32_e32 v100, v126
	v_permlane32_swap_b32_e32 v101, v127
	v_permlane32_swap_b32_e32 v108, v118
	v_permlane32_swap_b32_e32 v109, v119
	v_permlane32_swap_b32_e32 v116, v186
	v_permlane32_swap_b32_e32 v117, v187
	v_permlane32_swap_b32_e32 v124, v188
	v_permlane32_swap_b32_e32 v125, v189
	v_pk_fma_f32 v[100:101], v[126:127], v[190:191], v[100:101] op_sel_hi:[1,0,1]
	ds_write_b64 v198, v[100:101]
	v_pk_fma_f32 v[108:109], v[118:119], v[190:191], v[108:109] op_sel_hi:[1,0,1]
	ds_write_b64 v198, v[108:109] offset:8
	v_pk_fma_f32 v[116:117], v[186:187], v[190:191], v[116:117] op_sel_hi:[1,0,1]
	ds_write_b64 v198, v[116:117] offset:16
	v_pk_fma_f32 v[124:125], v[188:189], v[190:191], v[124:125] op_sel_hi:[1,0,1]
	ds_write_b64 v198, v[124:125] offset:24
	v_pk_mul_f32 v[182:183], v[178:179], v[42:43] op_sel:[1,1] op_sel_hi:[0,1]
	v_pk_fma_f32 v[102:103], v[178:179], v[42:43], v[182:183] op_sel_hi:[1,0,1] neg_hi:[0,0,1]
; #define LAS __attribute__((address_space(3)))
; __device__ __forceinline__ f32x2 cmulc(f32x2 a, f32x2 b) { return (f32x2){a.x * b.x + a.y * b.y, a.y * b.x - a.x * b.y}; }
; __device__ __forceinline__ void fft_inv2(LAS f32x2* B, const LAS f32x2* TW2, int tid) {
;     asm volatile("" : "+v"(tid));
;     const int b = tid >> 5, n2 = tid & 31, base = 512 * b + n2; f32x2 x[16];
;     x[0] = B[fpad(base)];
; #pragma unroll
;     for (int k = 1; k < 16; ++k) x[k] = cmulc(B[fpad(base + 32 * k)], TW2[k * 32 + n2]);
; template <int MODE> __device__ __forceinline__ void fft_pair32(LAS f32x2* B, const LAS f32x2* F, int wave, int lane) {
;     ...
;     dft16<true>(v);
; #pragma unroll
;     for (int j = 0; j < 16; ++j) { const f32x2 w = {hi ? CS[j] : 1.f, hi ? -SN[j] : 0.f}; const f32x2 u = j == 0 ? v[j] : cmulc(v[j], w);
;         const auto rx = __builtin_amdgcn_permlane32_swap(__float_as_uint(u.x), __float_as_uint(u.x), false, false);
;         const auto ry = __builtin_amdgcn_permlane32_swap(__float_as_uint(u.y), __float_as_uint(u.y), false, false);
;         const f32x2 a = {__uint_as_float(rx[0]), __uint_as_float(ry[0])}, b = {__uint_as_float(rx[1]), __uint_as_float(ry[1])};
;         p[16 * hi + j] = a + b * sg; }
	v_pk_fma_f32 v[178:179], v[178:179], v[42:43], v[182:183] op_sel_hi:[1,0,1] neg_hi:[0,0,1]
	v_pk_mul_f32 v[110:111], v[176:177], v[44:45] op_sel:[1,1] op_sel_hi:[0,1]
	v_pk_fma_f32 v[184:185], v[176:177], v[44:45], v[110:111] op_sel_hi:[1,0,1] neg_hi:[0,0,1]
	v_pk_fma_f32 v[176:177], v[176:177], v[44:45], v[110:111] op_sel_hi:[1,0,1] neg_hi:[0,0,1]
	v_pk_mul_f32 v[126:127], v[166:167], v[46:47] op_sel:[1,1] op_sel_hi:[0,1]
	v_pk_fma_f32 v[168:169], v[166:167], v[46:47], v[126:127] op_sel_hi:[1,0,1] neg_hi:[0,0,1]
	v_pk_fma_f32 v[166:167], v[166:167], v[46:47], v[126:127] op_sel_hi:[1,0,1] neg_hi:[0,0,1]
	v_pk_mul_f32 v[118:119], v[174:175], v[48:49] op_sel:[1,1] op_sel_hi:[0,1]
	v_pk_fma_f32 v[180:181], v[174:175], v[48:49], v[118:119] op_sel_hi:[1,0,1] neg_hi:[0,0,1]
	v_pk_fma_f32 v[174:175], v[174:175], v[48:49], v[118:119] op_sel_hi:[1,0,1] neg_hi:[0,0,1]
	s_nop 1
	v_permlane32_swap_b32_e32 v178, v102
	v_permlane32_swap_b32_e32 v179, v103
	v_permlane32_swap_b32_e32 v176, v184
	v_permlane32_swap_b32_e32 v177, v185
	v_permlane32_swap_b32_e32 v166, v168
	v_permlane32_swap_b32_e32 v167, v169
	v_permlane32_swap_b32_e32 v174, v180
	v_permlane32_swap_b32_e32 v175, v181
	v_pk_fma_f32 v[178:179], v[102:103], v[190:191], v[178:179] op_sel_hi:[1,0,1]
	ds_write_b64 v198, v[178:179] offset:32
	v_pk_fma_f32 v[176:177], v[184:185], v[190:191], v[176:177] op_sel_hi:[1,0,1]
	ds_write_b64 v198, v[176:177] offset:40
	v_pk_fma_f32 v[166:167], v[168:169], v[190:191], v[166:167] op_sel_hi:[1,0,1]
	ds_write_b64 v198, v[166:167] offset:48
	v_pk_fma_f32 v[174:175], v[180:181], v[190:191], v[174:175] op_sel_hi:[1,0,1]
	ds_write_b64 v198, v[174:175] offset:56
	v_pk_mul_f32 v[126:127], v[104:105], v[50:51] op_sel:[1,1] op_sel_hi:[0,1]
	v_pk_fma_f32 v[186:187], v[104:105], v[50:51], v[126:127] op_sel_hi:[1,0,1] neg_hi:[0,0,1]
	v_pk_fma_f32 v[104:105], v[104:105], v[50:51], v[126:127] op_sel_hi:[1,0,1] neg_hi:[0,0,1]
	v_pk_mul_f32 v[118:119], v[112:113], v[52:53] op_sel:[1,1] op_sel_hi:[0,1]
	v_pk_fma_f32 v[188:189], v[112:113], v[52:53], v[118:119] op_sel_hi:[1,0,1] neg_hi:[0,0,1]
	v_pk_fma_f32 v[112:113], v[112:113], v[52:53], v[118:119] op_sel_hi:[1,0,1] neg_hi:[0,0,1]
	v_pk_mul_f32 v[102:103], v[120:121], v[54:55] op_sel:[1,1] op_sel_hi:[0,1]
	v_pk_fma_f32 v[182:183], v[120:121], v[54:55], v[102:103] op_sel_hi:[1,0,1] neg_hi:[0,0,1]
	v_pk_fma_f32 v[120:121], v[120:121], v[54:55], v[102:103] op_sel_hi:[1,0,1] neg_hi:[0,0,1]
	v_pk_mul_f32 v[184:185], v[128:129], v[90:91] op_sel:[1,1] op_sel_hi:[0,1]
	v_pk_fma_f32 v[110:111], v[128:129], v[90:91], v[184:185] op_sel_hi:[1,0,1] neg_hi:[0,0,1]
	v_pk_fma_f32 v[128:129], v[128:129], v[90:91], v[184:185] op_sel_hi:[1,0,1] neg_hi:[0,0,1]
	s_nop 1
	v_permlane32_swap_b32_e32 v104, v186
	v_permlane32_swap_b32_e32 v105, v187
	v_permlane32_swap_b32_e32 v112, v188
	v_permlane32_swap_b32_e32 v113, v189
	v_permlane32_swap_b32_e32 v120, v182
	v_permlane32_swap_b32_e32 v121, v183
	v_permlane32_swap_b32_e32 v128, v110
	v_permlane32_swap_b32_e32 v129, v111
	v_pk_fma_f32 v[104:105], v[186:187], v[190:191], v[104:105] op_sel_hi:[1,0,1]
	ds_write_b64 v198, v[104:105] offset:64
	v_pk_fma_f32 v[112:113], v[188:189], v[190:191], v[112:113] op_sel_hi:[1,0,1]
	ds_write_b64 v198, v[112:113] offset:72
	v_pk_fma_f32 v[120:121], v[182:183], v[190:191], v[120:121] op_sel_hi:[1,0,1]
	ds_write_b64 v198, v[120:121] offset:80
	v_pk_fma_f32 v[128:129], v[110:111], v[190:191], v[128:129] op_sel_hi:[1,0,1]
	ds_write_b64 v198, v[128:129] offset:88
	v_pk_mul_f32 v[102:103], v[106:107], v[92:93] op_sel:[1,1] op_sel_hi:[0,1]
	v_pk_fma_f32 v[168:169], v[106:107], v[92:93], v[102:103] op_sel_hi:[1,0,1] neg_hi:[0,0,1]
	v_pk_fma_f32 v[106:107], v[106:107], v[92:93], v[102:103] op_sel_hi:[1,0,1] neg_hi:[0,0,1]
	v_pk_mul_f32 v[184:185], v[114:115], v[94:95] op_sel:[1,1] op_sel_hi:[0,1]
	v_pk_fma_f32 v[180:181], v[114:115], v[94:95], v[184:185] op_sel_hi:[1,0,1] neg_hi:[0,0,1]
	v_pk_fma_f32 v[114:115], v[114:115], v[94:95], v[184:185] op_sel_hi:[1,0,1] neg_hi:[0,0,1]
	v_pk_mul_f32 v[186:187], v[122:123], v[96:97] op_sel:[1,1] op_sel_hi:[0,1]
	v_pk_fma_f32 v[126:127], v[122:123], v[96:97], v[186:187] op_sel_hi:[1,0,1] neg_hi:[0,0,1]
	v_pk_fma_f32 v[122:123], v[122:123], v[96:97], v[186:187] op_sel_hi:[1,0,1] neg_hi:[0,0,1]
	v_pk_mul_f32 v[188:189], v[130:131], v[98:99] op_sel:[1,1] op_sel_hi:[0,1]
	v_pk_fma_f32 v[118:119], v[130:131], v[98:99], v[188:189] op_sel_hi:[1,0,1] neg_hi:[0,0,1]
	v_pk_fma_f32 v[130:131], v[130:131], v[98:99], v[188:189] op_sel_hi:[1,0,1] neg_hi:[0,0,1]
	s_nop 1
	v_permlane32_swap_b32_e32 v106, v168
	v_permlane32_swap_b32_e32 v107, v169
	v_permlane32_swap_b32_e32 v114, v180
	v_permlane32_swap_b32_e32 v115, v181
	v_permlane32_swap_b32_e32 v122, v126
	v_permlane32_swap_b32_e32 v123, v127
	v_permlane32_swap_b32_e32 v130, v118
	v_permlane32_swap_b32_e32 v131, v119
	v_pk_fma_f32 v[106:107], v[168:169], v[190:191], v[106:107] op_sel_hi:[1,0,1]
	ds_write_b64 v198, v[106:107] offset:96
	v_pk_fma_f32 v[114:115], v[180:181], v[190:191], v[114:115] op_sel_hi:[1,0,1]
	ds_write_b64 v198, v[114:115] offset:104
	v_pk_fma_f32 v[122:123], v[126:127], v[190:191], v[122:123] op_sel_hi:[1,0,1]
	ds_write_b64 v198, v[122:123] offset:112
	v_pk_fma_f32 v[130:131], v[118:119], v[190:191], v[130:131] op_sel_hi:[1,0,1]
	ds_write_b64 v198, v[130:131] offset:120
	s_waitcnt lgkmcnt(0)
	ds_read_b64 v[100:101], v5
	ds_read_b64 v[108:109], v5 offset:264
	ds_read_b64 v[182:183], v56 offset:256
	ds_read_b64 v[116:117], v5 offset:528
	ds_read_b64 v[110:111], v56 offset:512
	ds_read_b64 v[124:125], v5 offset:792
	ds_read_b64 v[102:103], v56 offset:768
	ds_read_b64 v[178:179], v5 offset:1056
	ds_read_b64 v[184:185], v56 offset:1024
	ds_read_b64 v[176:177], v5 offset:1320
	ds_read_b64 v[186:187], v56 offset:1280
	s_waitcnt lgkmcnt(8)
; #define LAS __attribute__((address_space(3)))
; __device__ __forceinline__ f32x2 cmulc(f32x2 a, f32x2 b) { return (f32x2){a.x * b.x + a.y * b.y, a.y * b.x - a.x * b.y}; }
; template <bool INV> __device__ __forceinline__ f32x2 cmul_tw(f32x2 a, f32x2 w) { return INV ? cmulc(a, w) : cmul(a, w); }
; template <bool INV> __device__ __forceinline__ void dft16(f32x2 (&x)[16]) {
;     constexpr float C1 = 0.92387953251128674f, S1 = 0.38268343236508977f, C2 = 0.70710678118654752f;
; #pragma unroll
;     for (int b = 0; b < 4; ++b) dft4<INV>(x[b], x[4 + b], x[8 + b], x[12 + b]);
;     const f32x2 w1 = {C1, -S1}, w2 = {C2, -C2}, w3 = {S1, -C1}, w4 = {0.f, -1.f}, w6 = {-C2, -C2}, w9 = {-C1, S1};
;     x[4 * 1 + 1] = cmul_tw<INV>(x[5], w1); x[4 * 1 + 2] = cmul_tw<INV>(x[6], w2); x[4 * 1 + 3] = cmul_tw<INV>(x[7], w3);
;     x[4 * 2 + 1] = cmul_tw<INV>(x[9], w2); x[4 * 2 + 2] = cmul_tw<INV>(x[10], w4); x[4 * 2 + 3] = cmul_tw<INV>(x[11], w6);
;     x[4 * 3 + 1] = cmul_tw<INV>(x[13], w3); x[4 * 3 + 2] = cmul_tw<INV>(x[14], w6); x[4 * 3 + 3] = cmul_tw<INV>(x[15], w9);
; #pragma unroll
;     for (int c = 0; c < 4; ++c) dft4<INV>(x[4 * c], x[4 * c + 1], x[4 * c + 2], x[4 * c + 3]);
;     f32x2 y[16];
; #pragma unroll
;     for (int k = 0; k < 16; ++k) y[k] = x[4 * (k & 3) + (k >> 2)];
; #pragma unroll
;     for (int k = 0; k < 16; ++k) x[k] = y[k];
; }
; __device__ __forceinline__ void fft_inv2(LAS f32x2* B, const LAS f32x2* TW2, int tid) {
;     asm volatile("" : "+v"(tid));
;     const int b = tid >> 5, n2 = tid & 31, base = 512 * b + n2; f32x2 x[16];
;     x[0] = B[fpad(base)];
; #pragma unroll
;     for (int k = 1; k < 16; ++k) x[k] = cmulc(B[fpad(base + 32 * k)], TW2[k * 32 + n2]);
;     dft16<true>(x);
; #pragma unroll
;     for (int r = 0; r < 16; ++r) B[fpad(base + 32 * r)] = x[r];
; }
	v_pk_mul_f32 v[188:189], v[108:109], v[182:183] op_sel:[1,1] op_sel_hi:[0,1]
	v_pk_fma_f32 v[108:109], v[108:109], v[182:183], v[188:189] op_sel_hi:[1,0,1] neg_hi:[0,0,1]
	s_waitcnt lgkmcnt(6)
	v_pk_mul_f32 v[168:169], v[116:117], v[110:111] op_sel:[1,1] op_sel_hi:[0,1]
	v_pk_fma_f32 v[116:117], v[116:117], v[110:111], v[168:169] op_sel_hi:[1,0,1] neg_hi:[0,0,1]
	s_waitcnt lgkmcnt(4)
	v_pk_mul_f32 v[180:181], v[124:125], v[102:103] op_sel:[1,1] op_sel_hi:[0,1]
	v_pk_fma_f32 v[124:125], v[124:125], v[102:103], v[180:181] op_sel_hi:[1,0,1] neg_hi:[0,0,1]
	s_waitcnt lgkmcnt(2)
	v_pk_mul_f32 v[126:127], v[178:179], v[184:185] op_sel:[1,1] op_sel_hi:[0,1]
	v_pk_fma_f32 v[178:179], v[178:179], v[184:185], v[126:127] op_sel_hi:[1,0,1] neg_hi:[0,0,1]
	s_waitcnt lgkmcnt(0)
	v_pk_mul_f32 v[118:119], v[176:177], v[186:187] op_sel:[1,1] op_sel_hi:[0,1]
	v_pk_fma_f32 v[176:177], v[176:177], v[186:187], v[118:119] op_sel_hi:[1,0,1] neg_hi:[0,0,1]
	ds_read_b64 v[166:167], v5 offset:1584
	ds_read_b64 v[188:189], v56 offset:1536
	ds_read_b64 v[174:175], v5 offset:1848
	ds_read_b64 v[168:169], v56 offset:1792
	ds_read_b64 v[104:105], v5 offset:2112
	ds_read_b64 v[180:181], v56 offset:2048
	ds_read_b64 v[112:113], v5 offset:2376
	ds_read_b64 v[126:127], v56 offset:2304
	ds_read_b64 v[120:121], v5 offset:2640
	ds_read_b64 v[118:119], v56 offset:2560
	s_waitcnt lgkmcnt(8)
	v_pk_mul_f32 v[182:183], v[166:167], v[188:189] op_sel:[1,1] op_sel_hi:[0,1]
	v_pk_fma_f32 v[166:167], v[166:167], v[188:189], v[182:183] op_sel_hi:[1,0,1] neg_hi:[0,0,1]
	s_waitcnt lgkmcnt(6)
	v_pk_mul_f32 v[110:111], v[174:175], v[168:169] op_sel:[1,1] op_sel_hi:[0,1]
	v_pk_fma_f32 v[174:175], v[174:175], v[168:169], v[110:111] op_sel_hi:[1,0,1] neg_hi:[0,0,1]
	s_waitcnt lgkmcnt(4)
	v_pk_mul_f32 v[102:103], v[104:105], v[180:181] op_sel:[1,1] op_sel_hi:[0,1]
	v_pk_fma_f32 v[104:105], v[104:105], v[180:181], v[102:103] op_sel_hi:[1,0,1] neg_hi:[0,0,1]
	s_waitcnt lgkmcnt(2)
	v_pk_mul_f32 v[184:185], v[112:113], v[126:127] op_sel:[1,1] op_sel_hi:[0,1]
	v_pk_fma_f32 v[112:113], v[112:113], v[126:127], v[184:185] op_sel_hi:[1,0,1] neg_hi:[0,0,1]
	s_waitcnt lgkmcnt(0)
	v_pk_mul_f32 v[186:187], v[120:121], v[118:119] op_sel:[1,1] op_sel_hi:[0,1]
	v_pk_fma_f32 v[120:121], v[120:121], v[118:119], v[186:187] op_sel_hi:[1,0,1] neg_hi:[0,0,1]
	ds_read_b64 v[128:129], v5 offset:2904
	ds_read_b64 v[182:183], v56 offset:2816
	ds_read_b64 v[106:107], v5 offset:3168
	ds_read_b64 v[110:111], v56 offset:3072
	ds_read_b64 v[114:115], v5 offset:3432
	ds_read_b64 v[102:103], v56 offset:3328
	ds_read_b64 v[122:123], v5 offset:3696
	ds_read_b64 v[184:185], v56 offset:3584
	ds_read_b64 v[130:131], v5 offset:3960
	ds_read_b64 v[186:187], v56 offset:3840
	s_waitcnt lgkmcnt(8)
	v_pk_mul_f32 v[188:189], v[128:129], v[182:183] op_sel:[1,1] op_sel_hi:[0,1]
	v_pk_fma_f32 v[128:129], v[128:129], v[182:183], v[188:189] op_sel_hi:[1,0,1] neg_hi:[0,0,1]
	s_waitcnt lgkmcnt(6)
	v_pk_mul_f32 v[168:169], v[106:107], v[110:111] op_sel:[1,1] op_sel_hi:[0,1]
	v_pk_fma_f32 v[106:107], v[106:107], v[110:111], v[168:169] op_sel_hi:[1,0,1] neg_hi:[0,0,1]
	s_waitcnt lgkmcnt(4)
	v_pk_mul_f32 v[180:181], v[114:115], v[102:103] op_sel:[1,1] op_sel_hi:[0,1]
	v_pk_fma_f32 v[114:115], v[114:115], v[102:103], v[180:181] op_sel_hi:[1,0,1] neg_hi:[0,0,1]
	s_waitcnt lgkmcnt(2)
	v_pk_mul_f32 v[126:127], v[122:123], v[184:185] op_sel:[1,1] op_sel_hi:[0,1]
	v_pk_fma_f32 v[122:123], v[122:123], v[184:185], v[126:127] op_sel_hi:[1,0,1] neg_hi:[0,0,1]
	s_waitcnt lgkmcnt(0)
	v_pk_mul_f32 v[118:119], v[130:131], v[186:187] op_sel:[1,1] op_sel_hi:[0,1]
	v_pk_fma_f32 v[130:131], v[130:131], v[186:187], v[118:119] op_sel_hi:[1,0,1] neg_hi:[0,0,1]
	v_pk_add_f32 v[188:189], v[100:101], v[104:105]
	v_pk_add_f32 v[168:169], v[100:101], v[104:105] neg_lo:[0,1] neg_hi:[0,1]
	v_pk_add_f32 v[180:181], v[178:179], v[106:107]
	v_pk_add_f32 v[126:127], v[178:179], v[106:107] neg_lo:[0,1] neg_hi:[0,1]
	v_pk_add_f32 v[100:101], v[188:189], v[180:181]
	v_pk_add_f32 v[104:105], v[188:189], v[180:181] neg_lo:[0,1] neg_hi:[0,1]
	v_pk_add_f32 v[178:179], v[168:169], v[126:127] op_sel:[0,1] op_sel_hi:[1,0] neg_lo:[0,1]
	v_pk_add_f32 v[106:107], v[168:169], v[126:127] op_sel:[0,1] op_sel_hi:[1,0] neg_hi:[0,1]
	v_pk_add_f32 v[118:119], v[108:109], v[112:113]
	v_pk_add_f32 v[182:183], v[108:109], v[112:113] neg_lo:[0,1] neg_hi:[0,1]
	v_pk_add_f32 v[110:111], v[176:177], v[114:115]
	v_pk_add_f32 v[102:103], v[176:177], v[114:115] neg_lo:[0,1] neg_hi:[0,1]
	v_pk_add_f32 v[108:109], v[118:119], v[110:111]
	v_pk_add_f32 v[112:113], v[118:119], v[110:111] neg_lo:[0,1] neg_hi:[0,1]
	v_pk_add_f32 v[176:177], v[182:183], v[102:103] op_sel:[0,1] op_sel_hi:[1,0] neg_lo:[0,1]
	v_pk_add_f32 v[114:115], v[182:183], v[102:103] op_sel:[0,1] op_sel_hi:[1,0] neg_hi:[0,1]
	v_pk_add_f32 v[184:185], v[116:117], v[120:121]
	v_pk_add_f32 v[186:187], v[116:117], v[120:121] neg_lo:[0,1] neg_hi:[0,1]
	v_pk_add_f32 v[188:189], v[166:167], v[122:123]
	v_pk_add_f32 v[168:169], v[166:167], v[122:123] neg_lo:[0,1] neg_hi:[0,1]
	v_pk_add_f32 v[116:117], v[184:185], v[188:189]
	v_pk_add_f32 v[120:121], v[184:185], v[188:189] neg_lo:[0,1] neg_hi:[0,1]
	v_pk_add_f32 v[166:167], v[186:187], v[168:169] op_sel:[0,1] op_sel_hi:[1,0] neg_lo:[0,1]
	v_pk_add_f32 v[122:123], v[186:187], v[168:169] op_sel:[0,1] op_sel_hi:[1,0] neg_hi:[0,1]
	v_pk_add_f32 v[180:181], v[124:125], v[128:129]
	v_pk_add_f32 v[126:127], v[124:125], v[128:129] neg_lo:[0,1] neg_hi:[0,1]
	v_pk_add_f32 v[118:119], v[174:175], v[130:131]
	v_pk_add_f32 v[182:183], v[174:175], v[130:131] neg_lo:[0,1] neg_hi:[0,1]
	v_pk_add_f32 v[124:125], v[180:181], v[118:119]
; #define LAS __attribute__((address_space(3)))
; __device__ __forceinline__ f32x2 cmulc(f32x2 a, f32x2 b) { return (f32x2){a.x * b.x + a.y * b.y, a.y * b.x - a.x * b.y}; }
; __device__ __forceinline__ void fft_inv2(LAS f32x2* B, const LAS f32x2* TW2, int tid) {
;     asm volatile("" : "+v"(tid));
;     const int b = tid >> 5, n2 = tid & 31, base = 512 * b + n2; f32x2 x[16];
;     x[0] = B[fpad(base)];
; #pragma unroll
;     for (int k = 1; k < 16; ++k) x[k] = cmulc(B[fpad(base + 32 * k)], TW2[k * 32 + n2]);
;     dft16<true>(x);
; #pragma unroll
;     for (int r = 0; r < 16; ++r) B[fpad(base + 32 * r)] = x[r];
; }
	v_pk_add_f32 v[128:129], v[180:181], v[118:119] neg_lo:[0,1] neg_hi:[0,1]
	v_pk_add_f32 v[174:175], v[126:127], v[182:183] op_sel:[0,1] op_sel_hi:[1,0] neg_lo:[0,1]
	v_pk_add_f32 v[130:131], v[126:127], v[182:183] op_sel:[0,1] op_sel_hi:[1,0] neg_hi:[0,1]
	v_pk_mul_f32 v[110:111], v[176:177], s[68:69] op_sel:[1,1] op_sel_hi:[0,1]
	v_pk_fma_f32 v[176:177], v[176:177], s[68:69], v[110:111] op_sel_hi:[1,0,1] neg_hi:[0,0,1]
	v_pk_mul_f32 v[102:103], v[166:167], s[84:85] op_sel:[1,1] op_sel_hi:[0,1]
	v_pk_fma_f32 v[166:167], v[166:167], s[84:85], v[102:103] op_sel_hi:[1,0,1] neg_hi:[0,0,1]
	v_pk_mul_f32 v[184:185], v[174:175], s[88:89] op_sel:[1,1] op_sel_hi:[0,1]
	v_pk_fma_f32 v[174:175], v[174:175], s[88:89], v[184:185] op_sel_hi:[1,0,1] neg_hi:[0,0,1]
	v_pk_mul_f32 v[186:187], v[112:113], s[84:85] op_sel:[1,1] op_sel_hi:[0,1]
	v_pk_fma_f32 v[112:113], v[112:113], s[84:85], v[186:187] op_sel_hi:[1,0,1] neg_hi:[0,0,1]
	v_pk_mul_f32 v[188:189], v[128:129], s[90:91] op_sel:[1,1] op_sel_hi:[0,1]
	v_pk_fma_f32 v[128:129], v[128:129], s[90:91], v[188:189] op_sel_hi:[1,0,1] neg_hi:[0,0,1]
	v_pk_mul_f32 v[168:169], v[114:115], s[88:89] op_sel:[1,1] op_sel_hi:[0,1]
	v_pk_fma_f32 v[114:115], v[114:115], s[88:89], v[168:169] op_sel_hi:[1,0,1] neg_hi:[0,0,1]
	v_pk_mul_f32 v[180:181], v[122:123], s[90:91] op_sel:[1,1] op_sel_hi:[0,1]
	v_pk_fma_f32 v[122:123], v[122:123], s[90:91], v[180:181] op_sel_hi:[1,0,1] neg_hi:[0,0,1]
	v_pk_mul_f32 v[126:127], v[130:131], s[98:99] op_sel:[1,1] op_sel_hi:[0,1]
	v_pk_fma_f32 v[130:131], v[130:131], s[98:99], v[126:127] op_sel_hi:[1,0,1] neg_hi:[0,0,1]
	v_pk_add_f32 v[118:119], v[100:101], v[116:117]
	v_pk_add_f32 v[182:183], v[100:101], v[116:117] neg_lo:[0,1] neg_hi:[0,1]
	v_pk_add_f32 v[110:111], v[108:109], v[124:125]
	v_pk_add_f32 v[102:103], v[108:109], v[124:125] neg_lo:[0,1] neg_hi:[0,1]
	v_pk_add_f32 v[100:101], v[118:119], v[110:111]
	v_pk_add_f32 v[116:117], v[118:119], v[110:111] neg_lo:[0,1] neg_hi:[0,1]
	v_pk_add_f32 v[108:109], v[182:183], v[102:103] op_sel:[0,1] op_sel_hi:[1,0] neg_lo:[0,1]
	v_pk_add_f32 v[124:125], v[182:183], v[102:103] op_sel:[0,1] op_sel_hi:[1,0] neg_hi:[0,1]
	v_pk_add_f32 v[184:185], v[178:179], v[166:167]
	v_pk_add_f32 v[186:187], v[178:179], v[166:167] neg_lo:[0,1] neg_hi:[0,1]
	v_pk_add_f32 v[188:189], v[176:177], v[174:175]
	v_pk_add_f32 v[168:169], v[176:177], v[174:175] neg_lo:[0,1] neg_hi:[0,1]
	v_pk_add_f32 v[178:179], v[184:185], v[188:189]
	v_pk_add_f32 v[166:167], v[184:185], v[188:189] neg_lo:[0,1] neg_hi:[0,1]
	v_pk_add_f32 v[176:177], v[186:187], v[168:169] op_sel:[0,1] op_sel_hi:[1,0] neg_lo:[0,1]
	v_pk_add_f32 v[174:175], v[186:187], v[168:169] op_sel:[0,1] op_sel_hi:[1,0] neg_hi:[0,1]
	v_pk_add_f32 v[180:181], v[104:105], v[120:121] op_sel:[0,1] op_sel_hi:[1,0] neg_lo:[0,1]
	v_pk_add_f32 v[126:127], v[104:105], v[120:121] op_sel:[0,1] op_sel_hi:[1,0] neg_hi:[0,1]
	v_pk_add_f32 v[118:119], v[112:113], v[128:129]
	v_pk_add_f32 v[182:183], v[112:113], v[128:129] neg_lo:[0,1] neg_hi:[0,1]
	v_pk_add_f32 v[104:105], v[180:181], v[118:119]
	v_pk_add_f32 v[120:121], v[180:181], v[118:119] neg_lo:[0,1] neg_hi:[0,1]
	v_pk_add_f32 v[112:113], v[126:127], v[182:183] op_sel:[0,1] op_sel_hi:[1,0] neg_lo:[0,1]
	v_pk_add_f32 v[128:129], v[126:127], v[182:183] op_sel:[0,1] op_sel_hi:[1,0] neg_hi:[0,1]
	v_pk_add_f32 v[110:111], v[106:107], v[122:123]
	v_pk_add_f32 v[102:103], v[106:107], v[122:123] neg_lo:[0,1] neg_hi:[0,1]
	v_pk_add_f32 v[184:185], v[114:115], v[130:131]
	v_pk_add_f32 v[186:187], v[114:115], v[130:131] neg_lo:[0,1] neg_hi:[0,1]
	v_pk_add_f32 v[106:107], v[110:111], v[184:185]
	v_pk_add_f32 v[122:123], v[110:111], v[184:185] neg_lo:[0,1] neg_hi:[0,1]
	v_pk_add_f32 v[114:115], v[102:103], v[186:187] op_sel:[0,1] op_sel_hi:[1,0] neg_lo:[0,1]
	v_pk_add_f32 v[130:131], v[102:103], v[186:187] op_sel:[0,1] op_sel_hi:[1,0] neg_hi:[0,1]
	ds_write_b64 v5, v[100:101]
	ds_write_b64 v5, v[178:179] offset:264
	ds_write_b64 v5, v[104:105] offset:528
	ds_write_b64 v5, v[106:107] offset:792
	ds_write_b64 v5, v[108:109] offset:1056
	ds_write_b64 v5, v[176:177] offset:1320
	ds_write_b64 v5, v[112:113] offset:1584
	ds_write_b64 v5, v[114:115] offset:1848
	ds_write_b64 v5, v[116:117] offset:2112
	ds_write_b64 v5, v[166:167] offset:2376
	ds_write_b64 v5, v[120:121] offset:2640
	ds_write_b64 v5, v[122:123] offset:2904
	ds_write_b64 v5, v[124:125] offset:3168
	ds_write_b64 v5, v[174:175] offset:3432
	ds_write_b64 v5, v[128:129] offset:3696
	ds_write_b64 v5, v[130:131] offset:3960
	s_waitcnt lgkmcnt(0)
	s_barrier
; #define LAS __attribute__((address_space(3)))
; __device__ __forceinline__ f32x2 cmulc(f32x2 a, f32x2 b) { return (f32x2){a.x * b.x + a.y * b.y, a.y * b.x - a.x * b.y}; }
; __device__ __forceinline__ void dft16_inv_lo(f32x2 (&x)[16]) {
;     constexpr float C1 = 0.92387953251128674f, S1 = 0.38268343236508977f, C2 = 0.70710678118654752f;
; #pragma unroll
;     for (int b = 0; b < 4; ++b) dft4<true>(x[b], x[4 + b], x[8 + b], x[12 + b]);
;     const f32x2 w1 = {C1, -S1}, w2 = {C2, -C2}, w3 = {S1, -C1}, w4 = {0.f, -1.f}, w6 = {-C2, -C2}, w9 = {-C1, S1};
;     x[5] = cmulc(x[5], w1); x[6] = cmulc(x[6], w2); x[7] = cmulc(x[7], w3);
;     x[9] = cmulc(x[9], w2); x[10] = cmulc(x[10], w4); x[11] = cmulc(x[11], w6);
;     x[13] = cmulc(x[13], w3); x[14] = cmulc(x[14], w6); x[15] = cmulc(x[15], w9);
;     f32x2 y[8];
; #pragma unroll
;     for (int c = 0; c < 4; ++c) { const f32x2 t0 = x[4 * c] + x[4 * c + 2], t1 = x[4 * c] - x[4 * c + 2], t2 = x[4 * c + 1] + x[4 * c + 3], t3 = x[4 * c + 1] - x[4 * c + 3];
;         y[c] = t0 + t2; y[4 + c] = t1 + (f32x2){-t3.y, t3.x}; }
; #pragma unroll
;     for (int k = 0; k < 8; ++k) x[k] = y[k];
; }
; __device__ __forceinline__ void fft_inv1(f32x2 (&x)[16], const LAS f32x2* B, int n2, const f32x2 (&w)[16]) {
;     asm volatile("" : "+v"(n2));
;     x[0] = B[fpad(n2)];
; #pragma unroll
;     for (int k = 1; k < 16; ++k) x[k] = cmulc(B[fpad(512 * k + n2)], w[k]);
;     dft16_inv_lo(x);
; }
	ds_read_b64 v[100:101], v3
	ds_read_b64 v[108:109], v3 offset:16896
	ds_read_b64 v[116:117], v3 offset:33792
	ds_read_b64 v[124:125], v3 offset:50688
	ds_read_b64 v[178:179], v3 offset:4224
	ds_read_b64 v[176:177], v3 offset:21120
	ds_read_b64 v[166:167], v3 offset:38016
	ds_read_b64 v[174:175], v3 offset:54912
	ds_read_b64 v[104:105], v3 offset:8448
	ds_read_b64 v[112:113], v3 offset:25344
	ds_read_b64 v[120:121], v3 offset:42240
	ds_read_b64 v[128:129], v3 offset:59136
	ds_read_b64 v[106:107], v3 offset:12672
	ds_read_b64 v[114:115], v3 offset:29568
	ds_read_b64 v[122:123], v3 offset:46464
	ds_read_b64 v[130:131], v3 offset:63360
	s_waitcnt lgkmcnt(14)
	v_pk_mul_f32 v[188:189], v[108:109], v[12:13] op_sel:[1,1] op_sel_hi:[0,1]
	v_pk_fma_f32 v[108:109], v[108:109], v[12:13], v[188:189] op_sel_hi:[1,0,1] neg_hi:[0,0,1]
	s_waitcnt lgkmcnt(13)
	v_pk_mul_f32 v[168:169], v[116:117], v[20:21] op_sel:[1,1] op_sel_hi:[0,1]
	v_pk_fma_f32 v[116:117], v[116:117], v[20:21], v[168:169] op_sel_hi:[1,0,1] neg_hi:[0,0,1]
	s_waitcnt lgkmcnt(12)
	v_pk_mul_f32 v[180:181], v[124:125], v[28:29] op_sel:[1,1] op_sel_hi:[0,1]
	v_pk_fma_f32 v[124:125], v[124:125], v[28:29], v[180:181] op_sel_hi:[1,0,1] neg_hi:[0,0,1]
	s_waitcnt lgkmcnt(11)
	v_pk_mul_f32 v[126:127], v[178:179], v[6:7] op_sel:[1,1] op_sel_hi:[0,1]
	v_pk_fma_f32 v[178:179], v[178:179], v[6:7], v[126:127] op_sel_hi:[1,0,1] neg_hi:[0,0,1]
	s_waitcnt lgkmcnt(10)
	v_pk_mul_f32 v[118:119], v[176:177], v[14:15] op_sel:[1,1] op_sel_hi:[0,1]
	v_pk_fma_f32 v[176:177], v[176:177], v[14:15], v[118:119] op_sel_hi:[1,0,1] neg_hi:[0,0,1]
	s_waitcnt lgkmcnt(9)
	v_pk_mul_f32 v[182:183], v[166:167], v[22:23] op_sel:[1,1] op_sel_hi:[0,1]
	v_pk_fma_f32 v[166:167], v[166:167], v[22:23], v[182:183] op_sel_hi:[1,0,1] neg_hi:[0,0,1]
	s_waitcnt lgkmcnt(8)
	v_pk_mul_f32 v[110:111], v[174:175], v[30:31] op_sel:[1,1] op_sel_hi:[0,1]
	v_pk_fma_f32 v[174:175], v[174:175], v[30:31], v[110:111] op_sel_hi:[1,0,1] neg_hi:[0,0,1]
	s_waitcnt lgkmcnt(7)
	v_pk_mul_f32 v[102:103], v[104:105], v[8:9] op_sel:[1,1] op_sel_hi:[0,1]
	v_pk_fma_f32 v[104:105], v[104:105], v[8:9], v[102:103] op_sel_hi:[1,0,1] neg_hi:[0,0,1]
	s_waitcnt lgkmcnt(6)
	v_pk_mul_f32 v[184:185], v[112:113], v[16:17] op_sel:[1,1] op_sel_hi:[0,1]
	v_pk_fma_f32 v[112:113], v[112:113], v[16:17], v[184:185] op_sel_hi:[1,0,1] neg_hi:[0,0,1]
	s_waitcnt lgkmcnt(5)
	v_pk_mul_f32 v[186:187], v[120:121], v[24:25] op_sel:[1,1] op_sel_hi:[0,1]
	v_pk_fma_f32 v[120:121], v[120:121], v[24:25], v[186:187] op_sel_hi:[1,0,1] neg_hi:[0,0,1]
	s_waitcnt lgkmcnt(4)
	v_pk_mul_f32 v[188:189], v[128:129], v[32:33] op_sel:[1,1] op_sel_hi:[0,1]
	v_pk_fma_f32 v[128:129], v[128:129], v[32:33], v[188:189] op_sel_hi:[1,0,1] neg_hi:[0,0,1]
	s_waitcnt lgkmcnt(3)
	v_pk_mul_f32 v[168:169], v[106:107], v[10:11] op_sel:[1,1] op_sel_hi:[0,1]
	v_pk_fma_f32 v[106:107], v[106:107], v[10:11], v[168:169] op_sel_hi:[1,0,1] neg_hi:[0,0,1]
	s_waitcnt lgkmcnt(2)
	v_pk_mul_f32 v[180:181], v[114:115], v[18:19] op_sel:[1,1] op_sel_hi:[0,1]
	v_pk_fma_f32 v[114:115], v[114:115], v[18:19], v[180:181] op_sel_hi:[1,0,1] neg_hi:[0,0,1]
	s_waitcnt lgkmcnt(1)
	v_pk_mul_f32 v[126:127], v[122:123], v[26:27] op_sel:[1,1] op_sel_hi:[0,1]
	v_pk_fma_f32 v[122:123], v[122:123], v[26:27], v[126:127] op_sel_hi:[1,0,1] neg_hi:[0,0,1]
	s_waitcnt lgkmcnt(0)
	v_pk_mul_f32 v[118:119], v[130:131], v[34:35] op_sel:[1,1] op_sel_hi:[0,1]
	v_pk_fma_f32 v[130:131], v[130:131], v[34:35], v[118:119] op_sel_hi:[1,0,1] neg_hi:[0,0,1]
	v_pk_add_f32 v[182:183], v[100:101], v[116:117]
	v_pk_add_f32 v[110:111], v[100:101], v[116:117] neg_lo:[0,1] neg_hi:[0,1]
	v_pk_add_f32 v[102:103], v[108:109], v[124:125]
	v_pk_add_f32 v[184:185], v[108:109], v[124:125] neg_lo:[0,1] neg_hi:[0,1]
	v_pk_add_f32 v[100:101], v[182:183], v[102:103]
	v_pk_add_f32 v[116:117], v[182:183], v[102:103] neg_lo:[0,1] neg_hi:[0,1]
	v_pk_add_f32 v[108:109], v[110:111], v[184:185] op_sel:[0,1] op_sel_hi:[1,0] neg_lo:[0,1]
	v_pk_add_f32 v[124:125], v[110:111], v[184:185] op_sel:[0,1] op_sel_hi:[1,0] neg_hi:[0,1]
	v_pk_add_f32 v[186:187], v[178:179], v[166:167]
	v_pk_add_f32 v[188:189], v[178:179], v[166:167] neg_lo:[0,1] neg_hi:[0,1]
	v_pk_add_f32 v[168:169], v[176:177], v[174:175]
	v_pk_add_f32 v[180:181], v[176:177], v[174:175] neg_lo:[0,1] neg_hi:[0,1]
	v_pk_add_f32 v[178:179], v[186:187], v[168:169]
	v_pk_add_f32 v[166:167], v[186:187], v[168:169] neg_lo:[0,1] neg_hi:[0,1]
	v_pk_add_f32 v[176:177], v[188:189], v[180:181] op_sel:[0,1] op_sel_hi:[1,0] neg_lo:[0,1]
	v_pk_add_f32 v[174:175], v[188:189], v[180:181] op_sel:[0,1] op_sel_hi:[1,0] neg_hi:[0,1]
	v_pk_add_f32 v[126:127], v[104:105], v[120:121]
	v_pk_add_f32 v[118:119], v[104:105], v[120:121] neg_lo:[0,1] neg_hi:[0,1]
	v_pk_add_f32 v[182:183], v[112:113], v[128:129]
	v_pk_add_f32 v[110:111], v[112:113], v[128:129] neg_lo:[0,1] neg_hi:[0,1]
	v_pk_add_f32 v[104:105], v[126:127], v[182:183]
	v_pk_add_f32 v[120:121], v[126:127], v[182:183] neg_lo:[0,1] neg_hi:[0,1]
	v_pk_add_f32 v[112:113], v[118:119], v[110:111] op_sel:[0,1] op_sel_hi:[1,0] neg_lo:[0,1]
	v_pk_add_f32 v[128:129], v[118:119], v[110:111] op_sel:[0,1] op_sel_hi:[1,0] neg_hi:[0,1]
	v_pk_add_f32 v[102:103], v[106:107], v[122:123]
	v_pk_add_f32 v[184:185], v[106:107], v[122:123] neg_lo:[0,1] neg_hi:[0,1]
	v_pk_add_f32 v[186:187], v[114:115], v[130:131]
	v_pk_add_f32 v[188:189], v[114:115], v[130:131] neg_lo:[0,1] neg_hi:[0,1]
	v_pk_add_f32 v[106:107], v[102:103], v[186:187]
	v_pk_add_f32 v[122:123], v[102:103], v[186:187] neg_lo:[0,1] neg_hi:[0,1]
	v_pk_add_f32 v[114:115], v[184:185], v[188:189] op_sel:[0,1] op_sel_hi:[1,0] neg_lo:[0,1]
; #define LAS __attribute__((address_space(3)))
; #define WG_SYNC() do { asm volatile("s_waitcnt lgkmcnt(0)" ::: "memory"); __builtin_amdgcn_s_barrier(); asm volatile("" ::: "memory"); } while (0)
; __device__ __forceinline__ void hy_stage(LAS float* plane, const bf16_t* PHY, int cg, int jc, int tid) {
;     asm volatile("" : "+v"(tid));
;     const u32x4* src = (const u32x4*)(PHY + (size_t)cg * MT * 4);
; #pragma unroll
;     for (int k = 0; k < 8; ++k) { const int i = tid + 512 * k; const u32x4 v = src[i];
;         const unsigned w0 = (jc & 2) ? v.y : v.x, w1 = (jc & 2) ? v.w : v.z;
;         f32x2 o; o.x = (jc & 1) ? bf_hi(w0) : bf_lo(w0); o.y = (jc & 1) ? bf_hi(w1) : bf_lo(w1);
;         *(LAS f32x2*)(plane + 2 * i) = o; }
; }
; __device__ __forceinline__ void hyena_fft(LAS unsigned char* lds, int layer, int G, const int wave_s) {
;     ...
;             WG_SYNC(); fft_inv1(x, Db, n2, w1p);
;             { const float fb0 = fbias[c];
; #pragma unroll
;               for (int r = 0; r < 8; ++r) { uz[r][0] = ux[r][0] * (x[r].x + fb0 * uz[r][0]); uz[r][1] = ux[r][1] * (x[r].y + fb0 * uz[r][1]); } }
;             WG_SYNC();
;             hy_stage(pl0, PHY, (HY / 4) + unit, jc, tid);
;             WG_SYNC();
	v_pk_add_f32 v[130:131], v[184:185], v[188:189] op_sel:[0,1] op_sel_hi:[1,0] neg_hi:[0,1]
	v_pk_mul_f32 v[168:169], v[176:177], s[68:69] op_sel:[1,1] op_sel_hi:[0,1]
	v_pk_fma_f32 v[176:177], v[176:177], s[68:69], v[168:169] op_sel_hi:[1,0,1] neg_hi:[0,0,1]
	v_pk_mul_f32 v[180:181], v[112:113], s[84:85] op_sel:[1,1] op_sel_hi:[0,1]
	v_pk_fma_f32 v[112:113], v[112:113], s[84:85], v[180:181] op_sel_hi:[1,0,1] neg_hi:[0,0,1]
	v_pk_mul_f32 v[126:127], v[114:115], s[88:89] op_sel:[1,1] op_sel_hi:[0,1]
	v_pk_fma_f32 v[114:115], v[114:115], s[88:89], v[126:127] op_sel_hi:[1,0,1] neg_hi:[0,0,1]
	v_pk_mul_f32 v[118:119], v[166:167], s[84:85] op_sel:[1,1] op_sel_hi:[0,1]
	v_pk_fma_f32 v[166:167], v[166:167], s[84:85], v[118:119] op_sel_hi:[1,0,1] neg_hi:[0,0,1]
	v_pk_mul_f32 v[182:183], v[122:123], s[90:91] op_sel:[1,1] op_sel_hi:[0,1]
	v_pk_fma_f32 v[122:123], v[122:123], s[90:91], v[182:183] op_sel_hi:[1,0,1] neg_hi:[0,0,1]
	v_pk_mul_f32 v[110:111], v[174:175], s[88:89] op_sel:[1,1] op_sel_hi:[0,1]
	v_pk_fma_f32 v[174:175], v[174:175], s[88:89], v[110:111] op_sel_hi:[1,0,1] neg_hi:[0,0,1]
	v_pk_mul_f32 v[102:103], v[128:129], s[90:91] op_sel:[1,1] op_sel_hi:[0,1]
	v_pk_fma_f32 v[128:129], v[128:129], s[90:91], v[102:103] op_sel_hi:[1,0,1] neg_hi:[0,0,1]
	v_pk_mul_f32 v[184:185], v[130:131], s[98:99] op_sel:[1,1] op_sel_hi:[0,1]
	v_pk_fma_f32 v[130:131], v[130:131], s[98:99], v[184:185] op_sel_hi:[1,0,1] neg_hi:[0,0,1]
	v_pk_add_f32 v[186:187], v[100:101], v[104:105]
	v_pk_add_f32 v[188:189], v[100:101], v[104:105] neg_lo:[0,1] neg_hi:[0,1]
	v_pk_add_f32 v[168:169], v[178:179], v[106:107]
	v_pk_add_f32 v[180:181], v[178:179], v[106:107] neg_lo:[0,1] neg_hi:[0,1]
	v_pk_add_f32 v[100:101], v[186:187], v[168:169]
	v_pk_add_f32 v[178:179], v[188:189], v[180:181] op_sel:[0,1] op_sel_hi:[1,0] neg_lo:[0,1]
	v_pk_add_f32 v[126:127], v[108:109], v[112:113]
	v_pk_add_f32 v[118:119], v[108:109], v[112:113] neg_lo:[0,1] neg_hi:[0,1]
	v_pk_add_f32 v[182:183], v[176:177], v[114:115]
	v_pk_add_f32 v[110:111], v[176:177], v[114:115] neg_lo:[0,1] neg_hi:[0,1]
	v_pk_add_f32 v[108:109], v[126:127], v[182:183]
	v_pk_add_f32 v[176:177], v[118:119], v[110:111] op_sel:[0,1] op_sel_hi:[1,0] neg_lo:[0,1]
	v_pk_add_f32 v[102:103], v[116:117], v[120:121] op_sel:[0,1] op_sel_hi:[1,0] neg_lo:[0,1]
	v_pk_add_f32 v[184:185], v[116:117], v[120:121] op_sel:[0,1] op_sel_hi:[1,0] neg_hi:[0,1]
	v_pk_add_f32 v[186:187], v[166:167], v[122:123]
	v_pk_add_f32 v[188:189], v[166:167], v[122:123] neg_lo:[0,1] neg_hi:[0,1]
	v_pk_add_f32 v[116:117], v[102:103], v[186:187]
	v_pk_add_f32 v[166:167], v[184:185], v[188:189] op_sel:[0,1] op_sel_hi:[1,0] neg_lo:[0,1]
	v_pk_add_f32 v[168:169], v[124:125], v[128:129]
	v_pk_add_f32 v[180:181], v[124:125], v[128:129] neg_lo:[0,1] neg_hi:[0,1]
	v_pk_add_f32 v[126:127], v[174:175], v[130:131]
	v_pk_add_f32 v[118:119], v[174:175], v[130:131] neg_lo:[0,1] neg_hi:[0,1]
	v_pk_add_f32 v[124:125], v[168:169], v[126:127]
	v_pk_add_f32 v[174:175], v[180:181], v[118:119] op_sel:[0,1] op_sel_hi:[1,0] neg_lo:[0,1]
	s_load_dword s35, s[50:51], 0x0
	s_waitcnt lgkmcnt(0)
	v_mov_b32_e32 v194, s35
	v_pk_fma_f32 v[182:183], v[132:133], v[194:195], v[100:101] op_sel_hi:[1,0,1]
	v_pk_mul_f32 v[132:133], v[148:149], v[182:183]
	v_pk_fma_f32 v[110:111], v[134:135], v[194:195], v[108:109] op_sel_hi:[1,0,1]
	v_pk_mul_f32 v[134:135], v[150:151], v[110:111]
	v_pk_fma_f32 v[102:103], v[136:137], v[194:195], v[116:117] op_sel_hi:[1,0,1]
	v_pk_mul_f32 v[136:137], v[152:153], v[102:103]
	v_pk_fma_f32 v[184:185], v[138:139], v[194:195], v[124:125] op_sel_hi:[1,0,1]
	v_pk_mul_f32 v[138:139], v[154:155], v[184:185]
	v_pk_fma_f32 v[186:187], v[140:141], v[194:195], v[178:179] op_sel_hi:[1,0,1]
	v_pk_mul_f32 v[140:141], v[158:159], v[186:187]
	v_pk_fma_f32 v[188:189], v[142:143], v[194:195], v[176:177] op_sel_hi:[1,0,1]
	v_pk_mul_f32 v[142:143], v[160:161], v[188:189]
	v_pk_fma_f32 v[168:169], v[144:145], v[194:195], v[166:167] op_sel_hi:[1,0,1]
	v_pk_mul_f32 v[144:145], v[162:163], v[168:169]
	v_pk_fma_f32 v[180:181], v[146:147], v[194:195], v[174:175] op_sel_hi:[1,0,1]
	v_pk_mul_f32 v[146:147], v[164:165], v[180:181]
	s_waitcnt lgkmcnt(0)
	s_barrier
	s_waitcnt vmcnt(7)
	v_perm_b32 v126, 0, v58, s15
	v_perm_b32 v127, 0, v60, s15
	ds_write_b64 v206, v[126:127]
	s_waitcnt vmcnt(6)
	v_perm_b32 v118, 0, v62, s15
	v_perm_b32 v119, 0, v64, s15
	ds_write_b64 v206, v[118:119] offset:4096
	s_waitcnt vmcnt(5)
	v_perm_b32 v182, 0, v66, s15
	v_perm_b32 v183, 0, v68, s15
	ds_write_b64 v206, v[182:183] offset:8192
	s_waitcnt vmcnt(4)
	v_perm_b32 v110, 0, v70, s15
	v_perm_b32 v111, 0, v72, s15
	ds_write_b64 v206, v[110:111] offset:12288
	s_waitcnt vmcnt(3)
	v_perm_b32 v102, 0, v74, s15
	v_perm_b32 v103, 0, v76, s15
	ds_write_b64 v206, v[102:103] offset:16384
	s_waitcnt vmcnt(2)
	v_perm_b32 v184, 0, v78, s15
	v_perm_b32 v185, 0, v80, s15
	ds_write_b64 v206, v[184:185] offset:20480
	s_waitcnt vmcnt(1)
	v_perm_b32 v186, 0, v82, s15
	v_perm_b32 v187, 0, v84, s15
	ds_write_b64 v206, v[186:187] offset:24576
	s_waitcnt vmcnt(0)
	v_perm_b32 v188, 0, v86, s15
	v_perm_b32 v189, 0, v88, s15
	ds_write_b64 v206, v[188:189] offset:28672
	s_waitcnt lgkmcnt(0)
	s_barrier
; #define LAS __attribute__((address_space(3)))
; #define WG_SYNC() do { asm volatile("s_waitcnt lgkmcnt(0)" ::: "memory"); __builtin_amdgcn_s_barrier(); asm volatile("" ::: "memory"); } while (0)
; __device__ __forceinline__ void hy_sconv(const LAS float* plane, float w0, float w1, float w2, float cb, int n2, float (&u)[8][2]) {
;     asm volatile("" : "+v"(n2));
; #pragma unroll
;     for (int r = 0; r < 8; ++r)
; #pragma unroll
;         for (int b = 0; b < 2; ++b) { const int t = n2 + 512 * r, row = b * SEQ + t;
;             float a = cb + w1 * plane[row];
;             if (t > 0) a += w0 * plane[row - 1];
;             if (t < SEQ - 1) a += w2 * plane[row + 1];
;             u[r][b] = a; }
; }
; __device__ __forceinline__ void hyena_fft(LAS unsigned char* lds, int layer, int G, const int wave_s) {
;     ...
;             hy_stage(pl0, PHY, (HY / 4) + unit, jc, tid);
;             WG_SYNC();
;             hy_sconv(pl0, cw[HY + c], cw[3 * HY + HY + c], cw[6 * HY + HY + c], cb[HY + c], n2, ux);
;             WG_SYNC();
	v_mov_b32_e32 v168, s17
	v_mov_b32_e32 v169, s23
	v_mov_b32_e32 v180, s25
	v_mov_b32_e32 v181, s26
	ds_read_b32 v126, v208
	ds_read_b32 v118, v210
	ds_read_b32 v182, v208 offset:4
	ds_read_b32 v127, v208 offset:16384
	ds_read_b32 v119, v210 offset:16384
	ds_read_b32 v183, v208 offset:16388
	ds_read_b32 v110, v208 offset:2048
	ds_read_b32 v102, v208 offset:2044
	ds_read_b32 v184, v208 offset:2052
	ds_read_b32 v111, v208 offset:18432
	ds_read_b32 v103, v208 offset:18428
	ds_read_b32 v185, v208 offset:18436
	s_waitcnt lgkmcnt(10)
	v_cndmask_b32_e64 v118, v118, 0, s[10:11]
	s_waitcnt lgkmcnt(7)
	v_cndmask_b32_e64 v119, v119, 0, s[10:11]
	v_pk_fma_f32 v[148:149], v[168:169], v[126:127], v[180:181] op_sel:[1,0,1]
	v_pk_fma_f32 v[148:149], v[168:169], v[118:119], v[148:149] op_sel_hi:[0,1,1]
	s_waitcnt lgkmcnt(6)
	v_pk_fma_f32 v[148:149], v[180:181], v[182:183], v[148:149] op_sel_hi:[0,1,1]
	s_waitcnt lgkmcnt(2)
	v_pk_fma_f32 v[150:151], v[168:169], v[110:111], v[180:181] op_sel:[1,0,1]
	s_waitcnt lgkmcnt(1)
	v_pk_fma_f32 v[150:151], v[168:169], v[102:103], v[150:151] op_sel_hi:[0,1,1]
	s_waitcnt lgkmcnt(0)
	v_pk_fma_f32 v[150:151], v[180:181], v[184:185], v[150:151] op_sel_hi:[0,1,1]
	ds_read_b32 v186, v208 offset:4096
	ds_read_b32 v188, v208 offset:4092
	ds_read_b32 v126, v208 offset:4100
	ds_read_b32 v187, v208 offset:20480
	ds_read_b32 v189, v208 offset:20476
	ds_read_b32 v127, v208 offset:20484
	ds_read_b32 v118, v208 offset:6144
	ds_read_b32 v182, v208 offset:6140
	ds_read_b32 v110, v208 offset:6148
	ds_read_b32 v119, v208 offset:22528
	ds_read_b32 v183, v208 offset:22524
	ds_read_b32 v111, v208 offset:22532
	s_waitcnt lgkmcnt(8)
	v_pk_fma_f32 v[152:153], v[168:169], v[186:187], v[180:181] op_sel:[1,0,1]
	s_waitcnt lgkmcnt(7)
	v_pk_fma_f32 v[152:153], v[168:169], v[188:189], v[152:153] op_sel_hi:[0,1,1]
	s_waitcnt lgkmcnt(6)
	v_pk_fma_f32 v[152:153], v[180:181], v[126:127], v[152:153] op_sel_hi:[0,1,1]
	s_waitcnt lgkmcnt(2)
	v_pk_fma_f32 v[154:155], v[168:169], v[118:119], v[180:181] op_sel:[1,0,1]
	s_waitcnt lgkmcnt(1)
	v_pk_fma_f32 v[154:155], v[168:169], v[182:183], v[154:155] op_sel_hi:[0,1,1]
	s_waitcnt lgkmcnt(0)
	v_pk_fma_f32 v[154:155], v[180:181], v[110:111], v[154:155] op_sel_hi:[0,1,1]
	ds_read_b32 v102, v208 offset:8192
	ds_read_b32 v184, v208 offset:8188
	ds_read_b32 v186, v208 offset:8196
	ds_read_b32 v103, v208 offset:24576
	ds_read_b32 v185, v208 offset:24572
	ds_read_b32 v187, v208 offset:24580
	ds_read_b32 v188, v208 offset:10240
	ds_read_b32 v126, v208 offset:10236
	ds_read_b32 v118, v208 offset:10244
	ds_read_b32 v189, v208 offset:26624
	ds_read_b32 v127, v208 offset:26620
	ds_read_b32 v119, v208 offset:26628
	s_waitcnt lgkmcnt(8)
	v_pk_fma_f32 v[158:159], v[168:169], v[102:103], v[180:181] op_sel:[1,0,1]
	s_waitcnt lgkmcnt(7)
	v_pk_fma_f32 v[158:159], v[168:169], v[184:185], v[158:159] op_sel_hi:[0,1,1]
	s_waitcnt lgkmcnt(6)
	v_pk_fma_f32 v[158:159], v[180:181], v[186:187], v[158:159] op_sel_hi:[0,1,1]
	s_waitcnt lgkmcnt(2)
	v_pk_fma_f32 v[160:161], v[168:169], v[188:189], v[180:181] op_sel:[1,0,1]
	s_waitcnt lgkmcnt(1)
	v_pk_fma_f32 v[160:161], v[168:169], v[126:127], v[160:161] op_sel_hi:[0,1,1]
	s_waitcnt lgkmcnt(0)
	v_pk_fma_f32 v[160:161], v[180:181], v[118:119], v[160:161] op_sel_hi:[0,1,1]
	ds_read_b32 v182, v208 offset:12288
	ds_read_b32 v110, v208 offset:12284
	ds_read_b32 v102, v208 offset:12292
	ds_read_b32 v183, v208 offset:28672
	ds_read_b32 v111, v208 offset:28668
	ds_read_b32 v103, v208 offset:28676
	ds_read_b32 v184, v208 offset:14336
	ds_read_b32 v186, v208 offset:14332
	ds_read_b32 v188, v208 offset:14340
	ds_read_b32 v185, v208 offset:30720
	ds_read_b32 v187, v208 offset:30716
	ds_read_b32 v189, v208 offset:30724
	s_waitcnt lgkmcnt(8)
	v_pk_fma_f32 v[162:163], v[168:169], v[182:183], v[180:181] op_sel:[1,0,1]
	s_waitcnt lgkmcnt(7)
	v_pk_fma_f32 v[162:163], v[168:169], v[110:111], v[162:163] op_sel_hi:[0,1,1]
	s_waitcnt lgkmcnt(6)
	v_pk_fma_f32 v[162:163], v[180:181], v[102:103], v[162:163] op_sel_hi:[0,1,1]
	s_waitcnt lgkmcnt(3)
	v_cndmask_b32_e64 v188, v188, 0, s[28:29]
	s_waitcnt lgkmcnt(0)
	v_cndmask_b32_e64 v189, v189, 0, s[28:29]
	v_pk_fma_f32 v[164:165], v[168:169], v[184:185], v[180:181] op_sel:[1,0,1]
	v_pk_fma_f32 v[164:165], v[168:169], v[186:187], v[164:165] op_sel_hi:[0,1,1]
	v_pk_fma_f32 v[164:165], v[180:181], v[188:189], v[164:165] op_sel_hi:[0,1,1]
	s_waitcnt lgkmcnt(0)
	s_barrier
	s_add_u32 s43, s80, 1
	s_cmp_ge_i32 s43, s93
	s_cbranch_scc1 .Lhfft_nowarm
	s_add_u32 s60, s46, 0x4000
	s_addc_u32 s61, s47, 0
	s_add_u32 s62, s60, 0x4000000
	s_addc_u32 s63, s61, 0
	v_lshlrev_b32_e32 v69, 5, v0
	global_load_dword v77, v69, s[60:61]
	s_waitcnt vmcnt(0)
	global_load_dword v77, v69, s[62:63]
; __device__ __forceinline__ f32x2 cmul(f32x2 a, f32x2 b) { return (f32x2){a.x * b.x - a.y * b.y, a.x * b.y + a.y * b.x}; }
; #define WG_SYNC() do { asm volatile("s_waitcnt lgkmcnt(0)" ::: "memory"); __builtin_amdgcn_s_barrier(); asm volatile("" ::: "memory"); } while (0)
; __device__ __forceinline__ void dft16_fwd_lo(f32x2 (&x)[16]) {
;     constexpr float C1 = 0.92387953251128674f, S1 = 0.38268343236508977f, C2 = 0.70710678118654752f;
; #pragma unroll
;     for (int b = 0; b < 4; ++b) { const f32x2 x0 = x[b], x1 = x[4 + b]; const f32x2 j1 = {x1.y, -x1.x};
;         x[b] = x0 + x1; x[4 + b] = x0 + j1; x[8 + b] = x0 - x1; x[12 + b] = x0 - j1; }
;     const f32x2 w1 = {C1, -S1}, w2 = {C2, -C2}, w3 = {S1, -C1}, w4 = {0.f, -1.f}, w6 = {-C2, -C2}, w9 = {-C1, S1};
;     x[5] = cmul(x[5], w1); x[6] = cmul(x[6], w2); x[7] = cmul(x[7], w3);
;     x[9] = cmul(x[9], w2); x[10] = cmul(x[10], w4); x[11] = cmul(x[11], w6);
;     x[13] = cmul(x[13], w3); x[14] = cmul(x[14], w6); x[15] = cmul(x[15], w9);
; #pragma unroll
;     for (int c = 0; c < 4; ++c) dft4<false>(x[4 * c], x[4 * c + 1], x[4 * c + 2], x[4 * c + 3]);
;     f32x2 y[16];
; #pragma unroll
;     for (int k = 0; k < 16; ++k) y[k] = x[4 * (k & 3) + (k >> 2)];
; #pragma unroll
;     for (int k = 0; k < 16; ++k) x[k] = y[k];
; }
; __device__ __forceinline__ void hyena_fft(LAS unsigned char* lds, int layer, int G, const int wave_s) {
;     ...
; #pragma unroll
;             for (int r = 0; r < 8; ++r) { x[r] = (f32x2){uz[r][0], uz[r][1]}; x[r + 8] = (f32x2){0.f, 0.f}; }
;             fft_fwd1<true>(x, Db, n2, w1p); WG_SYNC();
.Lhfft_nowarm:
	v_pk_add_f32 v[104:105], v[132:133], v[140:141] neg_lo:[0,1] neg_hi:[0,1]
	v_pk_add_f32 v[106:107], v[132:133], v[140:141] op_sel:[0,1] op_sel_hi:[1,0] neg_lo:[0,1]
	v_pk_add_f32 v[126:127], v[132:133], v[140:141] op_sel:[0,1] op_sel_hi:[1,0] neg_hi:[0,1]
	v_pk_add_f32 v[100:101], v[132:133], v[140:141]
	v_pk_add_f32 v[112:113], v[134:135], v[142:143] neg_lo:[0,1] neg_hi:[0,1]
	v_pk_add_f32 v[114:115], v[134:135], v[142:143] op_sel:[0,1] op_sel_hi:[1,0] neg_lo:[0,1]
	v_pk_add_f32 v[118:119], v[134:135], v[142:143] op_sel:[0,1] op_sel_hi:[1,0] neg_hi:[0,1]
	v_pk_add_f32 v[108:109], v[134:135], v[142:143]
	v_pk_add_f32 v[120:121], v[136:137], v[144:145] neg_lo:[0,1] neg_hi:[0,1]
	v_pk_add_f32 v[122:123], v[136:137], v[144:145] op_sel:[0,1] op_sel_hi:[1,0] neg_lo:[0,1]
	v_pk_add_f32 v[182:183], v[136:137], v[144:145] op_sel:[0,1] op_sel_hi:[1,0] neg_hi:[0,1]
	v_pk_add_f32 v[116:117], v[136:137], v[144:145]
	v_pk_add_f32 v[128:129], v[138:139], v[146:147] neg_lo:[0,1] neg_hi:[0,1]
	v_pk_add_f32 v[130:131], v[138:139], v[146:147] op_sel:[0,1] op_sel_hi:[1,0] neg_lo:[0,1]
	v_pk_add_f32 v[110:111], v[138:139], v[146:147] op_sel:[0,1] op_sel_hi:[1,0] neg_hi:[0,1]
	v_pk_add_f32 v[124:125], v[138:139], v[146:147]
	v_pk_mul_f32 v[102:103], v[118:119], s[68:69] op_sel:[1,1] op_sel_hi:[0,1]
	v_pk_fma_f32 v[118:119], v[118:119], s[68:69], v[102:103] op_sel_hi:[1,0,1] neg_lo:[0,0,1]
	v_pk_mul_f32 v[184:185], v[182:183], s[84:85] op_sel:[1,1] op_sel_hi:[0,1]
	v_pk_fma_f32 v[182:183], v[182:183], s[84:85], v[184:185] op_sel_hi:[1,0,1] neg_lo:[0,0,1]
	v_pk_mul_f32 v[186:187], v[110:111], s[88:89] op_sel:[1,1] op_sel_hi:[0,1]
	v_pk_fma_f32 v[110:111], v[110:111], s[88:89], v[186:187] op_sel_hi:[1,0,1] neg_lo:[0,0,1]
	v_pk_mul_f32 v[188:189], v[112:113], s[84:85] op_sel:[1,1] op_sel_hi:[0,1]
	v_pk_fma_f32 v[112:113], v[112:113], s[84:85], v[188:189] op_sel_hi:[1,0,1] neg_lo:[0,0,1]
	v_pk_mul_f32 v[168:169], v[128:129], s[90:91] op_sel:[1,1] op_sel_hi:[0,1]
	v_pk_fma_f32 v[128:129], v[128:129], s[90:91], v[168:169] op_sel_hi:[1,0,1] neg_lo:[0,0,1]
	v_pk_mul_f32 v[180:181], v[114:115], s[88:89] op_sel:[1,1] op_sel_hi:[0,1]
	v_pk_fma_f32 v[114:115], v[114:115], s[88:89], v[180:181] op_sel_hi:[1,0,1] neg_lo:[0,0,1]
	v_pk_mul_f32 v[178:179], v[122:123], s[90:91] op_sel:[1,1] op_sel_hi:[0,1]
	v_pk_fma_f32 v[122:123], v[122:123], s[90:91], v[178:179] op_sel_hi:[1,0,1] neg_lo:[0,0,1]
	v_pk_mul_f32 v[176:177], v[130:131], s[98:99] op_sel:[1,1] op_sel_hi:[0,1]
	v_pk_fma_f32 v[130:131], v[130:131], s[98:99], v[176:177] op_sel_hi:[1,0,1] neg_lo:[0,0,1]
	v_pk_add_f32 v[166:167], v[100:101], v[116:117]
	v_pk_add_f32 v[174:175], v[100:101], v[116:117] neg_lo:[0,1] neg_hi:[0,1]
	v_pk_add_f32 v[102:103], v[108:109], v[124:125]
	v_pk_add_f32 v[184:185], v[108:109], v[124:125] neg_lo:[0,1] neg_hi:[0,1]
	v_pk_add_f32 v[100:101], v[166:167], v[102:103]
	v_pk_add_f32 v[116:117], v[166:167], v[102:103] neg_lo:[0,1] neg_hi:[0,1]
	v_pk_add_f32 v[108:109], v[174:175], v[184:185] op_sel:[0,1] op_sel_hi:[1,0] neg_hi:[0,1]
	v_pk_add_f32 v[124:125], v[174:175], v[184:185] op_sel:[0,1] op_sel_hi:[1,0] neg_lo:[0,1]
	v_pk_add_f32 v[186:187], v[126:127], v[182:183]
	v_pk_add_f32 v[188:189], v[126:127], v[182:183] neg_lo:[0,1] neg_hi:[0,1]
	v_pk_add_f32 v[168:169], v[118:119], v[110:111]
	v_pk_add_f32 v[180:181], v[118:119], v[110:111] neg_lo:[0,1] neg_hi:[0,1]
	v_pk_add_f32 v[126:127], v[186:187], v[168:169]
	v_pk_add_f32 v[182:183], v[186:187], v[168:169] neg_lo:[0,1] neg_hi:[0,1]
	v_pk_add_f32 v[118:119], v[188:189], v[180:181] op_sel:[0,1] op_sel_hi:[1,0] neg_hi:[0,1]
	v_pk_add_f32 v[110:111], v[188:189], v[180:181] op_sel:[0,1] op_sel_hi:[1,0] neg_lo:[0,1]
	v_pk_add_f32 v[178:179], v[104:105], v[120:121] op_sel:[0,1] op_sel_hi:[1,0] neg_hi:[0,1]
	v_pk_add_f32 v[176:177], v[104:105], v[120:121] op_sel:[0,1] op_sel_hi:[1,0] neg_lo:[0,1]
	v_pk_add_f32 v[166:167], v[112:113], v[128:129]
	v_pk_add_f32 v[174:175], v[112:113], v[128:129] neg_lo:[0,1] neg_hi:[0,1]
	v_pk_add_f32 v[104:105], v[178:179], v[166:167]
	v_pk_add_f32 v[120:121], v[178:179], v[166:167] neg_lo:[0,1] neg_hi:[0,1]
	v_pk_add_f32 v[112:113], v[176:177], v[174:175] op_sel:[0,1] op_sel_hi:[1,0] neg_hi:[0,1]
	v_pk_add_f32 v[128:129], v[176:177], v[174:175] op_sel:[0,1] op_sel_hi:[1,0] neg_lo:[0,1]
	v_pk_add_f32 v[102:103], v[106:107], v[122:123]
	v_pk_add_f32 v[184:185], v[106:107], v[122:123] neg_lo:[0,1] neg_hi:[0,1]
	v_pk_add_f32 v[186:187], v[114:115], v[130:131]
	v_pk_add_f32 v[188:189], v[114:115], v[130:131] neg_lo:[0,1] neg_hi:[0,1]
	v_pk_add_f32 v[106:107], v[102:103], v[186:187]
	v_pk_add_f32 v[122:123], v[102:103], v[186:187] neg_lo:[0,1] neg_hi:[0,1]
	v_pk_add_f32 v[114:115], v[184:185], v[188:189] op_sel:[0,1] op_sel_hi:[1,0] neg_hi:[0,1]
	v_pk_add_f32 v[130:131], v[184:185], v[188:189] op_sel:[0,1] op_sel_hi:[1,0] neg_lo:[0,1]
	ds_write_b64 v3, v[100:101]
	v_pk_mul_f32 v[180:181], v[126:127], v[6:7] op_sel:[1,1] op_sel_hi:[0,1]
	v_pk_fma_f32 v[168:169], v[126:127], v[6:7], v[180:181] op_sel_hi:[1,0,1] neg_lo:[0,0,1]
	ds_write_b64 v3, v[168:169] offset:4224
	v_pk_mul_f32 v[176:177], v[104:105], v[8:9] op_sel:[1,1] op_sel_hi:[0,1]
	v_pk_fma_f32 v[178:179], v[104:105], v[8:9], v[176:177] op_sel_hi:[1,0,1] neg_lo:[0,0,1]
	ds_write_b64 v3, v[178:179] offset:8448
	v_pk_mul_f32 v[174:175], v[106:107], v[10:11] op_sel:[1,1] op_sel_hi:[0,1]
	v_pk_fma_f32 v[166:167], v[106:107], v[10:11], v[174:175] op_sel_hi:[1,0,1] neg_lo:[0,0,1]
	ds_write_b64 v3, v[166:167] offset:12672
	v_pk_mul_f32 v[184:185], v[108:109], v[12:13] op_sel:[1,1] op_sel_hi:[0,1]
	v_pk_fma_f32 v[102:103], v[108:109], v[12:13], v[184:185] op_sel_hi:[1,0,1] neg_lo:[0,0,1]
; #define LAS __attribute__((address_space(3)))
; __device__ __forceinline__ f32x2 cmul(f32x2 a, f32x2 b) { return (f32x2){a.x * b.x - a.y * b.y, a.x * b.y + a.y * b.x}; }
; template <bool LO> __device__ __forceinline__ void fft_fwd1(f32x2 (&x)[16], LAS f32x2* B, int n2, const f32x2 (&w)[16]) {
;     asm volatile("" : "+v"(n2));
;     if (LO) dft16_fwd_lo(x); else dft16<false>(x);
;     B[fpad(n2)] = x[0];
; #pragma unroll
;     for (int k = 1; k < 16; ++k) B[fpad(512 * k + n2)] = cmul(x[k], w[k]);
; }
; __device__ __forceinline__ void fft_fwd2(LAS f32x2* B, const LAS f32x2* TW2, int tid) {
;     asm volatile("" : "+v"(tid));
;     const int b = tid >> 5, n2 = tid & 31, base = 512 * b + n2; f32x2 x[16];
; #pragma unroll
;     for (int r = 0; r < 16; ++r) x[r] = B[fpad(base + 32 * r)];
;     dft16<false>(x);
;     B[fpad(base)] = x[0];
; #pragma unroll
;     for (int k = 1; k < 16; ++k) B[fpad(base + 32 * k)] = cmul(x[k], TW2[k * 32 + n2]);
; }
	ds_write_b64 v3, v[102:103] offset:16896
	v_pk_mul_f32 v[188:189], v[118:119], v[14:15] op_sel:[1,1] op_sel_hi:[0,1]
	v_pk_fma_f32 v[186:187], v[118:119], v[14:15], v[188:189] op_sel_hi:[1,0,1] neg_lo:[0,0,1]
	ds_write_b64 v3, v[186:187] offset:21120
	v_pk_mul_f32 v[168:169], v[112:113], v[16:17] op_sel:[1,1] op_sel_hi:[0,1]
	v_pk_fma_f32 v[180:181], v[112:113], v[16:17], v[168:169] op_sel_hi:[1,0,1] neg_lo:[0,0,1]
	ds_write_b64 v3, v[180:181] offset:25344
	v_pk_mul_f32 v[178:179], v[114:115], v[18:19] op_sel:[1,1] op_sel_hi:[0,1]
	v_pk_fma_f32 v[176:177], v[114:115], v[18:19], v[178:179] op_sel_hi:[1,0,1] neg_lo:[0,0,1]
	ds_write_b64 v3, v[176:177] offset:29568
	v_pk_mul_f32 v[166:167], v[116:117], v[20:21] op_sel:[1,1] op_sel_hi:[0,1]
	v_pk_fma_f32 v[174:175], v[116:117], v[20:21], v[166:167] op_sel_hi:[1,0,1] neg_lo:[0,0,1]
	ds_write_b64 v3, v[174:175] offset:33792
	v_pk_mul_f32 v[102:103], v[182:183], v[22:23] op_sel:[1,1] op_sel_hi:[0,1]
	v_pk_fma_f32 v[184:185], v[182:183], v[22:23], v[102:103] op_sel_hi:[1,0,1] neg_lo:[0,0,1]
	ds_write_b64 v3, v[184:185] offset:38016
	v_pk_mul_f32 v[186:187], v[120:121], v[24:25] op_sel:[1,1] op_sel_hi:[0,1]
	v_pk_fma_f32 v[188:189], v[120:121], v[24:25], v[186:187] op_sel_hi:[1,0,1] neg_lo:[0,0,1]
	ds_write_b64 v3, v[188:189] offset:42240
	v_pk_mul_f32 v[180:181], v[122:123], v[26:27] op_sel:[1,1] op_sel_hi:[0,1]
	v_pk_fma_f32 v[168:169], v[122:123], v[26:27], v[180:181] op_sel_hi:[1,0,1] neg_lo:[0,0,1]
	ds_write_b64 v3, v[168:169] offset:46464
	v_pk_mul_f32 v[176:177], v[124:125], v[28:29] op_sel:[1,1] op_sel_hi:[0,1]
	v_pk_fma_f32 v[178:179], v[124:125], v[28:29], v[176:177] op_sel_hi:[1,0,1] neg_lo:[0,0,1]
	ds_write_b64 v3, v[178:179] offset:50688
	v_pk_mul_f32 v[174:175], v[110:111], v[30:31] op_sel:[1,1] op_sel_hi:[0,1]
	v_pk_fma_f32 v[166:167], v[110:111], v[30:31], v[174:175] op_sel_hi:[1,0,1] neg_lo:[0,0,1]
	ds_write_b64 v3, v[166:167] offset:54912
	v_pk_mul_f32 v[184:185], v[128:129], v[32:33] op_sel:[1,1] op_sel_hi:[0,1]
	v_pk_fma_f32 v[102:103], v[128:129], v[32:33], v[184:185] op_sel_hi:[1,0,1] neg_lo:[0,0,1]
	ds_write_b64 v3, v[102:103] offset:59136
	v_pk_mul_f32 v[188:189], v[130:131], v[34:35] op_sel:[1,1] op_sel_hi:[0,1]
	v_pk_fma_f32 v[186:187], v[130:131], v[34:35], v[188:189] op_sel_hi:[1,0,1] neg_lo:[0,0,1]
	ds_write_b64 v3, v[186:187] offset:63360
	s_waitcnt lgkmcnt(0)
	s_barrier
	ds_read_b64 v[100:101], v5
	ds_read_b64 v[108:109], v5 offset:1056
	ds_read_b64 v[116:117], v5 offset:2112
	ds_read_b64 v[124:125], v5 offset:3168
	ds_read_b64 v[126:127], v5 offset:264
	ds_read_b64 v[118:119], v5 offset:1320
	ds_read_b64 v[182:183], v5 offset:2376
	ds_read_b64 v[110:111], v5 offset:3432
	ds_read_b64 v[104:105], v5 offset:528
	ds_read_b64 v[112:113], v5 offset:1584
	ds_read_b64 v[120:121], v5 offset:2640
	ds_read_b64 v[128:129], v5 offset:3696
	s_waitcnt lgkmcnt(8)
	ds_read_b64 v[106:107], v5 offset:792
	ds_read_b64 v[114:115], v5 offset:1848
	ds_read_b64 v[122:123], v5 offset:2904
	ds_read_b64 v[130:131], v5 offset:3960
	v_pk_add_f32 v[180:181], v[100:101], v[116:117]
	v_pk_add_f32 v[168:169], v[100:101], v[116:117] neg_lo:[0,1] neg_hi:[0,1]
	v_pk_add_f32 v[176:177], v[108:109], v[124:125]
	v_pk_add_f32 v[178:179], v[108:109], v[124:125] neg_lo:[0,1] neg_hi:[0,1]
	v_pk_add_f32 v[100:101], v[180:181], v[176:177]
	v_pk_add_f32 v[116:117], v[180:181], v[176:177] neg_lo:[0,1] neg_hi:[0,1]
	v_pk_add_f32 v[108:109], v[168:169], v[178:179] op_sel:[0,1] op_sel_hi:[1,0] neg_hi:[0,1]
	v_pk_add_f32 v[124:125], v[168:169], v[178:179] op_sel:[0,1] op_sel_hi:[1,0] neg_lo:[0,1]
	s_waitcnt lgkmcnt(9)
	v_pk_add_f32 v[174:175], v[126:127], v[182:183]
	v_pk_add_f32 v[166:167], v[126:127], v[182:183] neg_lo:[0,1] neg_hi:[0,1]
	s_waitcnt lgkmcnt(8)
	v_pk_add_f32 v[184:185], v[118:119], v[110:111]
	v_pk_add_f32 v[102:103], v[118:119], v[110:111] neg_lo:[0,1] neg_hi:[0,1]
	v_pk_add_f32 v[126:127], v[174:175], v[184:185]
	v_pk_add_f32 v[182:183], v[174:175], v[184:185] neg_lo:[0,1] neg_hi:[0,1]
	v_pk_add_f32 v[118:119], v[166:167], v[102:103] op_sel:[0,1] op_sel_hi:[1,0] neg_hi:[0,1]
	v_pk_add_f32 v[110:111], v[166:167], v[102:103] op_sel:[0,1] op_sel_hi:[1,0] neg_lo:[0,1]
	s_waitcnt lgkmcnt(5)
	v_pk_add_f32 v[188:189], v[104:105], v[120:121]
	v_pk_add_f32 v[186:187], v[104:105], v[120:121] neg_lo:[0,1] neg_hi:[0,1]
	s_waitcnt lgkmcnt(4)
	v_pk_add_f32 v[180:181], v[112:113], v[128:129]
	v_pk_add_f32 v[168:169], v[112:113], v[128:129] neg_lo:[0,1] neg_hi:[0,1]
	v_pk_add_f32 v[104:105], v[188:189], v[180:181]
	v_pk_add_f32 v[120:121], v[188:189], v[180:181] neg_lo:[0,1] neg_hi:[0,1]
	v_pk_add_f32 v[112:113], v[186:187], v[168:169] op_sel:[0,1] op_sel_hi:[1,0] neg_hi:[0,1]
	v_pk_add_f32 v[128:129], v[186:187], v[168:169] op_sel:[0,1] op_sel_hi:[1,0] neg_lo:[0,1]
	s_waitcnt lgkmcnt(1)
	v_pk_add_f32 v[176:177], v[106:107], v[122:123]
	v_pk_add_f32 v[178:179], v[106:107], v[122:123] neg_lo:[0,1] neg_hi:[0,1]
	s_waitcnt lgkmcnt(0)
; #define LAS __attribute__((address_space(3)))
; __device__ __forceinline__ f32x2 cmul(f32x2 a, f32x2 b) { return (f32x2){a.x * b.x - a.y * b.y, a.x * b.y + a.y * b.x}; }
; template <bool INV> __device__ __forceinline__ f32x2 cmul_tw(f32x2 a, f32x2 w) { return INV ? cmulc(a, w) : cmul(a, w); }
; template <bool INV> __device__ __forceinline__ void dft16(f32x2 (&x)[16]) {
;     constexpr float C1 = 0.92387953251128674f, S1 = 0.38268343236508977f, C2 = 0.70710678118654752f;
; #pragma unroll
;     for (int b = 0; b < 4; ++b) dft4<INV>(x[b], x[4 + b], x[8 + b], x[12 + b]);
;     const f32x2 w1 = {C1, -S1}, w2 = {C2, -C2}, w3 = {S1, -C1}, w4 = {0.f, -1.f}, w6 = {-C2, -C2}, w9 = {-C1, S1};
;     x[4 * 1 + 1] = cmul_tw<INV>(x[5], w1); x[4 * 1 + 2] = cmul_tw<INV>(x[6], w2); x[4 * 1 + 3] = cmul_tw<INV>(x[7], w3);
;     x[4 * 2 + 1] = cmul_tw<INV>(x[9], w2); x[4 * 2 + 2] = cmul_tw<INV>(x[10], w4); x[4 * 2 + 3] = cmul_tw<INV>(x[11], w6);
;     x[4 * 3 + 1] = cmul_tw<INV>(x[13], w3); x[4 * 3 + 2] = cmul_tw<INV>(x[14], w6); x[4 * 3 + 3] = cmul_tw<INV>(x[15], w9);
; #pragma unroll
;     for (int c = 0; c < 4; ++c) dft4<INV>(x[4 * c], x[4 * c + 1], x[4 * c + 2], x[4 * c + 3]);
;     f32x2 y[16];
; #pragma unroll
;     for (int k = 0; k < 16; ++k) y[k] = x[4 * (k & 3) + (k >> 2)];
; #pragma unroll
;     for (int k = 0; k < 16; ++k) x[k] = y[k];
; }
; __device__ __forceinline__ void fft_fwd2(LAS f32x2* B, const LAS f32x2* TW2, int tid) {
;     asm volatile("" : "+v"(tid));
;     const int b = tid >> 5, n2 = tid & 31, base = 512 * b + n2; f32x2 x[16];
; #pragma unroll
;     for (int r = 0; r < 16; ++r) x[r] = B[fpad(base + 32 * r)];
;     dft16<false>(x);
;     B[fpad(base)] = x[0];
; #pragma unroll
;     for (int k = 1; k < 16; ++k) B[fpad(base + 32 * k)] = cmul(x[k], TW2[k * 32 + n2]);
; }
	v_pk_add_f32 v[174:175], v[114:115], v[130:131]
	v_pk_add_f32 v[166:167], v[114:115], v[130:131] neg_lo:[0,1] neg_hi:[0,1]
	v_pk_add_f32 v[106:107], v[176:177], v[174:175]
	v_pk_add_f32 v[122:123], v[176:177], v[174:175] neg_lo:[0,1] neg_hi:[0,1]
	v_pk_add_f32 v[114:115], v[178:179], v[166:167] op_sel:[0,1] op_sel_hi:[1,0] neg_hi:[0,1]
	v_pk_add_f32 v[130:131], v[178:179], v[166:167] op_sel:[0,1] op_sel_hi:[1,0] neg_lo:[0,1]
	v_pk_mul_f32 v[184:185], v[118:119], s[68:69] op_sel:[1,1] op_sel_hi:[0,1]
	v_pk_fma_f32 v[118:119], v[118:119], s[68:69], v[184:185] op_sel_hi:[1,0,1] neg_lo:[0,0,1]
	v_pk_mul_f32 v[102:103], v[112:113], s[84:85] op_sel:[1,1] op_sel_hi:[0,1]
	v_pk_fma_f32 v[112:113], v[112:113], s[84:85], v[102:103] op_sel_hi:[1,0,1] neg_lo:[0,0,1]
	v_pk_mul_f32 v[188:189], v[114:115], s[88:89] op_sel:[1,1] op_sel_hi:[0,1]
	v_pk_fma_f32 v[114:115], v[114:115], s[88:89], v[188:189] op_sel_hi:[1,0,1] neg_lo:[0,0,1]
	v_pk_mul_f32 v[186:187], v[182:183], s[84:85] op_sel:[1,1] op_sel_hi:[0,1]
	v_pk_fma_f32 v[182:183], v[182:183], s[84:85], v[186:187] op_sel_hi:[1,0,1] neg_lo:[0,0,1]
	v_pk_mul_f32 v[180:181], v[122:123], s[90:91] op_sel:[1,1] op_sel_hi:[0,1]
	v_pk_fma_f32 v[122:123], v[122:123], s[90:91], v[180:181] op_sel_hi:[1,0,1] neg_lo:[0,0,1]
	v_pk_mul_f32 v[168:169], v[110:111], s[88:89] op_sel:[1,1] op_sel_hi:[0,1]
	v_pk_fma_f32 v[110:111], v[110:111], s[88:89], v[168:169] op_sel_hi:[1,0,1] neg_lo:[0,0,1]
	v_pk_mul_f32 v[176:177], v[128:129], s[90:91] op_sel:[1,1] op_sel_hi:[0,1]
	v_pk_fma_f32 v[128:129], v[128:129], s[90:91], v[176:177] op_sel_hi:[1,0,1] neg_lo:[0,0,1]
	v_pk_mul_f32 v[178:179], v[130:131], s[98:99] op_sel:[1,1] op_sel_hi:[0,1]
	v_pk_fma_f32 v[130:131], v[130:131], s[98:99], v[178:179] op_sel_hi:[1,0,1] neg_lo:[0,0,1]
	v_pk_add_f32 v[174:175], v[100:101], v[104:105]
	v_pk_add_f32 v[166:167], v[100:101], v[104:105] neg_lo:[0,1] neg_hi:[0,1]
	v_pk_add_f32 v[184:185], v[126:127], v[106:107]
	v_pk_add_f32 v[102:103], v[126:127], v[106:107] neg_lo:[0,1] neg_hi:[0,1]
	v_pk_add_f32 v[100:101], v[174:175], v[184:185]
	v_pk_add_f32 v[104:105], v[174:175], v[184:185] neg_lo:[0,1] neg_hi:[0,1]
	v_pk_add_f32 v[126:127], v[166:167], v[102:103] op_sel:[0,1] op_sel_hi:[1,0] neg_hi:[0,1]
	v_pk_add_f32 v[106:107], v[166:167], v[102:103] op_sel:[0,1] op_sel_hi:[1,0] neg_lo:[0,1]
	v_pk_add_f32 v[188:189], v[108:109], v[112:113]
	v_pk_add_f32 v[186:187], v[108:109], v[112:113] neg_lo:[0,1] neg_hi:[0,1]
	v_pk_add_f32 v[180:181], v[118:119], v[114:115]
	v_pk_add_f32 v[168:169], v[118:119], v[114:115] neg_lo:[0,1] neg_hi:[0,1]
	v_pk_add_f32 v[108:109], v[188:189], v[180:181]
	v_pk_add_f32 v[112:113], v[188:189], v[180:181] neg_lo:[0,1] neg_hi:[0,1]
	v_pk_add_f32 v[118:119], v[186:187], v[168:169] op_sel:[0,1] op_sel_hi:[1,0] neg_hi:[0,1]
	v_pk_add_f32 v[114:115], v[186:187], v[168:169] op_sel:[0,1] op_sel_hi:[1,0] neg_lo:[0,1]
	v_pk_add_f32 v[176:177], v[116:117], v[120:121] op_sel:[0,1] op_sel_hi:[1,0] neg_hi:[0,1]
	v_pk_add_f32 v[178:179], v[116:117], v[120:121] op_sel:[0,1] op_sel_hi:[1,0] neg_lo:[0,1]
	v_pk_add_f32 v[174:175], v[182:183], v[122:123]
	v_pk_add_f32 v[166:167], v[182:183], v[122:123] neg_lo:[0,1] neg_hi:[0,1]
	v_pk_add_f32 v[116:117], v[176:177], v[174:175]
	v_pk_add_f32 v[120:121], v[176:177], v[174:175] neg_lo:[0,1] neg_hi:[0,1]
	v_pk_add_f32 v[182:183], v[178:179], v[166:167] op_sel:[0,1] op_sel_hi:[1,0] neg_hi:[0,1]
	v_pk_add_f32 v[122:123], v[178:179], v[166:167] op_sel:[0,1] op_sel_hi:[1,0] neg_lo:[0,1]
	v_pk_add_f32 v[184:185], v[124:125], v[128:129]
	v_pk_add_f32 v[102:103], v[124:125], v[128:129] neg_lo:[0,1] neg_hi:[0,1]
	v_pk_add_f32 v[188:189], v[110:111], v[130:131]
	v_pk_add_f32 v[186:187], v[110:111], v[130:131] neg_lo:[0,1] neg_hi:[0,1]
	v_pk_add_f32 v[124:125], v[184:185], v[188:189]
	v_pk_add_f32 v[128:129], v[184:185], v[188:189] neg_lo:[0,1] neg_hi:[0,1]
	v_pk_add_f32 v[110:111], v[102:103], v[186:187] op_sel:[0,1] op_sel_hi:[1,0] neg_hi:[0,1]
	v_pk_add_f32 v[130:131], v[102:103], v[186:187] op_sel:[0,1] op_sel_hi:[1,0] neg_lo:[0,1]
	ds_write_b64 v5, v[100:101]
	ds_read_b64 v[180:181], v56 offset:256
	ds_read_b64 v[168:169], v56 offset:512
	ds_read_b64 v[176:177], v56 offset:768
	ds_read_b64 v[178:179], v56 offset:1024
	s_waitcnt lgkmcnt(3)
	v_pk_mul_f32 v[174:175], v[108:109], v[180:181] op_sel:[1,1] op_sel_hi:[0,1]
	v_pk_fma_f32 v[108:109], v[108:109], v[180:181], v[174:175] op_sel_hi:[1,0,1] neg_lo:[0,0,1]
	ds_write_b64 v5, v[108:109] offset:264
	s_waitcnt lgkmcnt(3)
	v_pk_mul_f32 v[166:167], v[116:117], v[168:169] op_sel:[1,1] op_sel_hi:[0,1]
	v_pk_fma_f32 v[116:117], v[116:117], v[168:169], v[166:167] op_sel_hi:[1,0,1] neg_lo:[0,0,1]
	ds_write_b64 v5, v[116:117] offset:528
	s_waitcnt lgkmcnt(3)
	v_pk_mul_f32 v[184:185], v[124:125], v[176:177] op_sel:[1,1] op_sel_hi:[0,1]
	v_pk_fma_f32 v[124:125], v[124:125], v[176:177], v[184:185] op_sel_hi:[1,0,1] neg_lo:[0,0,1]
	ds_write_b64 v5, v[124:125] offset:792
	s_waitcnt lgkmcnt(3)
	v_pk_mul_f32 v[102:103], v[126:127], v[178:179] op_sel:[1,1] op_sel_hi:[0,1]
	v_pk_fma_f32 v[126:127], v[126:127], v[178:179], v[102:103] op_sel_hi:[1,0,1] neg_lo:[0,0,1]
	ds_write_b64 v5, v[126:127] offset:1056
	ds_read_b64 v[188:189], v56 offset:1280
	ds_read_b64 v[186:187], v56 offset:1536
	ds_read_b64 v[174:175], v56 offset:1792
	ds_read_b64 v[166:167], v56 offset:2048
	s_waitcnt lgkmcnt(3)
	v_pk_mul_f32 v[184:185], v[118:119], v[188:189] op_sel:[1,1] op_sel_hi:[0,1]
	v_pk_fma_f32 v[118:119], v[118:119], v[188:189], v[184:185] op_sel_hi:[1,0,1] neg_lo:[0,0,1]
	ds_write_b64 v5, v[118:119] offset:1320
	s_waitcnt lgkmcnt(3)
; #define LAS __attribute__((address_space(3)))
; __device__ __forceinline__ f32x2 cmul(f32x2 a, f32x2 b) { return (f32x2){a.x * b.x - a.y * b.y, a.x * b.y + a.y * b.x}; }
; __device__ __forceinline__ void fft_fwd2(LAS f32x2* B, const LAS f32x2* TW2, int tid) {
;     ...
;     B[fpad(base)] = x[0];
; #pragma unroll
;     for (int k = 1; k < 16; ++k) B[fpad(base + 32 * k)] = cmul(x[k], TW2[k * 32 + n2]);
; }
; template <int MODE> __device__ __forceinline__ void fft_pair32(LAS f32x2* B, const LAS f32x2* F, int wave, int lane) {
;     ...
;     const int hi = lane >> 5, blk = 32 * wave + (lane & 31); const float sg = hi ? -1.f : 1.f;
;     LAS f32x2* p = B + 33 * blk; f32x2 v[16];
; #pragma unroll
;     for (int j = 0; j < 16; ++j) { const f32x2 d = p[j] + p[j + 16] * sg;
;         const f32x2 w = {hi ? CS[j] : 1.f, hi ? -SN[j] : 0.f}; v[j] = j == 0 ? d : cmul(d, w); }
	v_pk_mul_f32 v[102:103], v[182:183], v[186:187] op_sel:[1,1] op_sel_hi:[0,1]
	v_pk_fma_f32 v[182:183], v[182:183], v[186:187], v[102:103] op_sel_hi:[1,0,1] neg_lo:[0,0,1]
	ds_write_b64 v5, v[182:183] offset:1584
	s_waitcnt lgkmcnt(3)
	v_pk_mul_f32 v[180:181], v[110:111], v[174:175] op_sel:[1,1] op_sel_hi:[0,1]
	v_pk_fma_f32 v[110:111], v[110:111], v[174:175], v[180:181] op_sel_hi:[1,0,1] neg_lo:[0,0,1]
	ds_write_b64 v5, v[110:111] offset:1848
	s_waitcnt lgkmcnt(3)
	v_pk_mul_f32 v[168:169], v[104:105], v[166:167] op_sel:[1,1] op_sel_hi:[0,1]
	v_pk_fma_f32 v[104:105], v[104:105], v[166:167], v[168:169] op_sel_hi:[1,0,1] neg_lo:[0,0,1]
	ds_write_b64 v5, v[104:105] offset:2112
	ds_read_b64 v[176:177], v56 offset:2304
	ds_read_b64 v[178:179], v56 offset:2560
	ds_read_b64 v[184:185], v56 offset:2816
	ds_read_b64 v[102:103], v56 offset:3072
	s_waitcnt lgkmcnt(3)
	v_pk_mul_f32 v[180:181], v[112:113], v[176:177] op_sel:[1,1] op_sel_hi:[0,1]
	v_pk_fma_f32 v[112:113], v[112:113], v[176:177], v[180:181] op_sel_hi:[1,0,1] neg_lo:[0,0,1]
	ds_write_b64 v5, v[112:113] offset:2376
	s_waitcnt lgkmcnt(3)
	v_pk_mul_f32 v[168:169], v[120:121], v[178:179] op_sel:[1,1] op_sel_hi:[0,1]
	v_pk_fma_f32 v[120:121], v[120:121], v[178:179], v[168:169] op_sel_hi:[1,0,1] neg_lo:[0,0,1]
	ds_write_b64 v5, v[120:121] offset:2640
	s_waitcnt lgkmcnt(3)
	v_pk_mul_f32 v[188:189], v[128:129], v[184:185] op_sel:[1,1] op_sel_hi:[0,1]
	v_pk_fma_f32 v[128:129], v[128:129], v[184:185], v[188:189] op_sel_hi:[1,0,1] neg_lo:[0,0,1]
	ds_write_b64 v5, v[128:129] offset:2904
	s_waitcnt lgkmcnt(3)
	v_pk_mul_f32 v[186:187], v[106:107], v[102:103] op_sel:[1,1] op_sel_hi:[0,1]
	v_pk_fma_f32 v[106:107], v[106:107], v[102:103], v[186:187] op_sel_hi:[1,0,1] neg_lo:[0,0,1]
	ds_write_b64 v5, v[106:107] offset:3168
	ds_read_b64 v[174:175], v56 offset:3328
	ds_read_b64 v[166:167], v56 offset:3584
	ds_read_b64 v[180:181], v56 offset:3840
	s_waitcnt lgkmcnt(2)
	v_pk_mul_f32 v[168:169], v[114:115], v[174:175] op_sel:[1,1] op_sel_hi:[0,1]
	v_pk_fma_f32 v[114:115], v[114:115], v[174:175], v[168:169] op_sel_hi:[1,0,1] neg_lo:[0,0,1]
	ds_write_b64 v5, v[114:115] offset:3432
	s_waitcnt lgkmcnt(2)
	v_pk_mul_f32 v[188:189], v[122:123], v[166:167] op_sel:[1,1] op_sel_hi:[0,1]
	v_pk_fma_f32 v[122:123], v[122:123], v[166:167], v[188:189] op_sel_hi:[1,0,1] neg_lo:[0,0,1]
	ds_write_b64 v5, v[122:123] offset:3696
	s_waitcnt lgkmcnt(2)
	v_pk_mul_f32 v[186:187], v[130:131], v[180:181] op_sel:[1,1] op_sel_hi:[0,1]
	v_pk_fma_f32 v[130:131], v[130:131], v[180:181], v[186:187] op_sel_hi:[1,0,1] neg_lo:[0,0,1]
	ds_write_b64 v5, v[130:131] offset:3960
	s_waitcnt lgkmcnt(0)
	ds_read_b64 v[100:101], v156
	ds_read_b64 v[176:177], v156 offset:128
	ds_read_b64 v[108:109], v156 offset:8
	ds_read_b64 v[178:179], v156 offset:136
	ds_read_b64 v[116:117], v156 offset:16
	ds_read_b64 v[184:185], v156 offset:144
	ds_read_b64 v[124:125], v156 offset:24
	ds_read_b64 v[102:103], v156 offset:152
	s_waitcnt lgkmcnt(6)
	v_pk_fma_f32 v[100:101], v[176:177], v[190:191], v[100:101] op_sel_hi:[1,0,1]
	s_waitcnt lgkmcnt(4)
	v_pk_fma_f32 v[108:109], v[178:179], v[190:191], v[108:109] op_sel_hi:[1,0,1]
	v_pk_mul_f32 v[168:169], v[108:109], v[36:37] op_sel:[1,1] op_sel_hi:[0,1]
	v_pk_fma_f32 v[108:109], v[108:109], v[36:37], v[168:169] op_sel_hi:[1,0,1] neg_lo:[0,0,1]
	s_waitcnt lgkmcnt(2)
	v_pk_fma_f32 v[116:117], v[184:185], v[190:191], v[116:117] op_sel_hi:[1,0,1]
	v_pk_mul_f32 v[188:189], v[116:117], v[38:39] op_sel:[1,1] op_sel_hi:[0,1]
	v_pk_fma_f32 v[116:117], v[116:117], v[38:39], v[188:189] op_sel_hi:[1,0,1] neg_lo:[0,0,1]
	s_waitcnt lgkmcnt(0)
	v_pk_fma_f32 v[124:125], v[102:103], v[190:191], v[124:125] op_sel_hi:[1,0,1]
	v_pk_mul_f32 v[186:187], v[124:125], v[40:41] op_sel:[1,1] op_sel_hi:[0,1]
	v_pk_fma_f32 v[124:125], v[124:125], v[40:41], v[186:187] op_sel_hi:[1,0,1] neg_lo:[0,0,1]
	ds_read_b64 v[126:127], v156 offset:32
	ds_read_b64 v[174:175], v156 offset:160
	ds_read_b64 v[118:119], v156 offset:40
	ds_read_b64 v[166:167], v156 offset:168
	ds_read_b64 v[182:183], v156 offset:48
	ds_read_b64 v[180:181], v156 offset:176
	ds_read_b64 v[110:111], v156 offset:56
	ds_read_b64 v[168:169], v156 offset:184
	s_waitcnt lgkmcnt(6)
	v_pk_fma_f32 v[126:127], v[174:175], v[190:191], v[126:127] op_sel_hi:[1,0,1]
	v_pk_mul_f32 v[188:189], v[126:127], v[42:43] op_sel:[1,1] op_sel_hi:[0,1]
	v_pk_fma_f32 v[126:127], v[126:127], v[42:43], v[188:189] op_sel_hi:[1,0,1] neg_lo:[0,0,1]
	s_waitcnt lgkmcnt(4)
	v_pk_fma_f32 v[118:119], v[166:167], v[190:191], v[118:119] op_sel_hi:[1,0,1]
	v_pk_mul_f32 v[186:187], v[118:119], v[44:45] op_sel:[1,1] op_sel_hi:[0,1]
	v_pk_fma_f32 v[118:119], v[118:119], v[44:45], v[186:187] op_sel_hi:[1,0,1] neg_lo:[0,0,1]
	s_waitcnt lgkmcnt(2)
	v_pk_fma_f32 v[182:183], v[180:181], v[190:191], v[182:183] op_sel_hi:[1,0,1]
	v_pk_mul_f32 v[176:177], v[182:183], v[46:47] op_sel:[1,1] op_sel_hi:[0,1]
	v_pk_fma_f32 v[182:183], v[182:183], v[46:47], v[176:177] op_sel_hi:[1,0,1] neg_lo:[0,0,1]
	s_waitcnt lgkmcnt(0)
	v_pk_fma_f32 v[110:111], v[168:169], v[190:191], v[110:111] op_sel_hi:[1,0,1]
	v_pk_mul_f32 v[178:179], v[110:111], v[48:49] op_sel:[1,1] op_sel_hi:[0,1]
	v_pk_fma_f32 v[110:111], v[110:111], v[48:49], v[178:179] op_sel_hi:[1,0,1] neg_lo:[0,0,1]
	ds_read_b64 v[104:105], v156 offset:64
	ds_read_b64 v[184:185], v156 offset:192
	ds_read_b64 v[112:113], v156 offset:72
	ds_read_b64 v[102:103], v156 offset:200
	ds_read_b64 v[120:121], v156 offset:80
	ds_read_b64 v[188:189], v156 offset:208
	ds_read_b64 v[128:129], v156 offset:88
	ds_read_b64 v[186:187], v156 offset:216
	s_waitcnt lgkmcnt(6)
; __device__ __forceinline__ f32x2 cmul(f32x2 a, f32x2 b) { return (f32x2){a.x * b.x - a.y * b.y, a.x * b.y + a.y * b.x}; }
; template <bool INV> __device__ __forceinline__ f32x2 cmul_tw(f32x2 a, f32x2 w) { return INV ? cmulc(a, w) : cmul(a, w); }
; template <bool INV> __device__ __forceinline__ void dft16(f32x2 (&x)[16]) {
;     constexpr float C1 = 0.92387953251128674f, S1 = 0.38268343236508977f, C2 = 0.70710678118654752f;
; #pragma unroll
;     for (int b = 0; b < 4; ++b) dft4<INV>(x[b], x[4 + b], x[8 + b], x[12 + b]);
;     const f32x2 w1 = {C1, -S1}, w2 = {C2, -C2}, w3 = {S1, -C1}, w4 = {0.f, -1.f}, w6 = {-C2, -C2}, w9 = {-C1, S1};
;     x[4 * 1 + 1] = cmul_tw<INV>(x[5], w1); x[4 * 1 + 2] = cmul_tw<INV>(x[6], w2); x[4 * 1 + 3] = cmul_tw<INV>(x[7], w3);
;     x[4 * 2 + 1] = cmul_tw<INV>(x[9], w2); x[4 * 2 + 2] = cmul_tw<INV>(x[10], w4); x[4 * 2 + 3] = cmul_tw<INV>(x[11], w6);
;     x[4 * 3 + 1] = cmul_tw<INV>(x[13], w3); x[4 * 3 + 2] = cmul_tw<INV>(x[14], w6); x[4 * 3 + 3] = cmul_tw<INV>(x[15], w9);
; #pragma unroll
;     for (int c = 0; c < 4; ++c) dft4<INV>(x[4 * c], x[4 * c + 1], x[4 * c + 2], x[4 * c + 3]);
; template <int MODE> __device__ __forceinline__ void fft_pair32(LAS f32x2* B, const LAS f32x2* F, int wave, int lane) {
;     ...
;     for (int j = 0; j < 16; ++j) { const f32x2 d = p[j] + p[j + 16] * sg;
;         const f32x2 w = {hi ? CS[j] : 1.f, hi ? -SN[j] : 0.f}; v[j] = j == 0 ? d : cmul(d, w); }
;     dft16<false>(v);
	v_pk_fma_f32 v[104:105], v[184:185], v[190:191], v[104:105] op_sel_hi:[1,0,1]
	v_pk_mul_f32 v[176:177], v[104:105], v[50:51] op_sel:[1,1] op_sel_hi:[0,1]
	v_pk_fma_f32 v[104:105], v[104:105], v[50:51], v[176:177] op_sel_hi:[1,0,1] neg_lo:[0,0,1]
	s_waitcnt lgkmcnt(4)
	v_pk_fma_f32 v[112:113], v[102:103], v[190:191], v[112:113] op_sel_hi:[1,0,1]
	v_pk_mul_f32 v[178:179], v[112:113], v[52:53] op_sel:[1,1] op_sel_hi:[0,1]
	v_pk_fma_f32 v[112:113], v[112:113], v[52:53], v[178:179] op_sel_hi:[1,0,1] neg_lo:[0,0,1]
	s_waitcnt lgkmcnt(2)
	v_pk_fma_f32 v[120:121], v[188:189], v[190:191], v[120:121] op_sel_hi:[1,0,1]
	v_pk_mul_f32 v[174:175], v[120:121], v[54:55] op_sel:[1,1] op_sel_hi:[0,1]
	v_pk_fma_f32 v[120:121], v[120:121], v[54:55], v[174:175] op_sel_hi:[1,0,1] neg_lo:[0,0,1]
	s_waitcnt lgkmcnt(0)
	v_pk_fma_f32 v[128:129], v[186:187], v[190:191], v[128:129] op_sel_hi:[1,0,1]
	v_pk_mul_f32 v[166:167], v[128:129], v[90:91] op_sel:[1,1] op_sel_hi:[0,1]
	v_pk_fma_f32 v[128:129], v[128:129], v[90:91], v[166:167] op_sel_hi:[1,0,1] neg_lo:[0,0,1]
	ds_read_b64 v[106:107], v156 offset:96
	ds_read_b64 v[180:181], v156 offset:224
	ds_read_b64 v[114:115], v156 offset:104
	ds_read_b64 v[168:169], v156 offset:232
	ds_read_b64 v[122:123], v156 offset:112
	ds_read_b64 v[176:177], v156 offset:240
	ds_read_b64 v[130:131], v156 offset:120
	ds_read_b64 v[178:179], v156 offset:248
	s_waitcnt lgkmcnt(6)
	v_pk_fma_f32 v[106:107], v[180:181], v[190:191], v[106:107] op_sel_hi:[1,0,1]
	v_pk_mul_f32 v[174:175], v[106:107], v[92:93] op_sel:[1,1] op_sel_hi:[0,1]
	v_pk_fma_f32 v[106:107], v[106:107], v[92:93], v[174:175] op_sel_hi:[1,0,1] neg_lo:[0,0,1]
	s_waitcnt lgkmcnt(4)
	v_pk_fma_f32 v[114:115], v[168:169], v[190:191], v[114:115] op_sel_hi:[1,0,1]
	v_pk_mul_f32 v[166:167], v[114:115], v[94:95] op_sel:[1,1] op_sel_hi:[0,1]
	v_pk_fma_f32 v[114:115], v[114:115], v[94:95], v[166:167] op_sel_hi:[1,0,1] neg_lo:[0,0,1]
	s_waitcnt lgkmcnt(2)
	v_pk_fma_f32 v[122:123], v[176:177], v[190:191], v[122:123] op_sel_hi:[1,0,1]
	v_pk_mul_f32 v[184:185], v[122:123], v[96:97] op_sel:[1,1] op_sel_hi:[0,1]
	v_pk_fma_f32 v[122:123], v[122:123], v[96:97], v[184:185] op_sel_hi:[1,0,1] neg_lo:[0,0,1]
	s_waitcnt lgkmcnt(0)
	v_pk_fma_f32 v[130:131], v[178:179], v[190:191], v[130:131] op_sel_hi:[1,0,1]
	v_pk_mul_f32 v[102:103], v[130:131], v[98:99] op_sel:[1,1] op_sel_hi:[0,1]
	v_pk_fma_f32 v[130:131], v[130:131], v[98:99], v[102:103] op_sel_hi:[1,0,1] neg_lo:[0,0,1]
	v_pk_add_f32 v[188:189], v[100:101], v[104:105]
	v_pk_add_f32 v[186:187], v[100:101], v[104:105] neg_lo:[0,1] neg_hi:[0,1]
	v_pk_add_f32 v[174:175], v[126:127], v[106:107]
	v_pk_add_f32 v[166:167], v[126:127], v[106:107] neg_lo:[0,1] neg_hi:[0,1]
	v_pk_add_f32 v[100:101], v[188:189], v[174:175]
	v_pk_add_f32 v[104:105], v[188:189], v[174:175] neg_lo:[0,1] neg_hi:[0,1]
	v_pk_add_f32 v[126:127], v[186:187], v[166:167] op_sel:[0,1] op_sel_hi:[1,0] neg_hi:[0,1]
	v_pk_add_f32 v[106:107], v[186:187], v[166:167] op_sel:[0,1] op_sel_hi:[1,0] neg_lo:[0,1]
	v_pk_add_f32 v[184:185], v[108:109], v[112:113]
	v_pk_add_f32 v[102:103], v[108:109], v[112:113] neg_lo:[0,1] neg_hi:[0,1]
	v_pk_add_f32 v[180:181], v[118:119], v[114:115]
	v_pk_add_f32 v[168:169], v[118:119], v[114:115] neg_lo:[0,1] neg_hi:[0,1]
	v_pk_add_f32 v[108:109], v[184:185], v[180:181]
	v_pk_add_f32 v[112:113], v[184:185], v[180:181] neg_lo:[0,1] neg_hi:[0,1]
	v_pk_add_f32 v[118:119], v[102:103], v[168:169] op_sel:[0,1] op_sel_hi:[1,0] neg_hi:[0,1]
	v_pk_add_f32 v[114:115], v[102:103], v[168:169] op_sel:[0,1] op_sel_hi:[1,0] neg_lo:[0,1]
	v_pk_add_f32 v[176:177], v[116:117], v[120:121]
	v_pk_add_f32 v[178:179], v[116:117], v[120:121] neg_lo:[0,1] neg_hi:[0,1]
	v_pk_add_f32 v[188:189], v[182:183], v[122:123]
	v_pk_add_f32 v[186:187], v[182:183], v[122:123] neg_lo:[0,1] neg_hi:[0,1]
	v_pk_add_f32 v[116:117], v[176:177], v[188:189]
	v_pk_add_f32 v[120:121], v[176:177], v[188:189] neg_lo:[0,1] neg_hi:[0,1]
	v_pk_add_f32 v[182:183], v[178:179], v[186:187] op_sel:[0,1] op_sel_hi:[1,0] neg_hi:[0,1]
	v_pk_add_f32 v[122:123], v[178:179], v[186:187] op_sel:[0,1] op_sel_hi:[1,0] neg_lo:[0,1]
	v_pk_add_f32 v[174:175], v[124:125], v[128:129]
	v_pk_add_f32 v[166:167], v[124:125], v[128:129] neg_lo:[0,1] neg_hi:[0,1]
	v_pk_add_f32 v[184:185], v[110:111], v[130:131]
	v_pk_add_f32 v[102:103], v[110:111], v[130:131] neg_lo:[0,1] neg_hi:[0,1]
	v_pk_add_f32 v[124:125], v[174:175], v[184:185]
	v_pk_add_f32 v[128:129], v[174:175], v[184:185] neg_lo:[0,1] neg_hi:[0,1]
	v_pk_add_f32 v[110:111], v[166:167], v[102:103] op_sel:[0,1] op_sel_hi:[1,0] neg_hi:[0,1]
	v_pk_add_f32 v[130:131], v[166:167], v[102:103] op_sel:[0,1] op_sel_hi:[1,0] neg_lo:[0,1]
	v_pk_mul_f32 v[180:181], v[118:119], s[68:69] op_sel:[1,1] op_sel_hi:[0,1]
	v_pk_fma_f32 v[118:119], v[118:119], s[68:69], v[180:181] op_sel_hi:[1,0,1] neg_lo:[0,0,1]
	v_pk_mul_f32 v[168:169], v[182:183], s[84:85] op_sel:[1,1] op_sel_hi:[0,1]
	v_pk_fma_f32 v[182:183], v[182:183], s[84:85], v[168:169] op_sel_hi:[1,0,1] neg_lo:[0,0,1]
	v_pk_mul_f32 v[176:177], v[110:111], s[88:89] op_sel:[1,1] op_sel_hi:[0,1]
	v_pk_fma_f32 v[110:111], v[110:111], s[88:89], v[176:177] op_sel_hi:[1,0,1] neg_lo:[0,0,1]
	v_pk_mul_f32 v[178:179], v[112:113], s[84:85] op_sel:[1,1] op_sel_hi:[0,1]
	v_pk_fma_f32 v[112:113], v[112:113], s[84:85], v[178:179] op_sel_hi:[1,0,1] neg_lo:[0,0,1]
	v_pk_mul_f32 v[188:189], v[128:129], s[90:91] op_sel:[1,1] op_sel_hi:[0,1]
	v_pk_fma_f32 v[128:129], v[128:129], s[90:91], v[188:189] op_sel_hi:[1,0,1] neg_lo:[0,0,1]
	v_pk_mul_f32 v[186:187], v[114:115], s[88:89] op_sel:[1,1] op_sel_hi:[0,1]
	v_pk_fma_f32 v[114:115], v[114:115], s[88:89], v[186:187] op_sel_hi:[1,0,1] neg_lo:[0,0,1]
; #define LAS __attribute__((address_space(3)))
; __device__ __forceinline__ f32x2 cmul(f32x2 a, f32x2 b) { return (f32x2){a.x * b.x - a.y * b.y, a.x * b.y + a.y * b.x}; }
; template <bool INV> __device__ __forceinline__ f32x2 cmul_tw(f32x2 a, f32x2 w) { return INV ? cmulc(a, w) : cmul(a, w); }
; template <bool INV> __device__ __forceinline__ void dft16(f32x2 (&x)[16]) {
;     constexpr float C1 = 0.92387953251128674f, S1 = 0.38268343236508977f, C2 = 0.70710678118654752f;
; #pragma unroll
;     for (int b = 0; b < 4; ++b) dft4<INV>(x[b], x[4 + b], x[8 + b], x[12 + b]);
;     const f32x2 w1 = {C1, -S1}, w2 = {C2, -C2}, w3 = {S1, -C1}, w4 = {0.f, -1.f}, w6 = {-C2, -C2}, w9 = {-C1, S1};
;     x[4 * 1 + 1] = cmul_tw<INV>(x[5], w1); x[4 * 1 + 2] = cmul_tw<INV>(x[6], w2); x[4 * 1 + 3] = cmul_tw<INV>(x[7], w3);
;     x[4 * 2 + 1] = cmul_tw<INV>(x[9], w2); x[4 * 2 + 2] = cmul_tw<INV>(x[10], w4); x[4 * 2 + 3] = cmul_tw<INV>(x[11], w6);
;     x[4 * 3 + 1] = cmul_tw<INV>(x[13], w3); x[4 * 3 + 2] = cmul_tw<INV>(x[14], w6); x[4 * 3 + 3] = cmul_tw<INV>(x[15], w9);
; #pragma unroll
;     for (int c = 0; c < 4; ++c) dft4<INV>(x[4 * c], x[4 * c + 1], x[4 * c + 2], x[4 * c + 3]);
;     f32x2 y[16];
; #pragma unroll
;     for (int k = 0; k < 16; ++k) y[k] = x[4 * (k & 3) + (k >> 2)];
; #pragma unroll
;     for (int k = 0; k < 16; ++k) x[k] = y[k];
; }
; template <int MODE> __device__ __forceinline__ void fft_pair32(LAS f32x2* B, const LAS f32x2* F, int wave, int lane) {
;     ...
;     const int k1 = blk >> 4, k2 = blk & 15, kb1 = (16 - k1) & 15, b1 = k1 != 0 ? 1 : 0, kb2 = (16 - k2 - b1) & 15, b2 = (k2 != 0 || b1) ? 1 : 0;
;     const LAS f32x2* fa = F + 33 * blk; const LAS f32x2* fb = F + 33 * (16 * kb1 + kb2);
;     const LAS f32x2* fah = fa + hi; const LAS f32x2* fbh = fb + (1 - b2) - hi;
;     constexpr float SC = 1.0f / (2.0f * (float)FN);
; #pragma unroll
;     for (int k = 0; k < 16; ++k) { const f32x2 A = fah[2 * k]; f32x2 Bm = fbh[31 - 2 * k];
;         if (k == 0) { const f32x2 m0 = b2 ? fb[31] : fa[0]; Bm = hi ? Bm : m0; }
;         const f32x2 H = MODE == 0 ? (f32x2){(A.x + Bm.x) * SC, (A.y - Bm.y) * SC} : (f32x2){(A.y + Bm.y) * SC, (Bm.x - A.x) * SC};
;         v[k] = cmul(v[k], H); }
	v_pk_mul_f32 v[174:175], v[122:123], s[90:91] op_sel:[1,1] op_sel_hi:[0,1]
	v_pk_fma_f32 v[122:123], v[122:123], s[90:91], v[174:175] op_sel_hi:[1,0,1] neg_lo:[0,0,1]
	v_pk_mul_f32 v[166:167], v[130:131], s[98:99] op_sel:[1,1] op_sel_hi:[0,1]
	v_pk_fma_f32 v[130:131], v[130:131], s[98:99], v[166:167] op_sel_hi:[1,0,1] neg_lo:[0,0,1]
	v_pk_add_f32 v[184:185], v[100:101], v[116:117]
	v_pk_add_f32 v[102:103], v[100:101], v[116:117] neg_lo:[0,1] neg_hi:[0,1]
	v_pk_add_f32 v[180:181], v[108:109], v[124:125]
	v_pk_add_f32 v[168:169], v[108:109], v[124:125] neg_lo:[0,1] neg_hi:[0,1]
	v_pk_add_f32 v[100:101], v[184:185], v[180:181]
	v_pk_add_f32 v[116:117], v[184:185], v[180:181] neg_lo:[0,1] neg_hi:[0,1]
	v_pk_add_f32 v[108:109], v[102:103], v[168:169] op_sel:[0,1] op_sel_hi:[1,0] neg_hi:[0,1]
	v_pk_add_f32 v[124:125], v[102:103], v[168:169] op_sel:[0,1] op_sel_hi:[1,0] neg_lo:[0,1]
	v_pk_add_f32 v[176:177], v[126:127], v[182:183]
	v_pk_add_f32 v[178:179], v[126:127], v[182:183] neg_lo:[0,1] neg_hi:[0,1]
	v_pk_add_f32 v[188:189], v[118:119], v[110:111]
	v_pk_add_f32 v[186:187], v[118:119], v[110:111] neg_lo:[0,1] neg_hi:[0,1]
	v_pk_add_f32 v[126:127], v[176:177], v[188:189]
	v_pk_add_f32 v[182:183], v[176:177], v[188:189] neg_lo:[0,1] neg_hi:[0,1]
	v_pk_add_f32 v[118:119], v[178:179], v[186:187] op_sel:[0,1] op_sel_hi:[1,0] neg_hi:[0,1]
	v_pk_add_f32 v[110:111], v[178:179], v[186:187] op_sel:[0,1] op_sel_hi:[1,0] neg_lo:[0,1]
	v_pk_add_f32 v[174:175], v[104:105], v[120:121] op_sel:[0,1] op_sel_hi:[1,0] neg_hi:[0,1]
	v_pk_add_f32 v[166:167], v[104:105], v[120:121] op_sel:[0,1] op_sel_hi:[1,0] neg_lo:[0,1]
	v_pk_add_f32 v[184:185], v[112:113], v[128:129]
	v_pk_add_f32 v[102:103], v[112:113], v[128:129] neg_lo:[0,1] neg_hi:[0,1]
	v_pk_add_f32 v[104:105], v[174:175], v[184:185]
	v_pk_add_f32 v[120:121], v[174:175], v[184:185] neg_lo:[0,1] neg_hi:[0,1]
	v_pk_add_f32 v[112:113], v[166:167], v[102:103] op_sel:[0,1] op_sel_hi:[1,0] neg_hi:[0,1]
	v_pk_add_f32 v[128:129], v[166:167], v[102:103] op_sel:[0,1] op_sel_hi:[1,0] neg_lo:[0,1]
	v_pk_add_f32 v[180:181], v[106:107], v[122:123]
	v_pk_add_f32 v[168:169], v[106:107], v[122:123] neg_lo:[0,1] neg_hi:[0,1]
	v_pk_add_f32 v[176:177], v[114:115], v[130:131]
	v_pk_add_f32 v[178:179], v[114:115], v[130:131] neg_lo:[0,1] neg_hi:[0,1]
	v_pk_add_f32 v[106:107], v[180:181], v[176:177]
	v_pk_add_f32 v[122:123], v[180:181], v[176:177] neg_lo:[0,1] neg_hi:[0,1]
	v_pk_add_f32 v[114:115], v[168:169], v[178:179] op_sel:[0,1] op_sel_hi:[1,0] neg_hi:[0,1]
	v_pk_add_f32 v[130:131], v[168:169], v[178:179] op_sel:[0,1] op_sel_hi:[1,0] neg_lo:[0,1]
	ds_read_b64 v[188:189], v200
	ds_read_b64 v[184:185], v204
	ds_read_b64 v[186:187], v200 offset:16
	ds_read_b64 v[102:103], v202 offset:232
	ds_read_b64 v[174:175], v200 offset:32
	ds_read_b64 v[180:181], v202 offset:216
	ds_read_b64 v[166:167], v200 offset:48
	ds_read_b64 v[168:169], v202 offset:200
	s_waitcnt lgkmcnt(6)
	v_pk_add_f32 v[188:189], v[188:189], v[184:185] op_sel:[1,1] op_sel_hi:[0,0] neg_hi:[1,0]
	v_pk_mul_f32 v[176:177], v[100:101], v[188:189] op_sel:[1,1] op_sel_hi:[0,1]
	v_pk_fma_f32 v[100:101], v[100:101], v[188:189], v[176:177] op_sel_hi:[1,0,1] neg_lo:[0,0,1]
	s_waitcnt lgkmcnt(4)
	v_pk_add_f32 v[186:187], v[186:187], v[102:103] op_sel:[1,1] op_sel_hi:[0,0] neg_hi:[1,0]
	v_pk_mul_f32 v[178:179], v[126:127], v[186:187] op_sel:[1,1] op_sel_hi:[0,1]
	v_pk_fma_f32 v[126:127], v[126:127], v[186:187], v[178:179] op_sel_hi:[1,0,1] neg_lo:[0,0,1]
	s_waitcnt lgkmcnt(2)
	v_pk_add_f32 v[174:175], v[174:175], v[180:181] op_sel:[1,1] op_sel_hi:[0,0] neg_hi:[1,0]
	v_pk_mul_f32 v[176:177], v[104:105], v[174:175] op_sel:[1,1] op_sel_hi:[0,1]
	v_pk_fma_f32 v[104:105], v[104:105], v[174:175], v[176:177] op_sel_hi:[1,0,1] neg_lo:[0,0,1]
	s_waitcnt lgkmcnt(0)
	v_pk_add_f32 v[166:167], v[166:167], v[168:169] op_sel:[1,1] op_sel_hi:[0,0] neg_hi:[1,0]
	v_pk_mul_f32 v[178:179], v[106:107], v[166:167] op_sel:[1,1] op_sel_hi:[0,1]
	v_pk_fma_f32 v[106:107], v[106:107], v[166:167], v[178:179] op_sel_hi:[1,0,1] neg_lo:[0,0,1]
	ds_read_b64 v[176:177], v200 offset:64
	ds_read_b64 v[174:175], v202 offset:184
	ds_read_b64 v[178:179], v200 offset:80
	ds_read_b64 v[166:167], v202 offset:168
	ds_read_b64 v[188:189], v200 offset:96
	ds_read_b64 v[184:185], v202 offset:152
	ds_read_b64 v[186:187], v200 offset:112
	ds_read_b64 v[102:103], v202 offset:136
	s_waitcnt lgkmcnt(6)
	v_pk_add_f32 v[176:177], v[176:177], v[174:175] op_sel:[1,1] op_sel_hi:[0,0] neg_hi:[1,0]
	v_pk_mul_f32 v[180:181], v[108:109], v[176:177] op_sel:[1,1] op_sel_hi:[0,1]
	v_pk_fma_f32 v[108:109], v[108:109], v[176:177], v[180:181] op_sel_hi:[1,0,1] neg_lo:[0,0,1]
	s_waitcnt lgkmcnt(4)
	v_pk_add_f32 v[178:179], v[178:179], v[166:167] op_sel:[1,1] op_sel_hi:[0,0] neg_hi:[1,0]
	v_pk_mul_f32 v[168:169], v[118:119], v[178:179] op_sel:[1,1] op_sel_hi:[0,1]
	v_pk_fma_f32 v[118:119], v[118:119], v[178:179], v[168:169] op_sel_hi:[1,0,1] neg_lo:[0,0,1]
	s_waitcnt lgkmcnt(2)
	v_pk_add_f32 v[188:189], v[188:189], v[184:185] op_sel:[1,1] op_sel_hi:[0,0] neg_hi:[1,0]
	v_pk_mul_f32 v[180:181], v[112:113], v[188:189] op_sel:[1,1] op_sel_hi:[0,1]
	v_pk_fma_f32 v[112:113], v[112:113], v[188:189], v[180:181] op_sel_hi:[1,0,1] neg_lo:[0,0,1]
	s_waitcnt lgkmcnt(0)
	v_pk_add_f32 v[186:187], v[186:187], v[102:103] op_sel:[1,1] op_sel_hi:[0,0] neg_hi:[1,0]
	v_pk_mul_f32 v[168:169], v[114:115], v[186:187] op_sel:[1,1] op_sel_hi:[0,1]
	v_pk_fma_f32 v[114:115], v[114:115], v[186:187], v[168:169] op_sel_hi:[1,0,1] neg_lo:[0,0,1]
	ds_read_b64 v[180:181], v200 offset:128
	ds_read_b64 v[188:189], v202 offset:120
	ds_read_b64 v[168:169], v200 offset:144
	ds_read_b64 v[186:187], v202 offset:104
	ds_read_b64 v[176:177], v200 offset:160
	ds_read_b64 v[174:175], v202 offset:88
	ds_read_b64 v[178:179], v200 offset:176
	ds_read_b64 v[166:167], v202 offset:72
	s_waitcnt lgkmcnt(6)
; #define LAS __attribute__((address_space(3)))
; __device__ __forceinline__ f32x2 cmul(f32x2 a, f32x2 b) { return (f32x2){a.x * b.x - a.y * b.y, a.x * b.y + a.y * b.x}; }
; template <bool INV> __device__ __forceinline__ f32x2 cmul_tw(f32x2 a, f32x2 w) { return INV ? cmulc(a, w) : cmul(a, w); }
; template <bool INV> __device__ __forceinline__ void dft16(f32x2 (&x)[16]) {
;     constexpr float C1 = 0.92387953251128674f, S1 = 0.38268343236508977f, C2 = 0.70710678118654752f;
; #pragma unroll
;     for (int b = 0; b < 4; ++b) dft4<INV>(x[b], x[4 + b], x[8 + b], x[12 + b]);
;     const f32x2 w1 = {C1, -S1}, w2 = {C2, -C2}, w3 = {S1, -C1}, w4 = {0.f, -1.f}, w6 = {-C2, -C2}, w9 = {-C1, S1};
;     x[4 * 1 + 1] = cmul_tw<INV>(x[5], w1); x[4 * 1 + 2] = cmul_tw<INV>(x[6], w2); x[4 * 1 + 3] = cmul_tw<INV>(x[7], w3);
;     x[4 * 2 + 1] = cmul_tw<INV>(x[9], w2); x[4 * 2 + 2] = cmul_tw<INV>(x[10], w4); x[4 * 2 + 3] = cmul_tw<INV>(x[11], w6);
;     x[4 * 3 + 1] = cmul_tw<INV>(x[13], w3); x[4 * 3 + 2] = cmul_tw<INV>(x[14], w6); x[4 * 3 + 3] = cmul_tw<INV>(x[15], w9);
; #pragma unroll
;     for (int c = 0; c < 4; ++c) dft4<INV>(x[4 * c], x[4 * c + 1], x[4 * c + 2], x[4 * c + 3]);
; template <int MODE> __device__ __forceinline__ void fft_pair32(LAS f32x2* B, const LAS f32x2* F, int wave, int lane) {
;     ...
;     const int k1 = blk >> 4, k2 = blk & 15, kb1 = (16 - k1) & 15, b1 = k1 != 0 ? 1 : 0, kb2 = (16 - k2 - b1) & 15, b2 = (k2 != 0 || b1) ? 1 : 0;
;     const LAS f32x2* fa = F + 33 * blk; const LAS f32x2* fb = F + 33 * (16 * kb1 + kb2);
;     const LAS f32x2* fah = fa + hi; const LAS f32x2* fbh = fb + (1 - b2) - hi;
;     constexpr float SC = 1.0f / (2.0f * (float)FN);
; #pragma unroll
;     for (int k = 0; k < 16; ++k) { const f32x2 A = fah[2 * k]; f32x2 Bm = fbh[31 - 2 * k];
;         if (k == 0) { const f32x2 m0 = b2 ? fb[31] : fa[0]; Bm = hi ? Bm : m0; }
;         const f32x2 H = MODE == 0 ? (f32x2){(A.x + Bm.x) * SC, (A.y - Bm.y) * SC} : (f32x2){(A.y + Bm.y) * SC, (Bm.x - A.x) * SC};
;         v[k] = cmul(v[k], H); }
;     dft16<true>(v);
	v_pk_add_f32 v[180:181], v[180:181], v[188:189] op_sel:[1,1] op_sel_hi:[0,0] neg_hi:[1,0]
	v_pk_mul_f32 v[184:185], v[116:117], v[180:181] op_sel:[1,1] op_sel_hi:[0,1]
	v_pk_fma_f32 v[116:117], v[116:117], v[180:181], v[184:185] op_sel_hi:[1,0,1] neg_lo:[0,0,1]
	s_waitcnt lgkmcnt(4)
	v_pk_add_f32 v[168:169], v[168:169], v[186:187] op_sel:[1,1] op_sel_hi:[0,0] neg_hi:[1,0]
	v_pk_mul_f32 v[102:103], v[182:183], v[168:169] op_sel:[1,1] op_sel_hi:[0,1]
	v_pk_fma_f32 v[182:183], v[182:183], v[168:169], v[102:103] op_sel_hi:[1,0,1] neg_lo:[0,0,1]
	s_waitcnt lgkmcnt(2)
	v_pk_add_f32 v[176:177], v[176:177], v[174:175] op_sel:[1,1] op_sel_hi:[0,0] neg_hi:[1,0]
	v_pk_mul_f32 v[184:185], v[120:121], v[176:177] op_sel:[1,1] op_sel_hi:[0,1]
	v_pk_fma_f32 v[120:121], v[120:121], v[176:177], v[184:185] op_sel_hi:[1,0,1] neg_lo:[0,0,1]
	s_waitcnt lgkmcnt(0)
	v_pk_add_f32 v[178:179], v[178:179], v[166:167] op_sel:[1,1] op_sel_hi:[0,0] neg_hi:[1,0]
	v_pk_mul_f32 v[102:103], v[122:123], v[178:179] op_sel:[1,1] op_sel_hi:[0,1]
	v_pk_fma_f32 v[122:123], v[122:123], v[178:179], v[102:103] op_sel_hi:[1,0,1] neg_lo:[0,0,1]
	ds_read_b64 v[184:185], v200 offset:192
	ds_read_b64 v[176:177], v202 offset:56
	ds_read_b64 v[102:103], v200 offset:208
	ds_read_b64 v[178:179], v202 offset:40
	ds_read_b64 v[180:181], v200 offset:224
	ds_read_b64 v[188:189], v202 offset:24
	ds_read_b64 v[168:169], v200 offset:240
	ds_read_b64 v[186:187], v202 offset:8
	s_waitcnt lgkmcnt(6)
	v_pk_add_f32 v[184:185], v[184:185], v[176:177] op_sel:[1,1] op_sel_hi:[0,0] neg_hi:[1,0]
	v_pk_mul_f32 v[174:175], v[124:125], v[184:185] op_sel:[1,1] op_sel_hi:[0,1]
	v_pk_fma_f32 v[124:125], v[124:125], v[184:185], v[174:175] op_sel_hi:[1,0,1] neg_lo:[0,0,1]
	s_waitcnt lgkmcnt(4)
	v_pk_add_f32 v[102:103], v[102:103], v[178:179] op_sel:[1,1] op_sel_hi:[0,0] neg_hi:[1,0]
	v_pk_mul_f32 v[166:167], v[110:111], v[102:103] op_sel:[1,1] op_sel_hi:[0,1]
	v_pk_fma_f32 v[110:111], v[110:111], v[102:103], v[166:167] op_sel_hi:[1,0,1] neg_lo:[0,0,1]
	s_waitcnt lgkmcnt(2)
	v_pk_add_f32 v[180:181], v[180:181], v[188:189] op_sel:[1,1] op_sel_hi:[0,0] neg_hi:[1,0]
	v_pk_mul_f32 v[174:175], v[128:129], v[180:181] op_sel:[1,1] op_sel_hi:[0,1]
	v_pk_fma_f32 v[128:129], v[128:129], v[180:181], v[174:175] op_sel_hi:[1,0,1] neg_lo:[0,0,1]
	s_waitcnt lgkmcnt(0)
	v_pk_add_f32 v[168:169], v[168:169], v[186:187] op_sel:[1,1] op_sel_hi:[0,0] neg_hi:[1,0]
	v_pk_mul_f32 v[166:167], v[130:131], v[168:169] op_sel:[1,1] op_sel_hi:[0,1]
	v_pk_fma_f32 v[130:131], v[130:131], v[168:169], v[166:167] op_sel_hi:[1,0,1] neg_lo:[0,0,1]
	v_pk_add_f32 v[174:175], v[100:101], v[116:117]
	v_pk_add_f32 v[166:167], v[100:101], v[116:117] neg_lo:[0,1] neg_hi:[0,1]
	v_pk_add_f32 v[184:185], v[108:109], v[124:125]
	v_pk_add_f32 v[102:103], v[108:109], v[124:125] neg_lo:[0,1] neg_hi:[0,1]
	v_pk_add_f32 v[100:101], v[174:175], v[184:185]
	v_pk_add_f32 v[116:117], v[174:175], v[184:185] neg_lo:[0,1] neg_hi:[0,1]
	v_pk_add_f32 v[108:109], v[166:167], v[102:103] op_sel:[0,1] op_sel_hi:[1,0] neg_lo:[0,1]
	v_pk_add_f32 v[124:125], v[166:167], v[102:103] op_sel:[0,1] op_sel_hi:[1,0] neg_hi:[0,1]
	v_pk_add_f32 v[180:181], v[126:127], v[182:183]
	v_pk_add_f32 v[168:169], v[126:127], v[182:183] neg_lo:[0,1] neg_hi:[0,1]
	v_pk_add_f32 v[176:177], v[118:119], v[110:111]
	v_pk_add_f32 v[178:179], v[118:119], v[110:111] neg_lo:[0,1] neg_hi:[0,1]
	v_pk_add_f32 v[126:127], v[180:181], v[176:177]
	v_pk_add_f32 v[182:183], v[180:181], v[176:177] neg_lo:[0,1] neg_hi:[0,1]
	v_pk_add_f32 v[118:119], v[168:169], v[178:179] op_sel:[0,1] op_sel_hi:[1,0] neg_lo:[0,1]
	v_pk_add_f32 v[110:111], v[168:169], v[178:179] op_sel:[0,1] op_sel_hi:[1,0] neg_hi:[0,1]
	v_pk_add_f32 v[188:189], v[104:105], v[120:121]
	v_pk_add_f32 v[186:187], v[104:105], v[120:121] neg_lo:[0,1] neg_hi:[0,1]
	v_pk_add_f32 v[174:175], v[112:113], v[128:129]
	v_pk_add_f32 v[166:167], v[112:113], v[128:129] neg_lo:[0,1] neg_hi:[0,1]
	v_pk_add_f32 v[104:105], v[188:189], v[174:175]
	v_pk_add_f32 v[120:121], v[188:189], v[174:175] neg_lo:[0,1] neg_hi:[0,1]
	v_pk_add_f32 v[112:113], v[186:187], v[166:167] op_sel:[0,1] op_sel_hi:[1,0] neg_lo:[0,1]
	v_pk_add_f32 v[128:129], v[186:187], v[166:167] op_sel:[0,1] op_sel_hi:[1,0] neg_hi:[0,1]
	v_pk_add_f32 v[184:185], v[106:107], v[122:123]
	v_pk_add_f32 v[102:103], v[106:107], v[122:123] neg_lo:[0,1] neg_hi:[0,1]
	v_pk_add_f32 v[180:181], v[114:115], v[130:131]
	v_pk_add_f32 v[168:169], v[114:115], v[130:131] neg_lo:[0,1] neg_hi:[0,1]
	v_pk_add_f32 v[106:107], v[184:185], v[180:181]
	v_pk_add_f32 v[122:123], v[184:185], v[180:181] neg_lo:[0,1] neg_hi:[0,1]
	v_pk_add_f32 v[114:115], v[102:103], v[168:169] op_sel:[0,1] op_sel_hi:[1,0] neg_lo:[0,1]
	v_pk_add_f32 v[130:131], v[102:103], v[168:169] op_sel:[0,1] op_sel_hi:[1,0] neg_hi:[0,1]
	v_pk_mul_f32 v[176:177], v[118:119], s[68:69] op_sel:[1,1] op_sel_hi:[0,1]
	v_pk_fma_f32 v[118:119], v[118:119], s[68:69], v[176:177] op_sel_hi:[1,0,1] neg_hi:[0,0,1]
	v_pk_mul_f32 v[178:179], v[112:113], s[84:85] op_sel:[1,1] op_sel_hi:[0,1]
	v_pk_fma_f32 v[112:113], v[112:113], s[84:85], v[178:179] op_sel_hi:[1,0,1] neg_hi:[0,0,1]
	v_pk_mul_f32 v[188:189], v[114:115], s[88:89] op_sel:[1,1] op_sel_hi:[0,1]
	v_pk_fma_f32 v[114:115], v[114:115], s[88:89], v[188:189] op_sel_hi:[1,0,1] neg_hi:[0,0,1]
	v_pk_mul_f32 v[186:187], v[182:183], s[84:85] op_sel:[1,1] op_sel_hi:[0,1]
	v_pk_fma_f32 v[182:183], v[182:183], s[84:85], v[186:187] op_sel_hi:[1,0,1] neg_hi:[0,0,1]
	v_pk_mul_f32 v[174:175], v[122:123], s[90:91] op_sel:[1,1] op_sel_hi:[0,1]
	v_pk_fma_f32 v[122:123], v[122:123], s[90:91], v[174:175] op_sel_hi:[1,0,1] neg_hi:[0,0,1]
; __device__ __forceinline__ f32x2 cmulc(f32x2 a, f32x2 b) { return (f32x2){a.x * b.x + a.y * b.y, a.y * b.x - a.x * b.y}; }
; template <bool INV> __device__ __forceinline__ f32x2 cmul_tw(f32x2 a, f32x2 w) { return INV ? cmulc(a, w) : cmul(a, w); }
; template <bool INV> __device__ __forceinline__ void dft16(f32x2 (&x)[16]) {
;     constexpr float C1 = 0.92387953251128674f, S1 = 0.38268343236508977f, C2 = 0.70710678118654752f;
; #pragma unroll
;     for (int b = 0; b < 4; ++b) dft4<INV>(x[b], x[4 + b], x[8 + b], x[12 + b]);
;     const f32x2 w1 = {C1, -S1}, w2 = {C2, -C2}, w3 = {S1, -C1}, w4 = {0.f, -1.f}, w6 = {-C2, -C2}, w9 = {-C1, S1};
;     x[4 * 1 + 1] = cmul_tw<INV>(x[5], w1); x[4 * 1 + 2] = cmul_tw<INV>(x[6], w2); x[4 * 1 + 3] = cmul_tw<INV>(x[7], w3);
;     x[4 * 2 + 1] = cmul_tw<INV>(x[9], w2); x[4 * 2 + 2] = cmul_tw<INV>(x[10], w4); x[4 * 2 + 3] = cmul_tw<INV>(x[11], w6);
;     x[4 * 3 + 1] = cmul_tw<INV>(x[13], w3); x[4 * 3 + 2] = cmul_tw<INV>(x[14], w6); x[4 * 3 + 3] = cmul_tw<INV>(x[15], w9);
; #pragma unroll
;     for (int c = 0; c < 4; ++c) dft4<INV>(x[4 * c], x[4 * c + 1], x[4 * c + 2], x[4 * c + 3]);
;     f32x2 y[16];
; #pragma unroll
;     for (int k = 0; k < 16; ++k) y[k] = x[4 * (k & 3) + (k >> 2)];
; #pragma unroll
;     for (int k = 0; k < 16; ++k) x[k] = y[k];
; }
; template <int MODE> __device__ __forceinline__ void fft_pair32(LAS f32x2* B, const LAS f32x2* F, int wave, int lane) {
;     ...
;     dft16<true>(v);
; #pragma unroll
;     for (int j = 0; j < 16; ++j) { const f32x2 w = {hi ? CS[j] : 1.f, hi ? -SN[j] : 0.f}; const f32x2 u = j == 0 ? v[j] : cmulc(v[j], w);
;         const auto rx = __builtin_amdgcn_permlane32_swap(__float_as_uint(u.x), __float_as_uint(u.x), false, false);
;         const auto ry = __builtin_amdgcn_permlane32_swap(__float_as_uint(u.y), __float_as_uint(u.y), false, false);
;         const f32x2 a = {__uint_as_float(rx[0]), __uint_as_float(ry[0])}, b = {__uint_as_float(rx[1]), __uint_as_float(ry[1])};
;         p[16 * hi + j] = a + b * sg; }
	v_pk_mul_f32 v[166:167], v[110:111], s[88:89] op_sel:[1,1] op_sel_hi:[0,1]
	v_pk_fma_f32 v[110:111], v[110:111], s[88:89], v[166:167] op_sel_hi:[1,0,1] neg_hi:[0,0,1]
	v_pk_mul_f32 v[184:185], v[128:129], s[90:91] op_sel:[1,1] op_sel_hi:[0,1]
	v_pk_fma_f32 v[128:129], v[128:129], s[90:91], v[184:185] op_sel_hi:[1,0,1] neg_hi:[0,0,1]
	v_pk_mul_f32 v[102:103], v[130:131], s[98:99] op_sel:[1,1] op_sel_hi:[0,1]
	v_pk_fma_f32 v[130:131], v[130:131], s[98:99], v[102:103] op_sel_hi:[1,0,1] neg_hi:[0,0,1]
	v_pk_add_f32 v[180:181], v[100:101], v[104:105]
	v_pk_add_f32 v[168:169], v[100:101], v[104:105] neg_lo:[0,1] neg_hi:[0,1]
	v_pk_add_f32 v[176:177], v[126:127], v[106:107]
	v_pk_add_f32 v[178:179], v[126:127], v[106:107] neg_lo:[0,1] neg_hi:[0,1]
	v_pk_add_f32 v[100:101], v[180:181], v[176:177]
	v_pk_add_f32 v[104:105], v[180:181], v[176:177] neg_lo:[0,1] neg_hi:[0,1]
	v_pk_add_f32 v[126:127], v[168:169], v[178:179] op_sel:[0,1] op_sel_hi:[1,0] neg_lo:[0,1]
	v_pk_add_f32 v[106:107], v[168:169], v[178:179] op_sel:[0,1] op_sel_hi:[1,0] neg_hi:[0,1]
	v_pk_add_f32 v[188:189], v[108:109], v[112:113]
	v_pk_add_f32 v[186:187], v[108:109], v[112:113] neg_lo:[0,1] neg_hi:[0,1]
	v_pk_add_f32 v[174:175], v[118:119], v[114:115]
	v_pk_add_f32 v[166:167], v[118:119], v[114:115] neg_lo:[0,1] neg_hi:[0,1]
	v_pk_add_f32 v[108:109], v[188:189], v[174:175]
	v_pk_add_f32 v[112:113], v[188:189], v[174:175] neg_lo:[0,1] neg_hi:[0,1]
	v_pk_add_f32 v[118:119], v[186:187], v[166:167] op_sel:[0,1] op_sel_hi:[1,0] neg_lo:[0,1]
	v_pk_add_f32 v[114:115], v[186:187], v[166:167] op_sel:[0,1] op_sel_hi:[1,0] neg_hi:[0,1]
	v_pk_add_f32 v[184:185], v[116:117], v[120:121] op_sel:[0,1] op_sel_hi:[1,0] neg_lo:[0,1]
	v_pk_add_f32 v[102:103], v[116:117], v[120:121] op_sel:[0,1] op_sel_hi:[1,0] neg_hi:[0,1]
	v_pk_add_f32 v[180:181], v[182:183], v[122:123]
	v_pk_add_f32 v[168:169], v[182:183], v[122:123] neg_lo:[0,1] neg_hi:[0,1]
	v_pk_add_f32 v[116:117], v[184:185], v[180:181]
	v_pk_add_f32 v[120:121], v[184:185], v[180:181] neg_lo:[0,1] neg_hi:[0,1]
	v_pk_add_f32 v[182:183], v[102:103], v[168:169] op_sel:[0,1] op_sel_hi:[1,0] neg_lo:[0,1]
	v_pk_add_f32 v[122:123], v[102:103], v[168:169] op_sel:[0,1] op_sel_hi:[1,0] neg_hi:[0,1]
	v_pk_add_f32 v[176:177], v[124:125], v[128:129]
	v_pk_add_f32 v[178:179], v[124:125], v[128:129] neg_lo:[0,1] neg_hi:[0,1]
	v_pk_add_f32 v[188:189], v[110:111], v[130:131]
	v_pk_add_f32 v[186:187], v[110:111], v[130:131] neg_lo:[0,1] neg_hi:[0,1]
	v_pk_add_f32 v[124:125], v[176:177], v[188:189]
	v_pk_add_f32 v[128:129], v[176:177], v[188:189] neg_lo:[0,1] neg_hi:[0,1]
	v_pk_add_f32 v[110:111], v[178:179], v[186:187] op_sel:[0,1] op_sel_hi:[1,0] neg_lo:[0,1]
	v_pk_add_f32 v[130:131], v[178:179], v[186:187] op_sel:[0,1] op_sel_hi:[1,0] neg_hi:[0,1]
	v_mov_b32_e32 v174, v100
	v_mov_b32_e32 v175, v101
	v_pk_mul_f32 v[180:181], v[108:109], v[36:37] op_sel:[1,1] op_sel_hi:[0,1]
	v_pk_fma_f32 v[166:167], v[108:109], v[36:37], v[180:181] op_sel_hi:[1,0,1] neg_hi:[0,0,1]
	v_pk_fma_f32 v[108:109], v[108:109], v[36:37], v[180:181] op_sel_hi:[1,0,1] neg_hi:[0,0,1]
	v_pk_mul_f32 v[168:169], v[116:117], v[38:39] op_sel:[1,1] op_sel_hi:[0,1]
	v_pk_fma_f32 v[184:185], v[116:117], v[38:39], v[168:169] op_sel_hi:[1,0,1] neg_hi:[0,0,1]
	v_pk_fma_f32 v[116:117], v[116:117], v[38:39], v[168:169] op_sel_hi:[1,0,1] neg_hi:[0,0,1]
	v_pk_mul_f32 v[176:177], v[124:125], v[40:41] op_sel:[1,1] op_sel_hi:[0,1]
	v_pk_fma_f32 v[102:103], v[124:125], v[40:41], v[176:177] op_sel_hi:[1,0,1] neg_hi:[0,0,1]
	v_pk_fma_f32 v[124:125], v[124:125], v[40:41], v[176:177] op_sel_hi:[1,0,1] neg_hi:[0,0,1]
	s_nop 1
	v_permlane32_swap_b32_e32 v100, v174
	v_permlane32_swap_b32_e32 v101, v175
	v_permlane32_swap_b32_e32 v108, v166
	v_permlane32_swap_b32_e32 v109, v167
	v_permlane32_swap_b32_e32 v116, v184
	v_permlane32_swap_b32_e32 v117, v185
	v_permlane32_swap_b32_e32 v124, v102
	v_permlane32_swap_b32_e32 v125, v103
	v_pk_fma_f32 v[100:101], v[174:175], v[190:191], v[100:101] op_sel_hi:[1,0,1]
	ds_write_b64 v198, v[100:101]
	v_pk_fma_f32 v[108:109], v[166:167], v[190:191], v[108:109] op_sel_hi:[1,0,1]
	ds_write_b64 v198, v[108:109] offset:8
	v_pk_fma_f32 v[116:117], v[184:185], v[190:191], v[116:117] op_sel_hi:[1,0,1]
	ds_write_b64 v198, v[116:117] offset:16
	v_pk_fma_f32 v[124:125], v[102:103], v[190:191], v[124:125] op_sel_hi:[1,0,1]
	ds_write_b64 v198, v[124:125] offset:24
	v_pk_mul_f32 v[168:169], v[126:127], v[42:43] op_sel:[1,1] op_sel_hi:[0,1]
	v_pk_fma_f32 v[178:179], v[126:127], v[42:43], v[168:169] op_sel_hi:[1,0,1] neg_hi:[0,0,1]
	v_pk_fma_f32 v[126:127], v[126:127], v[42:43], v[168:169] op_sel_hi:[1,0,1] neg_hi:[0,0,1]
	v_pk_mul_f32 v[176:177], v[118:119], v[44:45] op_sel:[1,1] op_sel_hi:[0,1]
	v_pk_fma_f32 v[188:189], v[118:119], v[44:45], v[176:177] op_sel_hi:[1,0,1] neg_hi:[0,0,1]
	v_pk_fma_f32 v[118:119], v[118:119], v[44:45], v[176:177] op_sel_hi:[1,0,1] neg_hi:[0,0,1]
	v_pk_mul_f32 v[174:175], v[182:183], v[46:47] op_sel:[1,1] op_sel_hi:[0,1]
	v_pk_fma_f32 v[186:187], v[182:183], v[46:47], v[174:175] op_sel_hi:[1,0,1] neg_hi:[0,0,1]
	v_pk_fma_f32 v[182:183], v[182:183], v[46:47], v[174:175] op_sel_hi:[1,0,1] neg_hi:[0,0,1]
	v_pk_mul_f32 v[166:167], v[110:111], v[48:49] op_sel:[1,1] op_sel_hi:[0,1]
	v_pk_fma_f32 v[180:181], v[110:111], v[48:49], v[166:167] op_sel_hi:[1,0,1] neg_hi:[0,0,1]
	v_pk_fma_f32 v[110:111], v[110:111], v[48:49], v[166:167] op_sel_hi:[1,0,1] neg_hi:[0,0,1]
	s_nop 1
	v_permlane32_swap_b32_e32 v126, v178
	v_permlane32_swap_b32_e32 v127, v179
	v_permlane32_swap_b32_e32 v118, v188
	v_permlane32_swap_b32_e32 v119, v189
	v_permlane32_swap_b32_e32 v182, v186
; #define LAS __attribute__((address_space(3)))
; __device__ __forceinline__ f32x2 cmulc(f32x2 a, f32x2 b) { return (f32x2){a.x * b.x + a.y * b.y, a.y * b.x - a.x * b.y}; }
; __device__ __forceinline__ void fft_inv2(LAS f32x2* B, const LAS f32x2* TW2, int tid) {
;     asm volatile("" : "+v"(tid));
;     const int b = tid >> 5, n2 = tid & 31, base = 512 * b + n2; f32x2 x[16];
;     x[0] = B[fpad(base)];
; #pragma unroll
;     for (int k = 1; k < 16; ++k) x[k] = cmulc(B[fpad(base + 32 * k)], TW2[k * 32 + n2]);
; template <int MODE> __device__ __forceinline__ void fft_pair32(LAS f32x2* B, const LAS f32x2* F, int wave, int lane) {
;     ...
;     dft16<true>(v);
; #pragma unroll
;     for (int j = 0; j < 16; ++j) { const f32x2 w = {hi ? CS[j] : 1.f, hi ? -SN[j] : 0.f}; const f32x2 u = j == 0 ? v[j] : cmulc(v[j], w);
;         const auto rx = __builtin_amdgcn_permlane32_swap(__float_as_uint(u.x), __float_as_uint(u.x), false, false);
;         const auto ry = __builtin_amdgcn_permlane32_swap(__float_as_uint(u.y), __float_as_uint(u.y), false, false);
;         const f32x2 a = {__uint_as_float(rx[0]), __uint_as_float(ry[0])}, b = {__uint_as_float(rx[1]), __uint_as_float(ry[1])};
;         p[16 * hi + j] = a + b * sg; }
	v_permlane32_swap_b32_e32 v183, v187
	v_permlane32_swap_b32_e32 v110, v180
	v_permlane32_swap_b32_e32 v111, v181
	v_pk_fma_f32 v[126:127], v[178:179], v[190:191], v[126:127] op_sel_hi:[1,0,1]
	ds_write_b64 v198, v[126:127] offset:32
	v_pk_fma_f32 v[118:119], v[188:189], v[190:191], v[118:119] op_sel_hi:[1,0,1]
	ds_write_b64 v198, v[118:119] offset:40
	v_pk_fma_f32 v[182:183], v[186:187], v[190:191], v[182:183] op_sel_hi:[1,0,1]
	ds_write_b64 v198, v[182:183] offset:48
	v_pk_fma_f32 v[110:111], v[180:181], v[190:191], v[110:111] op_sel_hi:[1,0,1]
	ds_write_b64 v198, v[110:111] offset:56
	v_pk_mul_f32 v[174:175], v[104:105], v[50:51] op_sel:[1,1] op_sel_hi:[0,1]
	v_pk_fma_f32 v[184:185], v[104:105], v[50:51], v[174:175] op_sel_hi:[1,0,1] neg_hi:[0,0,1]
	v_pk_fma_f32 v[104:105], v[104:105], v[50:51], v[174:175] op_sel_hi:[1,0,1] neg_hi:[0,0,1]
	v_pk_mul_f32 v[166:167], v[112:113], v[52:53] op_sel:[1,1] op_sel_hi:[0,1]
	v_pk_fma_f32 v[102:103], v[112:113], v[52:53], v[166:167] op_sel_hi:[1,0,1] neg_hi:[0,0,1]
	v_pk_fma_f32 v[112:113], v[112:113], v[52:53], v[166:167] op_sel_hi:[1,0,1] neg_hi:[0,0,1]
	v_pk_mul_f32 v[178:179], v[120:121], v[54:55] op_sel:[1,1] op_sel_hi:[0,1]
	v_pk_fma_f32 v[168:169], v[120:121], v[54:55], v[178:179] op_sel_hi:[1,0,1] neg_hi:[0,0,1]
	v_pk_fma_f32 v[120:121], v[120:121], v[54:55], v[178:179] op_sel_hi:[1,0,1] neg_hi:[0,0,1]
	v_pk_mul_f32 v[188:189], v[128:129], v[90:91] op_sel:[1,1] op_sel_hi:[0,1]
	v_pk_fma_f32 v[176:177], v[128:129], v[90:91], v[188:189] op_sel_hi:[1,0,1] neg_hi:[0,0,1]
	v_pk_fma_f32 v[128:129], v[128:129], v[90:91], v[188:189] op_sel_hi:[1,0,1] neg_hi:[0,0,1]
	s_nop 1
	v_permlane32_swap_b32_e32 v104, v184
	v_permlane32_swap_b32_e32 v105, v185
	v_permlane32_swap_b32_e32 v112, v102
	v_permlane32_swap_b32_e32 v113, v103
	v_permlane32_swap_b32_e32 v120, v168
	v_permlane32_swap_b32_e32 v121, v169
	v_permlane32_swap_b32_e32 v128, v176
	v_permlane32_swap_b32_e32 v129, v177
	v_pk_fma_f32 v[104:105], v[184:185], v[190:191], v[104:105] op_sel_hi:[1,0,1]
	ds_write_b64 v198, v[104:105] offset:64
	v_pk_fma_f32 v[112:113], v[102:103], v[190:191], v[112:113] op_sel_hi:[1,0,1]
	ds_write_b64 v198, v[112:113] offset:72
	v_pk_fma_f32 v[120:121], v[168:169], v[190:191], v[120:121] op_sel_hi:[1,0,1]
	ds_write_b64 v198, v[120:121] offset:80
	v_pk_fma_f32 v[128:129], v[176:177], v[190:191], v[128:129] op_sel_hi:[1,0,1]
	ds_write_b64 v198, v[128:129] offset:88
	v_pk_mul_f32 v[178:179], v[106:107], v[92:93] op_sel:[1,1] op_sel_hi:[0,1]
	v_pk_fma_f32 v[186:187], v[106:107], v[92:93], v[178:179] op_sel_hi:[1,0,1] neg_hi:[0,0,1]
	v_pk_fma_f32 v[106:107], v[106:107], v[92:93], v[178:179] op_sel_hi:[1,0,1] neg_hi:[0,0,1]
	v_pk_mul_f32 v[188:189], v[114:115], v[94:95] op_sel:[1,1] op_sel_hi:[0,1]
	v_pk_fma_f32 v[180:181], v[114:115], v[94:95], v[188:189] op_sel_hi:[1,0,1] neg_hi:[0,0,1]
	v_pk_fma_f32 v[114:115], v[114:115], v[94:95], v[188:189] op_sel_hi:[1,0,1] neg_hi:[0,0,1]
	v_pk_mul_f32 v[184:185], v[122:123], v[96:97] op_sel:[1,1] op_sel_hi:[0,1]
	v_pk_fma_f32 v[174:175], v[122:123], v[96:97], v[184:185] op_sel_hi:[1,0,1] neg_hi:[0,0,1]
	v_pk_fma_f32 v[122:123], v[122:123], v[96:97], v[184:185] op_sel_hi:[1,0,1] neg_hi:[0,0,1]
	v_pk_mul_f32 v[102:103], v[130:131], v[98:99] op_sel:[1,1] op_sel_hi:[0,1]
	v_pk_fma_f32 v[166:167], v[130:131], v[98:99], v[102:103] op_sel_hi:[1,0,1] neg_hi:[0,0,1]
	v_pk_fma_f32 v[130:131], v[130:131], v[98:99], v[102:103] op_sel_hi:[1,0,1] neg_hi:[0,0,1]
	s_nop 1
	v_permlane32_swap_b32_e32 v106, v186
	v_permlane32_swap_b32_e32 v107, v187
	v_permlane32_swap_b32_e32 v114, v180
	v_permlane32_swap_b32_e32 v115, v181
	v_permlane32_swap_b32_e32 v122, v174
	v_permlane32_swap_b32_e32 v123, v175
	v_permlane32_swap_b32_e32 v130, v166
	v_permlane32_swap_b32_e32 v131, v167
	v_pk_fma_f32 v[106:107], v[186:187], v[190:191], v[106:107] op_sel_hi:[1,0,1]
	ds_write_b64 v198, v[106:107] offset:96
	v_pk_fma_f32 v[114:115], v[180:181], v[190:191], v[114:115] op_sel_hi:[1,0,1]
	ds_write_b64 v198, v[114:115] offset:104
	v_pk_fma_f32 v[122:123], v[174:175], v[190:191], v[122:123] op_sel_hi:[1,0,1]
	ds_write_b64 v198, v[122:123] offset:112
	v_pk_fma_f32 v[130:131], v[166:167], v[190:191], v[130:131] op_sel_hi:[1,0,1]
	ds_write_b64 v198, v[130:131] offset:120
	s_waitcnt lgkmcnt(0)
	ds_read_b64 v[100:101], v5
	ds_read_b64 v[108:109], v5 offset:264
	ds_read_b64 v[168:169], v56 offset:256
	ds_read_b64 v[116:117], v5 offset:528
	ds_read_b64 v[176:177], v56 offset:512
	ds_read_b64 v[124:125], v5 offset:792
	ds_read_b64 v[178:179], v56 offset:768
	ds_read_b64 v[126:127], v5 offset:1056
	ds_read_b64 v[188:189], v56 offset:1024
	ds_read_b64 v[118:119], v5 offset:1320
	ds_read_b64 v[184:185], v56 offset:1280
	s_waitcnt lgkmcnt(8)
	v_pk_mul_f32 v[102:103], v[108:109], v[168:169] op_sel:[1,1] op_sel_hi:[0,1]
	v_pk_fma_f32 v[108:109], v[108:109], v[168:169], v[102:103] op_sel_hi:[1,0,1] neg_hi:[0,0,1]
	s_waitcnt lgkmcnt(6)
	v_pk_mul_f32 v[186:187], v[116:117], v[176:177] op_sel:[1,1] op_sel_hi:[0,1]
	v_pk_fma_f32 v[116:117], v[116:117], v[176:177], v[186:187] op_sel_hi:[1,0,1] neg_hi:[0,0,1]
	s_waitcnt lgkmcnt(4)
	v_pk_mul_f32 v[180:181], v[124:125], v[178:179] op_sel:[1,1] op_sel_hi:[0,1]
	v_pk_fma_f32 v[124:125], v[124:125], v[178:179], v[180:181] op_sel_hi:[1,0,1] neg_hi:[0,0,1]
	s_waitcnt lgkmcnt(2)
	v_pk_mul_f32 v[174:175], v[126:127], v[188:189] op_sel:[1,1] op_sel_hi:[0,1]
	v_pk_fma_f32 v[126:127], v[126:127], v[188:189], v[174:175] op_sel_hi:[1,0,1] neg_hi:[0,0,1]
	s_waitcnt lgkmcnt(0)
; #define LAS __attribute__((address_space(3)))
; __device__ __forceinline__ f32x2 cmulc(f32x2 a, f32x2 b) { return (f32x2){a.x * b.x + a.y * b.y, a.y * b.x - a.x * b.y}; }
; template <bool INV> __device__ __forceinline__ f32x2 cmul_tw(f32x2 a, f32x2 w) { return INV ? cmulc(a, w) : cmul(a, w); }
; template <bool INV> __device__ __forceinline__ void dft16(f32x2 (&x)[16]) {
;     constexpr float C1 = 0.92387953251128674f, S1 = 0.38268343236508977f, C2 = 0.70710678118654752f;
; #pragma unroll
;     for (int b = 0; b < 4; ++b) dft4<INV>(x[b], x[4 + b], x[8 + b], x[12 + b]);
;     const f32x2 w1 = {C1, -S1}, w2 = {C2, -C2}, w3 = {S1, -C1}, w4 = {0.f, -1.f}, w6 = {-C2, -C2}, w9 = {-C1, S1};
;     x[4 * 1 + 1] = cmul_tw<INV>(x[5], w1); x[4 * 1 + 2] = cmul_tw<INV>(x[6], w2); x[4 * 1 + 3] = cmul_tw<INV>(x[7], w3);
;     x[4 * 2 + 1] = cmul_tw<INV>(x[9], w2); x[4 * 2 + 2] = cmul_tw<INV>(x[10], w4); x[4 * 2 + 3] = cmul_tw<INV>(x[11], w6);
;     x[4 * 3 + 1] = cmul_tw<INV>(x[13], w3); x[4 * 3 + 2] = cmul_tw<INV>(x[14], w6); x[4 * 3 + 3] = cmul_tw<INV>(x[15], w9);
; #pragma unroll
;     for (int c = 0; c < 4; ++c) dft4<INV>(x[4 * c], x[4 * c + 1], x[4 * c + 2], x[4 * c + 3]);
; __device__ __forceinline__ void fft_inv2(LAS f32x2* B, const LAS f32x2* TW2, int tid) {
;     asm volatile("" : "+v"(tid));
;     const int b = tid >> 5, n2 = tid & 31, base = 512 * b + n2; f32x2 x[16];
;     x[0] = B[fpad(base)];
; #pragma unroll
;     for (int k = 1; k < 16; ++k) x[k] = cmulc(B[fpad(base + 32 * k)], TW2[k * 32 + n2]);
;     dft16<true>(x);
	v_pk_mul_f32 v[166:167], v[118:119], v[184:185] op_sel:[1,1] op_sel_hi:[0,1]
	v_pk_fma_f32 v[118:119], v[118:119], v[184:185], v[166:167] op_sel_hi:[1,0,1] neg_hi:[0,0,1]
	ds_read_b64 v[182:183], v5 offset:1584
	ds_read_b64 v[102:103], v56 offset:1536
	ds_read_b64 v[110:111], v5 offset:1848
	ds_read_b64 v[186:187], v56 offset:1792
	ds_read_b64 v[104:105], v5 offset:2112
	ds_read_b64 v[180:181], v56 offset:2048
	ds_read_b64 v[112:113], v5 offset:2376
	ds_read_b64 v[174:175], v56 offset:2304
	ds_read_b64 v[120:121], v5 offset:2640
	ds_read_b64 v[166:167], v56 offset:2560
	s_waitcnt lgkmcnt(8)
	v_pk_mul_f32 v[168:169], v[182:183], v[102:103] op_sel:[1,1] op_sel_hi:[0,1]
	v_pk_fma_f32 v[182:183], v[182:183], v[102:103], v[168:169] op_sel_hi:[1,0,1] neg_hi:[0,0,1]
	s_waitcnt lgkmcnt(6)
	v_pk_mul_f32 v[176:177], v[110:111], v[186:187] op_sel:[1,1] op_sel_hi:[0,1]
	v_pk_fma_f32 v[110:111], v[110:111], v[186:187], v[176:177] op_sel_hi:[1,0,1] neg_hi:[0,0,1]
	s_waitcnt lgkmcnt(4)
	v_pk_mul_f32 v[178:179], v[104:105], v[180:181] op_sel:[1,1] op_sel_hi:[0,1]
	v_pk_fma_f32 v[104:105], v[104:105], v[180:181], v[178:179] op_sel_hi:[1,0,1] neg_hi:[0,0,1]
	s_waitcnt lgkmcnt(2)
	v_pk_mul_f32 v[188:189], v[112:113], v[174:175] op_sel:[1,1] op_sel_hi:[0,1]
	v_pk_fma_f32 v[112:113], v[112:113], v[174:175], v[188:189] op_sel_hi:[1,0,1] neg_hi:[0,0,1]
	s_waitcnt lgkmcnt(0)
	v_pk_mul_f32 v[184:185], v[120:121], v[166:167] op_sel:[1,1] op_sel_hi:[0,1]
	v_pk_fma_f32 v[120:121], v[120:121], v[166:167], v[184:185] op_sel_hi:[1,0,1] neg_hi:[0,0,1]
	ds_read_b64 v[128:129], v5 offset:2904
	ds_read_b64 v[168:169], v56 offset:2816
	ds_read_b64 v[106:107], v5 offset:3168
	ds_read_b64 v[176:177], v56 offset:3072
	ds_read_b64 v[114:115], v5 offset:3432
	ds_read_b64 v[178:179], v56 offset:3328
	ds_read_b64 v[122:123], v5 offset:3696
	ds_read_b64 v[188:189], v56 offset:3584
	ds_read_b64 v[130:131], v5 offset:3960
	ds_read_b64 v[184:185], v56 offset:3840
	s_waitcnt lgkmcnt(8)
	v_pk_mul_f32 v[102:103], v[128:129], v[168:169] op_sel:[1,1] op_sel_hi:[0,1]
	v_pk_fma_f32 v[128:129], v[128:129], v[168:169], v[102:103] op_sel_hi:[1,0,1] neg_hi:[0,0,1]
	s_waitcnt lgkmcnt(6)
	v_pk_mul_f32 v[186:187], v[106:107], v[176:177] op_sel:[1,1] op_sel_hi:[0,1]
	v_pk_fma_f32 v[106:107], v[106:107], v[176:177], v[186:187] op_sel_hi:[1,0,1] neg_hi:[0,0,1]
	s_waitcnt lgkmcnt(4)
	v_pk_mul_f32 v[180:181], v[114:115], v[178:179] op_sel:[1,1] op_sel_hi:[0,1]
	v_pk_fma_f32 v[114:115], v[114:115], v[178:179], v[180:181] op_sel_hi:[1,0,1] neg_hi:[0,0,1]
	s_waitcnt lgkmcnt(2)
	v_pk_mul_f32 v[174:175], v[122:123], v[188:189] op_sel:[1,1] op_sel_hi:[0,1]
	v_pk_fma_f32 v[122:123], v[122:123], v[188:189], v[174:175] op_sel_hi:[1,0,1] neg_hi:[0,0,1]
	s_waitcnt lgkmcnt(0)
	v_pk_mul_f32 v[166:167], v[130:131], v[184:185] op_sel:[1,1] op_sel_hi:[0,1]
	v_pk_fma_f32 v[130:131], v[130:131], v[184:185], v[166:167] op_sel_hi:[1,0,1] neg_hi:[0,0,1]
	v_pk_add_f32 v[102:103], v[100:101], v[104:105]
	v_pk_add_f32 v[186:187], v[100:101], v[104:105] neg_lo:[0,1] neg_hi:[0,1]
	v_pk_add_f32 v[180:181], v[126:127], v[106:107]
	v_pk_add_f32 v[174:175], v[126:127], v[106:107] neg_lo:[0,1] neg_hi:[0,1]
	v_pk_add_f32 v[100:101], v[102:103], v[180:181]
	v_pk_add_f32 v[104:105], v[102:103], v[180:181] neg_lo:[0,1] neg_hi:[0,1]
	v_pk_add_f32 v[126:127], v[186:187], v[174:175] op_sel:[0,1] op_sel_hi:[1,0] neg_lo:[0,1]
	v_pk_add_f32 v[106:107], v[186:187], v[174:175] op_sel:[0,1] op_sel_hi:[1,0] neg_hi:[0,1]
	v_pk_add_f32 v[166:167], v[108:109], v[112:113]
	v_pk_add_f32 v[168:169], v[108:109], v[112:113] neg_lo:[0,1] neg_hi:[0,1]
	v_pk_add_f32 v[176:177], v[118:119], v[114:115]
	v_pk_add_f32 v[178:179], v[118:119], v[114:115] neg_lo:[0,1] neg_hi:[0,1]
	v_pk_add_f32 v[108:109], v[166:167], v[176:177]
	v_pk_add_f32 v[112:113], v[166:167], v[176:177] neg_lo:[0,1] neg_hi:[0,1]
	v_pk_add_f32 v[118:119], v[168:169], v[178:179] op_sel:[0,1] op_sel_hi:[1,0] neg_lo:[0,1]
	v_pk_add_f32 v[114:115], v[168:169], v[178:179] op_sel:[0,1] op_sel_hi:[1,0] neg_hi:[0,1]
	v_pk_add_f32 v[188:189], v[116:117], v[120:121]
	v_pk_add_f32 v[184:185], v[116:117], v[120:121] neg_lo:[0,1] neg_hi:[0,1]
	v_pk_add_f32 v[102:103], v[182:183], v[122:123]
	v_pk_add_f32 v[186:187], v[182:183], v[122:123] neg_lo:[0,1] neg_hi:[0,1]
	v_pk_add_f32 v[116:117], v[188:189], v[102:103]
	v_pk_add_f32 v[120:121], v[188:189], v[102:103] neg_lo:[0,1] neg_hi:[0,1]
	v_pk_add_f32 v[182:183], v[184:185], v[186:187] op_sel:[0,1] op_sel_hi:[1,0] neg_lo:[0,1]
	v_pk_add_f32 v[122:123], v[184:185], v[186:187] op_sel:[0,1] op_sel_hi:[1,0] neg_hi:[0,1]
	v_pk_add_f32 v[180:181], v[124:125], v[128:129]
	v_pk_add_f32 v[174:175], v[124:125], v[128:129] neg_lo:[0,1] neg_hi:[0,1]
	v_pk_add_f32 v[166:167], v[110:111], v[130:131]
	v_pk_add_f32 v[168:169], v[110:111], v[130:131] neg_lo:[0,1] neg_hi:[0,1]
	v_pk_add_f32 v[124:125], v[180:181], v[166:167]
	v_pk_add_f32 v[128:129], v[180:181], v[166:167] neg_lo:[0,1] neg_hi:[0,1]
	v_pk_add_f32 v[110:111], v[174:175], v[168:169] op_sel:[0,1] op_sel_hi:[1,0] neg_lo:[0,1]
	v_pk_add_f32 v[130:131], v[174:175], v[168:169] op_sel:[0,1] op_sel_hi:[1,0] neg_hi:[0,1]
	v_pk_mul_f32 v[176:177], v[118:119], s[68:69] op_sel:[1,1] op_sel_hi:[0,1]
	v_pk_fma_f32 v[118:119], v[118:119], s[68:69], v[176:177] op_sel_hi:[1,0,1] neg_hi:[0,0,1]
	v_pk_mul_f32 v[178:179], v[182:183], s[84:85] op_sel:[1,1] op_sel_hi:[0,1]
	v_pk_fma_f32 v[182:183], v[182:183], s[84:85], v[178:179] op_sel_hi:[1,0,1] neg_hi:[0,0,1]
	v_pk_mul_f32 v[188:189], v[110:111], s[88:89] op_sel:[1,1] op_sel_hi:[0,1]
	v_pk_fma_f32 v[110:111], v[110:111], s[88:89], v[188:189] op_sel_hi:[1,0,1] neg_hi:[0,0,1]
; #define LAS __attribute__((address_space(3)))
; __device__ __forceinline__ f32x2 cmulc(f32x2 a, f32x2 b) { return (f32x2){a.x * b.x + a.y * b.y, a.y * b.x - a.x * b.y}; }
; __device__ __forceinline__ void fft_inv2(LAS f32x2* B, const LAS f32x2* TW2, int tid) {
;     asm volatile("" : "+v"(tid));
;     const int b = tid >> 5, n2 = tid & 31, base = 512 * b + n2; f32x2 x[16];
;     x[0] = B[fpad(base)];
; #pragma unroll
;     for (int k = 1; k < 16; ++k) x[k] = cmulc(B[fpad(base + 32 * k)], TW2[k * 32 + n2]);
;     dft16<true>(x);
; #pragma unroll
;     for (int r = 0; r < 16; ++r) B[fpad(base + 32 * r)] = x[r];
; }
; __device__ __forceinline__ void fft_inv1(f32x2 (&x)[16], const LAS f32x2* B, int n2, const f32x2 (&w)[16]) {
;     asm volatile("" : "+v"(n2));
;     x[0] = B[fpad(n2)];
; #pragma unroll
;     for (int k = 1; k < 16; ++k) x[k] = cmulc(B[fpad(512 * k + n2)], w[k]);
;     dft16_inv_lo(x);
	v_pk_mul_f32 v[184:185], v[112:113], s[84:85] op_sel:[1,1] op_sel_hi:[0,1]
	v_pk_fma_f32 v[112:113], v[112:113], s[84:85], v[184:185] op_sel_hi:[1,0,1] neg_hi:[0,0,1]
	v_pk_mul_f32 v[102:103], v[128:129], s[90:91] op_sel:[1,1] op_sel_hi:[0,1]
	v_pk_fma_f32 v[128:129], v[128:129], s[90:91], v[102:103] op_sel_hi:[1,0,1] neg_hi:[0,0,1]
	v_pk_mul_f32 v[186:187], v[114:115], s[88:89] op_sel:[1,1] op_sel_hi:[0,1]
	v_pk_fma_f32 v[114:115], v[114:115], s[88:89], v[186:187] op_sel_hi:[1,0,1] neg_hi:[0,0,1]
	v_pk_mul_f32 v[180:181], v[122:123], s[90:91] op_sel:[1,1] op_sel_hi:[0,1]
	v_pk_fma_f32 v[122:123], v[122:123], s[90:91], v[180:181] op_sel_hi:[1,0,1] neg_hi:[0,0,1]
	v_pk_mul_f32 v[174:175], v[130:131], s[98:99] op_sel:[1,1] op_sel_hi:[0,1]
	v_pk_fma_f32 v[130:131], v[130:131], s[98:99], v[174:175] op_sel_hi:[1,0,1] neg_hi:[0,0,1]
	v_pk_add_f32 v[166:167], v[100:101], v[116:117]
	v_pk_add_f32 v[168:169], v[100:101], v[116:117] neg_lo:[0,1] neg_hi:[0,1]
	v_pk_add_f32 v[176:177], v[108:109], v[124:125]
	v_pk_add_f32 v[178:179], v[108:109], v[124:125] neg_lo:[0,1] neg_hi:[0,1]
	v_pk_add_f32 v[100:101], v[166:167], v[176:177]
	v_pk_add_f32 v[116:117], v[166:167], v[176:177] neg_lo:[0,1] neg_hi:[0,1]
	v_pk_add_f32 v[108:109], v[168:169], v[178:179] op_sel:[0,1] op_sel_hi:[1,0] neg_lo:[0,1]
	v_pk_add_f32 v[124:125], v[168:169], v[178:179] op_sel:[0,1] op_sel_hi:[1,0] neg_hi:[0,1]
	v_pk_add_f32 v[188:189], v[126:127], v[182:183]
	v_pk_add_f32 v[184:185], v[126:127], v[182:183] neg_lo:[0,1] neg_hi:[0,1]
	v_pk_add_f32 v[102:103], v[118:119], v[110:111]
	v_pk_add_f32 v[186:187], v[118:119], v[110:111] neg_lo:[0,1] neg_hi:[0,1]
	v_pk_add_f32 v[126:127], v[188:189], v[102:103]
	v_pk_add_f32 v[182:183], v[188:189], v[102:103] neg_lo:[0,1] neg_hi:[0,1]
	v_pk_add_f32 v[118:119], v[184:185], v[186:187] op_sel:[0,1] op_sel_hi:[1,0] neg_lo:[0,1]
	v_pk_add_f32 v[110:111], v[184:185], v[186:187] op_sel:[0,1] op_sel_hi:[1,0] neg_hi:[0,1]
	v_pk_add_f32 v[180:181], v[104:105], v[120:121] op_sel:[0,1] op_sel_hi:[1,0] neg_lo:[0,1]
	v_pk_add_f32 v[174:175], v[104:105], v[120:121] op_sel:[0,1] op_sel_hi:[1,0] neg_hi:[0,1]
	v_pk_add_f32 v[166:167], v[112:113], v[128:129]
	v_pk_add_f32 v[168:169], v[112:113], v[128:129] neg_lo:[0,1] neg_hi:[0,1]
	v_pk_add_f32 v[104:105], v[180:181], v[166:167]
	v_pk_add_f32 v[120:121], v[180:181], v[166:167] neg_lo:[0,1] neg_hi:[0,1]
	v_pk_add_f32 v[112:113], v[174:175], v[168:169] op_sel:[0,1] op_sel_hi:[1,0] neg_lo:[0,1]
	v_pk_add_f32 v[128:129], v[174:175], v[168:169] op_sel:[0,1] op_sel_hi:[1,0] neg_hi:[0,1]
	v_pk_add_f32 v[176:177], v[106:107], v[122:123]
	v_pk_add_f32 v[178:179], v[106:107], v[122:123] neg_lo:[0,1] neg_hi:[0,1]
	v_pk_add_f32 v[188:189], v[114:115], v[130:131]
	v_pk_add_f32 v[184:185], v[114:115], v[130:131] neg_lo:[0,1] neg_hi:[0,1]
	v_pk_add_f32 v[106:107], v[176:177], v[188:189]
	v_pk_add_f32 v[122:123], v[176:177], v[188:189] neg_lo:[0,1] neg_hi:[0,1]
	v_pk_add_f32 v[114:115], v[178:179], v[184:185] op_sel:[0,1] op_sel_hi:[1,0] neg_lo:[0,1]
	v_pk_add_f32 v[130:131], v[178:179], v[184:185] op_sel:[0,1] op_sel_hi:[1,0] neg_hi:[0,1]
	ds_write_b64 v5, v[100:101]
	ds_write_b64 v5, v[126:127] offset:264
	ds_write_b64 v5, v[104:105] offset:528
	ds_write_b64 v5, v[106:107] offset:792
	ds_write_b64 v5, v[108:109] offset:1056
	ds_write_b64 v5, v[118:119] offset:1320
	ds_write_b64 v5, v[112:113] offset:1584
	ds_write_b64 v5, v[114:115] offset:1848
	ds_write_b64 v5, v[116:117] offset:2112
	ds_write_b64 v5, v[182:183] offset:2376
	ds_write_b64 v5, v[120:121] offset:2640
	ds_write_b64 v5, v[122:123] offset:2904
	ds_write_b64 v5, v[124:125] offset:3168
	ds_write_b64 v5, v[110:111] offset:3432
	ds_write_b64 v5, v[128:129] offset:3696
	ds_write_b64 v5, v[130:131] offset:3960
	s_waitcnt lgkmcnt(0)
	s_barrier
	ds_read_b64 v[100:101], v3
	ds_read_b64 v[108:109], v3 offset:16896
	ds_read_b64 v[116:117], v3 offset:33792
	ds_read_b64 v[124:125], v3 offset:50688
	ds_read_b64 v[126:127], v3 offset:4224
	ds_read_b64 v[118:119], v3 offset:21120
	ds_read_b64 v[182:183], v3 offset:38016
	ds_read_b64 v[110:111], v3 offset:54912
	ds_read_b64 v[104:105], v3 offset:8448
	ds_read_b64 v[112:113], v3 offset:25344
	ds_read_b64 v[120:121], v3 offset:42240
	ds_read_b64 v[128:129], v3 offset:59136
	ds_read_b64 v[106:107], v3 offset:12672
	ds_read_b64 v[114:115], v3 offset:29568
	ds_read_b64 v[122:123], v3 offset:46464
	ds_read_b64 v[130:131], v3 offset:63360
	s_waitcnt lgkmcnt(14)
	v_pk_mul_f32 v[102:103], v[108:109], v[12:13] op_sel:[1,1] op_sel_hi:[0,1]
	v_pk_fma_f32 v[108:109], v[108:109], v[12:13], v[102:103] op_sel_hi:[1,0,1] neg_hi:[0,0,1]
	s_waitcnt lgkmcnt(13)
	v_pk_mul_f32 v[186:187], v[116:117], v[20:21] op_sel:[1,1] op_sel_hi:[0,1]
	v_pk_fma_f32 v[116:117], v[116:117], v[20:21], v[186:187] op_sel_hi:[1,0,1] neg_hi:[0,0,1]
	s_waitcnt lgkmcnt(12)
	v_pk_mul_f32 v[180:181], v[124:125], v[28:29] op_sel:[1,1] op_sel_hi:[0,1]
	v_pk_fma_f32 v[124:125], v[124:125], v[28:29], v[180:181] op_sel_hi:[1,0,1] neg_hi:[0,0,1]
	s_waitcnt lgkmcnt(11)
	v_pk_mul_f32 v[174:175], v[126:127], v[6:7] op_sel:[1,1] op_sel_hi:[0,1]
	v_pk_fma_f32 v[126:127], v[126:127], v[6:7], v[174:175] op_sel_hi:[1,0,1] neg_hi:[0,0,1]
	s_waitcnt lgkmcnt(10)
	v_pk_mul_f32 v[166:167], v[118:119], v[14:15] op_sel:[1,1] op_sel_hi:[0,1]
	v_pk_fma_f32 v[118:119], v[118:119], v[14:15], v[166:167] op_sel_hi:[1,0,1] neg_hi:[0,0,1]
	s_waitcnt lgkmcnt(9)
	v_pk_mul_f32 v[168:169], v[182:183], v[22:23] op_sel:[1,1] op_sel_hi:[0,1]
	v_pk_fma_f32 v[182:183], v[182:183], v[22:23], v[168:169] op_sel_hi:[1,0,1] neg_hi:[0,0,1]
	s_waitcnt lgkmcnt(8)
; __device__ __forceinline__ f32x2 cmulc(f32x2 a, f32x2 b) { return (f32x2){a.x * b.x + a.y * b.y, a.y * b.x - a.x * b.y}; }
; #define WG_SYNC() do { asm volatile("s_waitcnt lgkmcnt(0)" ::: "memory"); __builtin_amdgcn_s_barrier(); asm volatile("" ::: "memory"); } while (0)
; __device__ __forceinline__ void dft16_inv_lo(f32x2 (&x)[16]) {
;     constexpr float C1 = 0.92387953251128674f, S1 = 0.38268343236508977f, C2 = 0.70710678118654752f;
; #pragma unroll
;     for (int b = 0; b < 4; ++b) dft4<true>(x[b], x[4 + b], x[8 + b], x[12 + b]);
;     const f32x2 w1 = {C1, -S1}, w2 = {C2, -C2}, w3 = {S1, -C1}, w4 = {0.f, -1.f}, w6 = {-C2, -C2}, w9 = {-C1, S1};
;     x[5] = cmulc(x[5], w1); x[6] = cmulc(x[6], w2); x[7] = cmulc(x[7], w3);
;     x[9] = cmulc(x[9], w2); x[10] = cmulc(x[10], w4); x[11] = cmulc(x[11], w6);
;     x[13] = cmulc(x[13], w3); x[14] = cmulc(x[14], w6); x[15] = cmulc(x[15], w9);
;     f32x2 y[8];
; #pragma unroll
;     for (int c = 0; c < 4; ++c) { const f32x2 t0 = x[4 * c] + x[4 * c + 2], t1 = x[4 * c] - x[4 * c + 2], t2 = x[4 * c + 1] + x[4 * c + 3], t3 = x[4 * c + 1] - x[4 * c + 3];
;         y[c] = t0 + t2; y[4 + c] = t1 + (f32x2){-t3.y, t3.x}; }
; #pragma unroll
;     for (int k = 0; k < 8; ++k) x[k] = y[k];
; __device__ __forceinline__ void hyena_fft(LAS unsigned char* lds, int layer, int G, const int wave_s) {
;     ...
;             WG_SYNC(); fft_inv1(x, Db, n2, w1p);
;             { const float fb1 = fbias[HY + c]; float* zo = ZT + (size_t)c * MT;
	v_pk_mul_f32 v[176:177], v[110:111], v[30:31] op_sel:[1,1] op_sel_hi:[0,1]
	v_pk_fma_f32 v[110:111], v[110:111], v[30:31], v[176:177] op_sel_hi:[1,0,1] neg_hi:[0,0,1]
	s_waitcnt lgkmcnt(7)
	v_pk_mul_f32 v[178:179], v[104:105], v[8:9] op_sel:[1,1] op_sel_hi:[0,1]
	v_pk_fma_f32 v[104:105], v[104:105], v[8:9], v[178:179] op_sel_hi:[1,0,1] neg_hi:[0,0,1]
	s_waitcnt lgkmcnt(6)
	v_pk_mul_f32 v[188:189], v[112:113], v[16:17] op_sel:[1,1] op_sel_hi:[0,1]
	v_pk_fma_f32 v[112:113], v[112:113], v[16:17], v[188:189] op_sel_hi:[1,0,1] neg_hi:[0,0,1]
	s_waitcnt lgkmcnt(5)
	v_pk_mul_f32 v[184:185], v[120:121], v[24:25] op_sel:[1,1] op_sel_hi:[0,1]
	v_pk_fma_f32 v[120:121], v[120:121], v[24:25], v[184:185] op_sel_hi:[1,0,1] neg_hi:[0,0,1]
	s_waitcnt lgkmcnt(4)
	v_pk_mul_f32 v[102:103], v[128:129], v[32:33] op_sel:[1,1] op_sel_hi:[0,1]
	v_pk_fma_f32 v[128:129], v[128:129], v[32:33], v[102:103] op_sel_hi:[1,0,1] neg_hi:[0,0,1]
	s_waitcnt lgkmcnt(3)
	v_pk_mul_f32 v[186:187], v[106:107], v[10:11] op_sel:[1,1] op_sel_hi:[0,1]
	v_pk_fma_f32 v[106:107], v[106:107], v[10:11], v[186:187] op_sel_hi:[1,0,1] neg_hi:[0,0,1]
	s_waitcnt lgkmcnt(2)
	v_pk_mul_f32 v[180:181], v[114:115], v[18:19] op_sel:[1,1] op_sel_hi:[0,1]
	v_pk_fma_f32 v[114:115], v[114:115], v[18:19], v[180:181] op_sel_hi:[1,0,1] neg_hi:[0,0,1]
	s_waitcnt lgkmcnt(1)
	v_pk_mul_f32 v[174:175], v[122:123], v[26:27] op_sel:[1,1] op_sel_hi:[0,1]
	v_pk_fma_f32 v[122:123], v[122:123], v[26:27], v[174:175] op_sel_hi:[1,0,1] neg_hi:[0,0,1]
	s_waitcnt lgkmcnt(0)
	v_pk_mul_f32 v[166:167], v[130:131], v[34:35] op_sel:[1,1] op_sel_hi:[0,1]
	v_pk_fma_f32 v[130:131], v[130:131], v[34:35], v[166:167] op_sel_hi:[1,0,1] neg_hi:[0,0,1]
	v_pk_add_f32 v[168:169], v[100:101], v[116:117]
	v_pk_add_f32 v[176:177], v[100:101], v[116:117] neg_lo:[0,1] neg_hi:[0,1]
	v_pk_add_f32 v[178:179], v[108:109], v[124:125]
	v_pk_add_f32 v[188:189], v[108:109], v[124:125] neg_lo:[0,1] neg_hi:[0,1]
	v_pk_add_f32 v[100:101], v[168:169], v[178:179]
	v_pk_add_f32 v[116:117], v[168:169], v[178:179] neg_lo:[0,1] neg_hi:[0,1]
	v_pk_add_f32 v[108:109], v[176:177], v[188:189] op_sel:[0,1] op_sel_hi:[1,0] neg_lo:[0,1]
	v_pk_add_f32 v[124:125], v[176:177], v[188:189] op_sel:[0,1] op_sel_hi:[1,0] neg_hi:[0,1]
	v_pk_add_f32 v[184:185], v[126:127], v[182:183]
	v_pk_add_f32 v[102:103], v[126:127], v[182:183] neg_lo:[0,1] neg_hi:[0,1]
	v_pk_add_f32 v[186:187], v[118:119], v[110:111]
	v_pk_add_f32 v[180:181], v[118:119], v[110:111] neg_lo:[0,1] neg_hi:[0,1]
	v_pk_add_f32 v[126:127], v[184:185], v[186:187]
	v_pk_add_f32 v[182:183], v[184:185], v[186:187] neg_lo:[0,1] neg_hi:[0,1]
	v_pk_add_f32 v[118:119], v[102:103], v[180:181] op_sel:[0,1] op_sel_hi:[1,0] neg_lo:[0,1]
	v_pk_add_f32 v[110:111], v[102:103], v[180:181] op_sel:[0,1] op_sel_hi:[1,0] neg_hi:[0,1]
	v_pk_add_f32 v[174:175], v[104:105], v[120:121]
	v_pk_add_f32 v[166:167], v[104:105], v[120:121] neg_lo:[0,1] neg_hi:[0,1]
	v_pk_add_f32 v[168:169], v[112:113], v[128:129]
	v_pk_add_f32 v[176:177], v[112:113], v[128:129] neg_lo:[0,1] neg_hi:[0,1]
	v_pk_add_f32 v[104:105], v[174:175], v[168:169]
	v_pk_add_f32 v[120:121], v[174:175], v[168:169] neg_lo:[0,1] neg_hi:[0,1]
	v_pk_add_f32 v[112:113], v[166:167], v[176:177] op_sel:[0,1] op_sel_hi:[1,0] neg_lo:[0,1]
	v_pk_add_f32 v[128:129], v[166:167], v[176:177] op_sel:[0,1] op_sel_hi:[1,0] neg_hi:[0,1]
	v_pk_add_f32 v[178:179], v[106:107], v[122:123]
	v_pk_add_f32 v[188:189], v[106:107], v[122:123] neg_lo:[0,1] neg_hi:[0,1]
	v_pk_add_f32 v[184:185], v[114:115], v[130:131]
	v_pk_add_f32 v[102:103], v[114:115], v[130:131] neg_lo:[0,1] neg_hi:[0,1]
	v_pk_add_f32 v[106:107], v[178:179], v[184:185]
	v_pk_add_f32 v[122:123], v[178:179], v[184:185] neg_lo:[0,1] neg_hi:[0,1]
	v_pk_add_f32 v[114:115], v[188:189], v[102:103] op_sel:[0,1] op_sel_hi:[1,0] neg_lo:[0,1]
	v_pk_add_f32 v[130:131], v[188:189], v[102:103] op_sel:[0,1] op_sel_hi:[1,0] neg_hi:[0,1]
	v_pk_mul_f32 v[186:187], v[118:119], s[68:69] op_sel:[1,1] op_sel_hi:[0,1]
	v_pk_fma_f32 v[118:119], v[118:119], s[68:69], v[186:187] op_sel_hi:[1,0,1] neg_hi:[0,0,1]
	v_pk_mul_f32 v[180:181], v[112:113], s[84:85] op_sel:[1,1] op_sel_hi:[0,1]
	v_pk_fma_f32 v[112:113], v[112:113], s[84:85], v[180:181] op_sel_hi:[1,0,1] neg_hi:[0,0,1]
	v_pk_mul_f32 v[174:175], v[114:115], s[88:89] op_sel:[1,1] op_sel_hi:[0,1]
	v_pk_fma_f32 v[114:115], v[114:115], s[88:89], v[174:175] op_sel_hi:[1,0,1] neg_hi:[0,0,1]
	v_pk_mul_f32 v[166:167], v[182:183], s[84:85] op_sel:[1,1] op_sel_hi:[0,1]
	v_pk_fma_f32 v[182:183], v[182:183], s[84:85], v[166:167] op_sel_hi:[1,0,1] neg_hi:[0,0,1]
	v_pk_mul_f32 v[168:169], v[122:123], s[90:91] op_sel:[1,1] op_sel_hi:[0,1]
	v_pk_fma_f32 v[122:123], v[122:123], s[90:91], v[168:169] op_sel_hi:[1,0,1] neg_hi:[0,0,1]
	v_pk_mul_f32 v[176:177], v[110:111], s[88:89] op_sel:[1,1] op_sel_hi:[0,1]
	v_pk_fma_f32 v[110:111], v[110:111], s[88:89], v[176:177] op_sel_hi:[1,0,1] neg_hi:[0,0,1]
	v_pk_mul_f32 v[178:179], v[128:129], s[90:91] op_sel:[1,1] op_sel_hi:[0,1]
	v_pk_fma_f32 v[128:129], v[128:129], s[90:91], v[178:179] op_sel_hi:[1,0,1] neg_hi:[0,0,1]
	v_pk_mul_f32 v[188:189], v[130:131], s[98:99] op_sel:[1,1] op_sel_hi:[0,1]
	v_pk_fma_f32 v[130:131], v[130:131], s[98:99], v[188:189] op_sel_hi:[1,0,1] neg_hi:[0,0,1]
	v_pk_add_f32 v[184:185], v[100:101], v[104:105]
	v_pk_add_f32 v[102:103], v[100:101], v[104:105] neg_lo:[0,1] neg_hi:[0,1]
	v_pk_add_f32 v[186:187], v[126:127], v[106:107]
	v_pk_add_f32 v[180:181], v[126:127], v[106:107] neg_lo:[0,1] neg_hi:[0,1]
	v_pk_add_f32 v[100:101], v[184:185], v[186:187]
	v_pk_add_f32 v[126:127], v[102:103], v[180:181] op_sel:[0,1] op_sel_hi:[1,0] neg_lo:[0,1]
	v_pk_add_f32 v[174:175], v[108:109], v[112:113]
	v_pk_add_f32 v[166:167], v[108:109], v[112:113] neg_lo:[0,1] neg_hi:[0,1]
	v_pk_add_f32 v[168:169], v[118:119], v[114:115]
	v_pk_add_f32 v[176:177], v[118:119], v[114:115] neg_lo:[0,1] neg_hi:[0,1]
	v_pk_add_f32 v[108:109], v[174:175], v[168:169]
	v_pk_add_f32 v[118:119], v[166:167], v[176:177] op_sel:[0,1] op_sel_hi:[1,0] neg_lo:[0,1]
	v_pk_add_f32 v[178:179], v[116:117], v[120:121] op_sel:[0,1] op_sel_hi:[1,0] neg_lo:[0,1]
	v_pk_add_f32 v[188:189], v[116:117], v[120:121] op_sel:[0,1] op_sel_hi:[1,0] neg_hi:[0,1]
	v_pk_add_f32 v[184:185], v[182:183], v[122:123]
	v_pk_add_f32 v[102:103], v[182:183], v[122:123] neg_lo:[0,1] neg_hi:[0,1]
	v_pk_add_f32 v[116:117], v[178:179], v[184:185]
	v_pk_add_f32 v[182:183], v[188:189], v[102:103] op_sel:[0,1] op_sel_hi:[1,0] neg_lo:[0,1]
	v_pk_add_f32 v[186:187], v[124:125], v[128:129]
	v_pk_add_f32 v[180:181], v[124:125], v[128:129] neg_lo:[0,1] neg_hi:[0,1]
	v_pk_add_f32 v[174:175], v[110:111], v[130:131]
	v_pk_add_f32 v[166:167], v[110:111], v[130:131] neg_lo:[0,1] neg_hi:[0,1]
	v_pk_add_f32 v[124:125], v[186:187], v[174:175]
	v_pk_add_f32 v[110:111], v[180:181], v[166:167] op_sel:[0,1] op_sel_hi:[1,0] neg_lo:[0,1]
	s_load_dword s35, s[50:51], 0x1000
	s_mul_i32 s43, s80, 0x8800
	s_add_u32 s46, s40, s43
	s_addc_u32 s47, s41, 0
	s_waitcnt lgkmcnt(0)
; __device__ __forceinline__ void hyena_fft(LAS unsigned char* lds, int layer, int G, const int wave_s) {
;     ...
;             { const float fb1 = fbias[HY + c]; float* zo = ZT + (size_t)c * MT;
; #pragma unroll
;               for (int r = 0; r < 8; ++r) { const int t = n2 + 512 * r;
;                   zo[t] = ux[r][0] * (x[r].x + fb1 * uz[r][0]); zo[SEQ + t] = ux[r][1] * (x[r].y + fb1 * uz[r][1]); } }
;         }
	v_mov_b32_e32 v194, s35
	v_pk_fma_f32 v[168:169], v[132:133], v[194:195], v[100:101] op_sel_hi:[1,0,1]
	v_pk_mul_f32 v[168:169], v[148:149], v[168:169]
	s_add_u32 s60, s46, 0
	s_addc_u32 s61, s47, 0
	s_add_u32 s62, s60, 0x4000
	s_addc_u32 s63, s61, 0
	global_store_dword v212, v168, s[60:61]
	global_store_dword v212, v169, s[62:63]
	v_pk_fma_f32 v[176:177], v[134:135], v[194:195], v[108:109] op_sel_hi:[1,0,1]
	v_pk_mul_f32 v[176:177], v[150:151], v[176:177]
	global_store_dword v212, v176, s[60:61] offset:2048
	global_store_dword v212, v177, s[62:63] offset:2048
	v_pk_fma_f32 v[178:179], v[136:137], v[194:195], v[116:117] op_sel_hi:[1,0,1]
	v_pk_mul_f32 v[178:179], v[152:153], v[178:179]
	s_add_u32 s60, s46, 0x1000
	s_addc_u32 s61, s47, 0
	s_add_u32 s62, s60, 0x4000
	s_addc_u32 s63, s61, 0
	global_store_dword v212, v178, s[60:61]
	global_store_dword v212, v179, s[62:63]
	v_pk_fma_f32 v[188:189], v[138:139], v[194:195], v[124:125] op_sel_hi:[1,0,1]
	v_pk_mul_f32 v[188:189], v[154:155], v[188:189]
	global_store_dword v212, v188, s[60:61] offset:2048
	global_store_dword v212, v189, s[62:63] offset:2048
	v_pk_fma_f32 v[184:185], v[140:141], v[194:195], v[126:127] op_sel_hi:[1,0,1]
	v_pk_mul_f32 v[184:185], v[158:159], v[184:185]
	s_add_u32 s60, s46, 0x2000
	s_addc_u32 s61, s47, 0
	s_add_u32 s62, s60, 0x4000
	s_addc_u32 s63, s61, 0
	global_store_dword v212, v184, s[60:61]
	global_store_dword v212, v185, s[62:63]
	v_pk_fma_f32 v[102:103], v[142:143], v[194:195], v[118:119] op_sel_hi:[1,0,1]
	v_pk_mul_f32 v[102:103], v[160:161], v[102:103]
	global_store_dword v212, v102, s[60:61] offset:2048
	global_store_dword v212, v103, s[62:63] offset:2048
	v_pk_fma_f32 v[186:187], v[144:145], v[194:195], v[182:183] op_sel_hi:[1,0,1]
	v_pk_mul_f32 v[186:187], v[162:163], v[186:187]
	s_add_u32 s60, s46, 0x3000
	s_addc_u32 s61, s47, 0
	s_add_u32 s62, s60, 0x4000
	s_addc_u32 s63, s61, 0
	global_store_dword v212, v186, s[60:61]
	global_store_dword v212, v187, s[62:63]
	v_pk_fma_f32 v[180:181], v[146:147], v[194:195], v[110:111] op_sel_hi:[1,0,1]
	v_pk_mul_f32 v[180:181], v[164:165], v[180:181]
	global_store_dword v212, v180, s[60:61] offset:2048
	global_store_dword v212, v181, s[62:63] offset:2048
	s_add_u32 s80, s80, 1
	s_cmp_lt_i32 s80, s93
	s_cbranch_scc1 .Lhfft_loop
	s_waitcnt vmcnt(0) lgkmcnt(0)
